# K-loops: additionally the LDS-DMA stage of phases 3,7 is issued in phases 4,8 (memory parts now 12 reads / 4 reads+4 DMA / 8 reads / 4 DMA); stage order and vmcnt points unchanged
# speedup vs baseline: 1.0047x; 1.0005x over previous
.LBB0_122:
	v_mov_b64_e32 v[0:1], 0x180
	s_ashr_i32 s15, s14, 31
	v_cmp_lt_i64_e32 vcc, s[16:17], v[0:1]
	s_lshl_b64 s[16:17], s[14:15], 19
	s_add_u32 s16, s30, s16
	s_addc_u32 s17, s31, s17
	s_and_b64 s[18:19], vcc, exec
	s_cselect_b32 s7, s17, s21
	s_cselect_b32 s9, s16, s20
	s_ashr_i32 s13, s12, 31
	s_lshl_b64 s[18:19], s[12:13], 19
	s_add_u32 s18, s34, s18
	s_addc_u32 s19, s35, s19
	s_and_b64 s[22:23], vcc, exec
	s_cselect_b32 s13, s19, s3
	s_cselect_b32 s15, s18, s2
	s_add_u32 s20, s20, 0x40080
	s_addc_u32 s21, s21, 0
	s_add_u32 s50, s2, 0x100
	s_addc_u32 s51, s3, 0
	s_mov_b32 s52, -2
	s_add_u32 s2, s20, 0xfffc0080
	s_addc_u32 s3, s21, -1
	ds_read_b128 v[24:27], v164
	ds_read_b128 v[28:31], v164 offset:1024
	ds_read_b128 v[32:35], v164 offset:2048
	ds_read_b128 v[36:39], v164 offset:3072
	s_cmp_eq_u32 s52, 12
	s_cselect_b32 s23, s7, s3
	s_cselect_b32 s22, s9, s2
	s_cselect_b32 s3, s13, s51
	s_cselect_b32 s2, s15, s50
	ds_read_b128 v[154:157], v165
	ds_read_b128 v[158:161], v165 offset:1024
	ds_read_b128 v[180:183], v165 offset:2048
	ds_read_b128 v[184:187], v165 offset:3072
	ds_read_b128 v[188:191], v165 offset:4096
	ds_read_b128 v[192:195], v165 offset:5120
	ds_read_b128 v[196:199], v165 offset:6144
	ds_read_b128 v[200:203], v165 offset:7168
	s_waitcnt lgkmcnt(8)
	s_barrier
	s_waitcnt lgkmcnt(0)
	v_mfma_f32_16x16x32_bf16 v[140:143], v[24:27], v[154:157], 0
	v_mfma_f32_16x16x32_bf16 v[136:139], v[32:35], v[154:157], 0
	v_mfma_f32_16x16x32_bf16 v[124:127], v[24:27], v[180:183], 0
	v_mfma_f32_16x16x32_bf16 v[120:123], v[32:35], v[180:183], 0
	v_mfma_f32_16x16x32_bf16 v[108:111], v[24:27], v[188:191], 0
	v_mfma_f32_16x16x32_bf16 v[104:107], v[32:35], v[188:191], 0
	v_mfma_f32_16x16x32_bf16 v[92:95], v[24:27], v[196:199], 0
	v_mfma_f32_16x16x32_bf16 v[88:91], v[32:35], v[196:199], 0
	v_mfma_f32_16x16x32_bf16 v[140:143], v[28:31], v[158:161], v[140:143]
	v_mfma_f32_16x16x32_bf16 v[136:139], v[36:39], v[158:161], v[136:139]
	v_mfma_f32_16x16x32_bf16 v[124:127], v[28:31], v[184:187], v[124:127]
	v_mfma_f32_16x16x32_bf16 v[120:123], v[36:39], v[184:187], v[120:123]
	v_mfma_f32_16x16x32_bf16 v[108:111], v[28:31], v[192:195], v[108:111]
	v_mfma_f32_16x16x32_bf16 v[104:107], v[36:39], v[192:195], v[104:107]
	v_mfma_f32_16x16x32_bf16 v[92:95], v[28:31], v[200:203], v[92:95]
	v_mfma_f32_16x16x32_bf16 v[88:91], v[36:39], v[200:203], v[88:91]
	s_barrier
	s_add_i32 m0, s37, 0xc000
	ds_read_b128 v[204:207], v164 offset:16384
	ds_read_b128 v[208:211], v164 offset:17408
	ds_read_b128 v[212:215], v164 offset:18432
	global_load_lds_dwordx4 v150, s[20:21]
	s_add_i32 m0, s37, 0xe000
	ds_read_b128 v[216:219], v164 offset:19456
	global_load_lds_dwordx4 v152, s[20:21]
	s_add_u32 s98, s2, 0x80
	s_addc_u32 s99, s3, 0
	s_add_i32 m0, s36, 0x10000
	s_nop 0
	global_load_lds_dwordx4 v168, s[2:3]
	s_add_i32 m0, s36, 0x12000
	s_nop 0
	global_load_lds_dwordx4 v148, s[2:3]
	s_barrier
	s_waitcnt lgkmcnt(0)
	v_mfma_f32_16x16x32_bf16 v[132:135], v[204:207], v[154:157], 0
	v_mfma_f32_16x16x32_bf16 v[128:131], v[212:215], v[154:157], 0
	v_mfma_f32_16x16x32_bf16 v[116:119], v[204:207], v[180:183], 0
	v_mfma_f32_16x16x32_bf16 v[112:115], v[212:215], v[180:183], 0
	v_mfma_f32_16x16x32_bf16 v[100:103], v[204:207], v[188:191], 0
	v_mfma_f32_16x16x32_bf16 v[96:99], v[212:215], v[188:191], 0
	v_mfma_f32_16x16x32_bf16 v[84:87], v[204:207], v[196:199], 0
	v_mfma_f32_16x16x32_bf16 v[80:83], v[212:215], v[196:199], 0
	v_mfma_f32_16x16x32_bf16 v[132:135], v[208:211], v[158:161], v[132:135]
	v_mfma_f32_16x16x32_bf16 v[128:131], v[216:219], v[158:161], v[128:131]
	v_mfma_f32_16x16x32_bf16 v[116:119], v[208:211], v[184:187], v[116:119]
	v_mfma_f32_16x16x32_bf16 v[112:115], v[216:219], v[184:187], v[112:115]
	v_mfma_f32_16x16x32_bf16 v[100:103], v[208:211], v[192:195], v[100:103]
	v_mfma_f32_16x16x32_bf16 v[96:99], v[216:219], v[192:195], v[96:99]
	v_mfma_f32_16x16x32_bf16 v[84:87], v[208:211], v[200:203], v[84:87]
	v_mfma_f32_16x16x32_bf16 v[80:83], v[216:219], v[200:203], v[80:83]
	s_add_u32 s100, s22, 0x80
	s_addc_u32 s101, s23, 0
	s_barrier
	ds_read_b128 v[154:157], v165 offset:16384
	ds_read_b128 v[158:161], v165 offset:17408
	ds_read_b128 v[180:183], v165 offset:18432
	ds_read_b128 v[184:187], v165 offset:19456
	ds_read_b128 v[188:191], v165 offset:20480
	ds_read_b128 v[192:195], v165 offset:21504
	ds_read_b128 v[196:199], v165 offset:22528
	ds_read_b128 v[200:203], v165 offset:23552
	s_barrier
	s_waitcnt lgkmcnt(0)
	v_mfma_f32_16x16x32_bf16 v[76:79], v[24:27], v[154:157], 0
	v_mfma_f32_16x16x32_bf16 v[72:75], v[32:35], v[154:157], 0
	v_mfma_f32_16x16x32_bf16 v[60:63], v[24:27], v[180:183], 0
	v_mfma_f32_16x16x32_bf16 v[56:59], v[32:35], v[180:183], 0
	v_mfma_f32_16x16x32_bf16 v[44:47], v[24:27], v[188:191], 0
	v_mfma_f32_16x16x32_bf16 v[40:43], v[32:35], v[188:191], 0
	v_mfma_f32_16x16x32_bf16 v[12:15], v[24:27], v[196:199], 0
	v_mfma_f32_16x16x32_bf16 v[8:11], v[32:35], v[196:199], 0
	v_mfma_f32_16x16x32_bf16 v[76:79], v[28:31], v[158:161], v[76:79]
	v_mfma_f32_16x16x32_bf16 v[72:75], v[36:39], v[158:161], v[72:75]
	v_mfma_f32_16x16x32_bf16 v[60:63], v[28:31], v[184:187], v[60:63]
	v_mfma_f32_16x16x32_bf16 v[56:59], v[36:39], v[184:187], v[56:59]
	v_mfma_f32_16x16x32_bf16 v[44:47], v[28:31], v[192:195], v[44:47]
	v_mfma_f32_16x16x32_bf16 v[40:43], v[36:39], v[192:195], v[40:43]
	v_mfma_f32_16x16x32_bf16 v[12:15], v[28:31], v[200:203], v[12:15]
	v_mfma_f32_16x16x32_bf16 v[8:11], v[36:39], v[200:203], v[8:11]
	s_barrier
	s_mov_b32 m0, s37
	s_nop 0
	global_load_lds_dwordx4 v144, s[22:23]
	s_mov_b32 m0, s38
	s_nop 0
	global_load_lds_dwordx4 v146, s[22:23]
	s_add_i32 m0, s36, 0x14000
	s_add_u32 s54, s2, 0x40000
	s_addc_u32 s55, s3, 0
	global_load_lds_dwordx4 v168, s[54:55]
	s_add_i32 m0, s36, 0x16000
	s_add_u32 s22, s22, 0x40000
	s_addc_u32 s23, s23, 0
	global_load_lds_dwordx4 v148, s[54:55]
	s_waitcnt vmcnt(6)
	s_barrier
	v_mfma_f32_16x16x32_bf16 v[20:23], v[204:207], v[188:191], 0
	v_mfma_f32_16x16x32_bf16 v[16:19], v[212:215], v[188:191], 0
	v_mfma_f32_16x16x32_bf16 v[4:7], v[204:207], v[196:199], 0
	v_mfma_f32_16x16x32_bf16 v[0:3], v[212:215], v[196:199], 0
	v_mfma_f32_16x16x32_bf16 v[24:27], v[204:207], v[154:157], 0
	v_mfma_f32_16x16x32_bf16 v[28:31], v[212:215], v[154:157], 0
	v_mfma_f32_16x16x32_bf16 v[32:35], v[204:207], v[180:183], 0
	v_mfma_f32_16x16x32_bf16 v[36:39], v[212:215], v[180:183], 0
	v_mfma_f32_16x16x32_bf16 v[20:23], v[208:211], v[192:195], v[20:23]
	v_mfma_f32_16x16x32_bf16 v[16:19], v[216:219], v[192:195], v[16:19]
	v_mfma_f32_16x16x32_bf16 v[4:7], v[208:211], v[200:203], v[4:7]
	v_mfma_f32_16x16x32_bf16 v[0:3], v[216:219], v[200:203], v[0:3]
	v_mfma_f32_16x16x32_bf16 v[24:27], v[208:211], v[158:161], v[24:27]
	v_mfma_f32_16x16x32_bf16 v[28:31], v[216:219], v[158:161], v[28:31]
	v_mfma_f32_16x16x32_bf16 v[32:35], v[208:211], v[184:187], v[32:35]
	v_mfma_f32_16x16x32_bf16 v[36:39], v[216:219], v[184:187], v[36:39]
	s_barrier
	ds_read_b128 v[48:51], v164 offset:32768
	ds_read_b128 v[52:55], v164 offset:33792
	ds_read_b128 v[64:67], v164 offset:34816
	ds_read_b128 v[68:71], v164 offset:35840
	ds_read_b128 v[154:157], v165 offset:32768
	ds_read_b128 v[158:161], v165 offset:33792
	ds_read_b128 v[180:183], v165 offset:34816
	ds_read_b128 v[184:187], v165 offset:35840
	ds_read_b128 v[188:191], v165 offset:36864
	ds_read_b128 v[192:195], v165 offset:37888
	ds_read_b128 v[196:199], v165 offset:38912
	ds_read_b128 v[200:203], v165 offset:39936
	s_waitcnt lgkmcnt(8)
	s_barrier
	s_waitcnt lgkmcnt(0)
	v_mfma_f32_16x16x32_bf16 v[140:143], v[48:51], v[154:157], v[140:143]
	v_mfma_f32_16x16x32_bf16 v[136:139], v[64:67], v[154:157], v[136:139]
	v_mfma_f32_16x16x32_bf16 v[124:127], v[48:51], v[180:183], v[124:127]
	v_mfma_f32_16x16x32_bf16 v[120:123], v[64:67], v[180:183], v[120:123]
	v_mfma_f32_16x16x32_bf16 v[108:111], v[48:51], v[188:191], v[108:111]
	v_mfma_f32_16x16x32_bf16 v[104:107], v[64:67], v[188:191], v[104:107]
	v_mfma_f32_16x16x32_bf16 v[92:95], v[48:51], v[196:199], v[92:95]
	v_mfma_f32_16x16x32_bf16 v[88:91], v[64:67], v[196:199], v[88:91]
	v_mfma_f32_16x16x32_bf16 v[140:143], v[52:55], v[158:161], v[140:143]
	v_mfma_f32_16x16x32_bf16 v[136:139], v[68:71], v[158:161], v[136:139]
	v_mfma_f32_16x16x32_bf16 v[124:127], v[52:55], v[184:187], v[124:127]
	v_mfma_f32_16x16x32_bf16 v[120:123], v[68:71], v[184:187], v[120:123]
	v_mfma_f32_16x16x32_bf16 v[108:111], v[52:55], v[192:195], v[108:111]
	v_mfma_f32_16x16x32_bf16 v[104:107], v[68:71], v[192:195], v[104:107]
	v_mfma_f32_16x16x32_bf16 v[92:95], v[52:55], v[200:203], v[92:95]
	v_mfma_f32_16x16x32_bf16 v[88:91], v[68:71], v[200:203], v[88:91]
	s_barrier
	s_mov_b32 m0, s39
	ds_read_b128 v[204:207], v164 offset:49152
	ds_read_b128 v[208:211], v164 offset:50176
	ds_read_b128 v[212:215], v164 offset:51200
	global_load_lds_dwordx4 v144, s[22:23]
	s_mov_b32 m0, s40
	ds_read_b128 v[216:219], v164 offset:52224
	global_load_lds_dwordx4 v146, s[22:23]
	s_add_i32 m0, s36, 0x18000
	s_nop 0
	global_load_lds_dwordx4 v168, s[98:99]
	s_add_i32 m0, s36, 0x1a000
	s_nop 0
	global_load_lds_dwordx4 v148, s[98:99]
	s_barrier
	s_waitcnt lgkmcnt(0)
	v_mfma_f32_16x16x32_bf16 v[132:135], v[204:207], v[154:157], v[132:135]
	v_mfma_f32_16x16x32_bf16 v[128:131], v[212:215], v[154:157], v[128:131]
	v_mfma_f32_16x16x32_bf16 v[116:119], v[204:207], v[180:183], v[116:119]
	v_mfma_f32_16x16x32_bf16 v[112:115], v[212:215], v[180:183], v[112:115]
	v_mfma_f32_16x16x32_bf16 v[100:103], v[204:207], v[188:191], v[100:103]
	v_mfma_f32_16x16x32_bf16 v[96:99], v[212:215], v[188:191], v[96:99]
	v_mfma_f32_16x16x32_bf16 v[84:87], v[204:207], v[196:199], v[84:87]
	v_mfma_f32_16x16x32_bf16 v[80:83], v[212:215], v[196:199], v[80:83]
	v_mfma_f32_16x16x32_bf16 v[132:135], v[208:211], v[158:161], v[132:135]
	v_mfma_f32_16x16x32_bf16 v[128:131], v[216:219], v[158:161], v[128:131]
	v_mfma_f32_16x16x32_bf16 v[116:119], v[208:211], v[184:187], v[116:119]
	v_mfma_f32_16x16x32_bf16 v[112:115], v[216:219], v[184:187], v[112:115]
	v_mfma_f32_16x16x32_bf16 v[100:103], v[208:211], v[192:195], v[100:103]
	v_mfma_f32_16x16x32_bf16 v[96:99], v[216:219], v[192:195], v[96:99]
	v_mfma_f32_16x16x32_bf16 v[84:87], v[208:211], v[200:203], v[84:87]
	v_mfma_f32_16x16x32_bf16 v[80:83], v[216:219], v[200:203], v[80:83]
	s_barrier
	ds_read_b128 v[154:157], v165 offset:49152
	ds_read_b128 v[158:161], v165 offset:50176
	ds_read_b128 v[180:183], v165 offset:51200
	ds_read_b128 v[184:187], v165 offset:52224
	ds_read_b128 v[188:191], v165 offset:53248
	ds_read_b128 v[192:195], v165 offset:54272
	ds_read_b128 v[196:199], v165 offset:55296
	ds_read_b128 v[200:203], v165 offset:56320
	s_barrier
	s_waitcnt lgkmcnt(0)
	v_mfma_f32_16x16x32_bf16 v[76:79], v[48:51], v[154:157], v[76:79]
	v_mfma_f32_16x16x32_bf16 v[72:75], v[64:67], v[154:157], v[72:75]
	v_mfma_f32_16x16x32_bf16 v[60:63], v[48:51], v[180:183], v[60:63]
	v_mfma_f32_16x16x32_bf16 v[56:59], v[64:67], v[180:183], v[56:59]
	v_mfma_f32_16x16x32_bf16 v[44:47], v[48:51], v[188:191], v[44:47]
	v_mfma_f32_16x16x32_bf16 v[40:43], v[64:67], v[188:191], v[40:43]
	v_mfma_f32_16x16x32_bf16 v[12:15], v[48:51], v[196:199], v[12:15]
	v_mfma_f32_16x16x32_bf16 v[8:11], v[64:67], v[196:199], v[8:11]
	v_mfma_f32_16x16x32_bf16 v[76:79], v[52:55], v[158:161], v[76:79]
	v_mfma_f32_16x16x32_bf16 v[72:75], v[68:71], v[158:161], v[72:75]
	v_mfma_f32_16x16x32_bf16 v[60:63], v[52:55], v[184:187], v[60:63]
	v_mfma_f32_16x16x32_bf16 v[56:59], v[68:71], v[184:187], v[56:59]
	v_mfma_f32_16x16x32_bf16 v[44:47], v[52:55], v[192:195], v[44:47]
	v_mfma_f32_16x16x32_bf16 v[40:43], v[68:71], v[192:195], v[40:43]
	v_mfma_f32_16x16x32_bf16 v[12:15], v[52:55], v[200:203], v[12:15]
	v_mfma_f32_16x16x32_bf16 v[8:11], v[68:71], v[200:203], v[8:11]
	s_barrier
	s_mov_b32 m0, s45
	s_nop 0
	global_load_lds_dwordx4 v144, s[100:101]
	s_mov_b32 m0, s46
	s_nop 0
	global_load_lds_dwordx4 v146, s[100:101]
	s_add_i32 m0, s36, 0x1c000
	s_add_u32 s2, s2, 0x40080
	s_addc_u32 s3, s3, 0
	global_load_lds_dwordx4 v168, s[2:3]
	s_add_i32 m0, s36, 0x1e000
	s_add_i32 s52, s52, 2
	global_load_lds_dwordx4 v148, s[2:3]
	s_waitcnt vmcnt(6)
	s_barrier
	v_mfma_f32_16x16x32_bf16 v[24:27], v[204:207], v[154:157], v[24:27]
	v_mfma_f32_16x16x32_bf16 v[68:71], v[208:211], v[158:161], v[24:27]
	v_mfma_f32_16x16x32_bf16 v[24:27], v[212:215], v[154:157], v[28:31]
	v_mfma_f32_16x16x32_bf16 v[64:67], v[216:219], v[158:161], v[24:27]
	v_mfma_f32_16x16x32_bf16 v[24:27], v[204:207], v[180:183], v[32:35]
	v_mfma_f32_16x16x32_bf16 v[52:55], v[208:211], v[184:187], v[24:27]
	v_mfma_f32_16x16x32_bf16 v[24:27], v[212:215], v[180:183], v[36:39]
	v_mfma_f32_16x16x32_bf16 v[20:23], v[204:207], v[188:191], v[20:23]
	v_mfma_f32_16x16x32_bf16 v[16:19], v[212:215], v[188:191], v[16:19]
	v_mfma_f32_16x16x32_bf16 v[4:7], v[204:207], v[196:199], v[4:7]
	v_mfma_f32_16x16x32_bf16 v[0:3], v[212:215], v[196:199], v[0:3]
	v_mfma_f32_16x16x32_bf16 v[48:51], v[216:219], v[184:187], v[24:27]
	v_mfma_f32_16x16x32_bf16 v[20:23], v[208:211], v[192:195], v[20:23]
	v_mfma_f32_16x16x32_bf16 v[16:19], v[216:219], v[192:195], v[16:19]
	v_mfma_f32_16x16x32_bf16 v[4:7], v[208:211], v[200:203], v[4:7]
	v_mfma_f32_16x16x32_bf16 v[0:3], v[216:219], v[200:203], v[0:3]
	s_add_u32 s20, s20, 0x100
	s_addc_u32 s21, s21, 0
	s_add_u32 s50, s50, 0x100
	s_addc_u32 s51, s51, 0
	s_cmp_gt_u32 s52, 13
	s_barrier
.LBB0_123:
	s_add_u32 s2, s20, 0xfffc0080
	s_addc_u32 s3, s21, -1
	ds_read_b128 v[24:27], v164
	ds_read_b128 v[28:31], v164 offset:1024
	ds_read_b128 v[32:35], v164 offset:2048
	ds_read_b128 v[36:39], v164 offset:3072
	s_cmp_eq_u32 s52, 12
	s_cselect_b32 s23, s7, s3
	s_cselect_b32 s22, s9, s2
	s_cselect_b32 s3, s13, s51
	s_cselect_b32 s2, s15, s50
	ds_read_b128 v[154:157], v165
	ds_read_b128 v[158:161], v165 offset:1024
	ds_read_b128 v[180:183], v165 offset:2048
	ds_read_b128 v[184:187], v165 offset:3072
	ds_read_b128 v[188:191], v165 offset:4096
	ds_read_b128 v[192:195], v165 offset:5120
	ds_read_b128 v[196:199], v165 offset:6144
	ds_read_b128 v[200:203], v165 offset:7168
	s_waitcnt lgkmcnt(8)
	s_barrier
	s_waitcnt lgkmcnt(0)
	v_mfma_f32_16x16x32_bf16 v[140:143], v[24:27], v[154:157], v[140:143]
	v_mfma_f32_16x16x32_bf16 v[136:139], v[32:35], v[154:157], v[136:139]
	v_mfma_f32_16x16x32_bf16 v[124:127], v[24:27], v[180:183], v[124:127]
	v_mfma_f32_16x16x32_bf16 v[120:123], v[32:35], v[180:183], v[120:123]
	v_mfma_f32_16x16x32_bf16 v[108:111], v[24:27], v[188:191], v[108:111]
	v_mfma_f32_16x16x32_bf16 v[104:107], v[32:35], v[188:191], v[104:107]
	v_mfma_f32_16x16x32_bf16 v[92:95], v[24:27], v[196:199], v[92:95]
	v_mfma_f32_16x16x32_bf16 v[88:91], v[32:35], v[196:199], v[88:91]
	v_mfma_f32_16x16x32_bf16 v[140:143], v[28:31], v[158:161], v[140:143]
	v_mfma_f32_16x16x32_bf16 v[136:139], v[36:39], v[158:161], v[136:139]
	v_mfma_f32_16x16x32_bf16 v[124:127], v[28:31], v[184:187], v[124:127]
	v_mfma_f32_16x16x32_bf16 v[120:123], v[36:39], v[184:187], v[120:123]
	v_mfma_f32_16x16x32_bf16 v[108:111], v[28:31], v[192:195], v[108:111]
	v_mfma_f32_16x16x32_bf16 v[104:107], v[36:39], v[192:195], v[104:107]
	v_mfma_f32_16x16x32_bf16 v[92:95], v[28:31], v[200:203], v[92:95]
	v_mfma_f32_16x16x32_bf16 v[88:91], v[36:39], v[200:203], v[88:91]
	s_barrier
	s_add_i32 m0, s37, 0xc000
	ds_read_b128 v[204:207], v164 offset:16384
	ds_read_b128 v[208:211], v164 offset:17408
	ds_read_b128 v[212:215], v164 offset:18432
	global_load_lds_dwordx4 v150, s[20:21]
	s_add_i32 m0, s37, 0xe000
	ds_read_b128 v[216:219], v164 offset:19456
	global_load_lds_dwordx4 v152, s[20:21]
	s_add_u32 s98, s2, 0x80
	s_addc_u32 s99, s3, 0
	s_add_i32 m0, s36, 0x10000
	s_nop 0
	global_load_lds_dwordx4 v168, s[2:3]
	s_add_i32 m0, s36, 0x12000
	s_nop 0
	global_load_lds_dwordx4 v148, s[2:3]
	s_barrier
	s_waitcnt lgkmcnt(0)
	v_mfma_f32_16x16x32_bf16 v[132:135], v[204:207], v[154:157], v[132:135]
	v_mfma_f32_16x16x32_bf16 v[128:131], v[212:215], v[154:157], v[128:131]
	v_mfma_f32_16x16x32_bf16 v[116:119], v[204:207], v[180:183], v[116:119]
	v_mfma_f32_16x16x32_bf16 v[112:115], v[212:215], v[180:183], v[112:115]
	v_mfma_f32_16x16x32_bf16 v[100:103], v[204:207], v[188:191], v[100:103]
	v_mfma_f32_16x16x32_bf16 v[96:99], v[212:215], v[188:191], v[96:99]
	v_mfma_f32_16x16x32_bf16 v[84:87], v[204:207], v[196:199], v[84:87]
	v_mfma_f32_16x16x32_bf16 v[80:83], v[212:215], v[196:199], v[80:83]
	v_mfma_f32_16x16x32_bf16 v[132:135], v[208:211], v[158:161], v[132:135]
	v_mfma_f32_16x16x32_bf16 v[128:131], v[216:219], v[158:161], v[128:131]
	v_mfma_f32_16x16x32_bf16 v[116:119], v[208:211], v[184:187], v[116:119]
	v_mfma_f32_16x16x32_bf16 v[112:115], v[216:219], v[184:187], v[112:115]
	v_mfma_f32_16x16x32_bf16 v[100:103], v[208:211], v[192:195], v[100:103]
	v_mfma_f32_16x16x32_bf16 v[96:99], v[216:219], v[192:195], v[96:99]
	v_mfma_f32_16x16x32_bf16 v[84:87], v[208:211], v[200:203], v[84:87]
	v_mfma_f32_16x16x32_bf16 v[80:83], v[216:219], v[200:203], v[80:83]
	s_add_u32 s100, s22, 0x80
	s_addc_u32 s101, s23, 0
	s_barrier
	ds_read_b128 v[154:157], v165 offset:16384
	ds_read_b128 v[158:161], v165 offset:17408
	ds_read_b128 v[180:183], v165 offset:18432
	ds_read_b128 v[184:187], v165 offset:19456
	ds_read_b128 v[188:191], v165 offset:20480
	ds_read_b128 v[192:195], v165 offset:21504
	ds_read_b128 v[196:199], v165 offset:22528
	ds_read_b128 v[200:203], v165 offset:23552
	s_barrier
	s_waitcnt lgkmcnt(0)
	v_mfma_f32_16x16x32_bf16 v[76:79], v[24:27], v[154:157], v[76:79]
	v_mfma_f32_16x16x32_bf16 v[72:75], v[32:35], v[154:157], v[72:75]
	v_mfma_f32_16x16x32_bf16 v[60:63], v[24:27], v[180:183], v[60:63]
	v_mfma_f32_16x16x32_bf16 v[56:59], v[32:35], v[180:183], v[56:59]
	v_mfma_f32_16x16x32_bf16 v[44:47], v[24:27], v[188:191], v[44:47]
	v_mfma_f32_16x16x32_bf16 v[40:43], v[32:35], v[188:191], v[40:43]
	v_mfma_f32_16x16x32_bf16 v[12:15], v[24:27], v[196:199], v[12:15]
	v_mfma_f32_16x16x32_bf16 v[8:11], v[32:35], v[196:199], v[8:11]
	v_mfma_f32_16x16x32_bf16 v[76:79], v[28:31], v[158:161], v[76:79]
	v_mfma_f32_16x16x32_bf16 v[72:75], v[36:39], v[158:161], v[72:75]
	v_mfma_f32_16x16x32_bf16 v[60:63], v[28:31], v[184:187], v[60:63]
	v_mfma_f32_16x16x32_bf16 v[56:59], v[36:39], v[184:187], v[56:59]
	v_mfma_f32_16x16x32_bf16 v[44:47], v[28:31], v[192:195], v[44:47]
	v_mfma_f32_16x16x32_bf16 v[40:43], v[36:39], v[192:195], v[40:43]
	v_mfma_f32_16x16x32_bf16 v[12:15], v[28:31], v[200:203], v[12:15]
	v_mfma_f32_16x16x32_bf16 v[8:11], v[36:39], v[200:203], v[8:11]
	s_barrier
	s_mov_b32 m0, s37
	s_nop 0
	global_load_lds_dwordx4 v144, s[22:23]
	s_mov_b32 m0, s38
	s_nop 0
	global_load_lds_dwordx4 v146, s[22:23]
	s_add_i32 m0, s36, 0x14000
	s_add_u32 s54, s2, 0x40000
	s_addc_u32 s55, s3, 0
	global_load_lds_dwordx4 v168, s[54:55]
	s_add_i32 m0, s36, 0x16000
	s_add_u32 s22, s22, 0x40000
	s_addc_u32 s23, s23, 0
	global_load_lds_dwordx4 v148, s[54:55]
	s_waitcnt vmcnt(6)
	s_barrier
	v_mfma_f32_16x16x32_bf16 v[20:23], v[204:207], v[188:191], v[20:23]
	v_mfma_f32_16x16x32_bf16 v[16:19], v[212:215], v[188:191], v[16:19]
	v_mfma_f32_16x16x32_bf16 v[4:7], v[204:207], v[196:199], v[4:7]
	v_mfma_f32_16x16x32_bf16 v[0:3], v[212:215], v[196:199], v[0:3]
	v_mfma_f32_16x16x32_bf16 v[24:27], v[204:207], v[154:157], v[68:71]
	v_mfma_f32_16x16x32_bf16 v[28:31], v[212:215], v[154:157], v[64:67]
	v_mfma_f32_16x16x32_bf16 v[32:35], v[204:207], v[180:183], v[52:55]
	v_mfma_f32_16x16x32_bf16 v[36:39], v[212:215], v[180:183], v[48:51]
	v_mfma_f32_16x16x32_bf16 v[20:23], v[208:211], v[192:195], v[20:23]
	v_mfma_f32_16x16x32_bf16 v[16:19], v[216:219], v[192:195], v[16:19]
	v_mfma_f32_16x16x32_bf16 v[4:7], v[208:211], v[200:203], v[4:7]
	v_mfma_f32_16x16x32_bf16 v[0:3], v[216:219], v[200:203], v[0:3]
	v_mfma_f32_16x16x32_bf16 v[24:27], v[208:211], v[158:161], v[24:27]
	v_mfma_f32_16x16x32_bf16 v[28:31], v[216:219], v[158:161], v[28:31]
	v_mfma_f32_16x16x32_bf16 v[32:35], v[208:211], v[184:187], v[32:35]
	v_mfma_f32_16x16x32_bf16 v[36:39], v[216:219], v[184:187], v[36:39]
	s_barrier
	ds_read_b128 v[48:51], v164 offset:32768
	ds_read_b128 v[52:55], v164 offset:33792
	ds_read_b128 v[64:67], v164 offset:34816
	ds_read_b128 v[68:71], v164 offset:35840
	ds_read_b128 v[154:157], v165 offset:32768
	ds_read_b128 v[158:161], v165 offset:33792
	ds_read_b128 v[180:183], v165 offset:34816
	ds_read_b128 v[184:187], v165 offset:35840
	ds_read_b128 v[188:191], v165 offset:36864
	ds_read_b128 v[192:195], v165 offset:37888
	ds_read_b128 v[196:199], v165 offset:38912
	ds_read_b128 v[200:203], v165 offset:39936
	s_waitcnt lgkmcnt(8)
	s_barrier
	s_waitcnt lgkmcnt(0)
	v_mfma_f32_16x16x32_bf16 v[140:143], v[48:51], v[154:157], v[140:143]
	v_mfma_f32_16x16x32_bf16 v[136:139], v[64:67], v[154:157], v[136:139]
	v_mfma_f32_16x16x32_bf16 v[124:127], v[48:51], v[180:183], v[124:127]
	v_mfma_f32_16x16x32_bf16 v[120:123], v[64:67], v[180:183], v[120:123]
	v_mfma_f32_16x16x32_bf16 v[108:111], v[48:51], v[188:191], v[108:111]
	v_mfma_f32_16x16x32_bf16 v[104:107], v[64:67], v[188:191], v[104:107]
	v_mfma_f32_16x16x32_bf16 v[92:95], v[48:51], v[196:199], v[92:95]
	v_mfma_f32_16x16x32_bf16 v[88:91], v[64:67], v[196:199], v[88:91]
	v_mfma_f32_16x16x32_bf16 v[140:143], v[52:55], v[158:161], v[140:143]
	v_mfma_f32_16x16x32_bf16 v[136:139], v[68:71], v[158:161], v[136:139]
	v_mfma_f32_16x16x32_bf16 v[124:127], v[52:55], v[184:187], v[124:127]
	v_mfma_f32_16x16x32_bf16 v[120:123], v[68:71], v[184:187], v[120:123]
	v_mfma_f32_16x16x32_bf16 v[108:111], v[52:55], v[192:195], v[108:111]
	v_mfma_f32_16x16x32_bf16 v[104:107], v[68:71], v[192:195], v[104:107]
	v_mfma_f32_16x16x32_bf16 v[92:95], v[52:55], v[200:203], v[92:95]
	v_mfma_f32_16x16x32_bf16 v[88:91], v[68:71], v[200:203], v[88:91]
	s_barrier
	s_mov_b32 m0, s39
	ds_read_b128 v[204:207], v164 offset:49152
	ds_read_b128 v[208:211], v164 offset:50176
	ds_read_b128 v[212:215], v164 offset:51200
	global_load_lds_dwordx4 v144, s[22:23]
	s_mov_b32 m0, s40
	ds_read_b128 v[216:219], v164 offset:52224
	global_load_lds_dwordx4 v146, s[22:23]
	s_add_i32 m0, s36, 0x18000
	s_nop 0
	global_load_lds_dwordx4 v168, s[98:99]
	s_add_i32 m0, s36, 0x1a000
	s_nop 0
	global_load_lds_dwordx4 v148, s[98:99]
	s_barrier
	s_waitcnt lgkmcnt(0)
	v_mfma_f32_16x16x32_bf16 v[132:135], v[204:207], v[154:157], v[132:135]
	v_mfma_f32_16x16x32_bf16 v[128:131], v[212:215], v[154:157], v[128:131]
	v_mfma_f32_16x16x32_bf16 v[116:119], v[204:207], v[180:183], v[116:119]
	v_mfma_f32_16x16x32_bf16 v[112:115], v[212:215], v[180:183], v[112:115]
	v_mfma_f32_16x16x32_bf16 v[100:103], v[204:207], v[188:191], v[100:103]
	v_mfma_f32_16x16x32_bf16 v[96:99], v[212:215], v[188:191], v[96:99]
	v_mfma_f32_16x16x32_bf16 v[84:87], v[204:207], v[196:199], v[84:87]
	v_mfma_f32_16x16x32_bf16 v[80:83], v[212:215], v[196:199], v[80:83]
	v_mfma_f32_16x16x32_bf16 v[132:135], v[208:211], v[158:161], v[132:135]
	v_mfma_f32_16x16x32_bf16 v[128:131], v[216:219], v[158:161], v[128:131]
	v_mfma_f32_16x16x32_bf16 v[116:119], v[208:211], v[184:187], v[116:119]
	v_mfma_f32_16x16x32_bf16 v[112:115], v[216:219], v[184:187], v[112:115]
	v_mfma_f32_16x16x32_bf16 v[100:103], v[208:211], v[192:195], v[100:103]
	v_mfma_f32_16x16x32_bf16 v[96:99], v[216:219], v[192:195], v[96:99]
	v_mfma_f32_16x16x32_bf16 v[84:87], v[208:211], v[200:203], v[84:87]
	v_mfma_f32_16x16x32_bf16 v[80:83], v[216:219], v[200:203], v[80:83]
	s_barrier
	ds_read_b128 v[154:157], v165 offset:49152
	ds_read_b128 v[158:161], v165 offset:50176
	ds_read_b128 v[180:183], v165 offset:51200
	ds_read_b128 v[184:187], v165 offset:52224
	ds_read_b128 v[188:191], v165 offset:53248
	ds_read_b128 v[192:195], v165 offset:54272
	ds_read_b128 v[196:199], v165 offset:55296
	ds_read_b128 v[200:203], v165 offset:56320
	s_barrier
	s_waitcnt lgkmcnt(0)
	v_mfma_f32_16x16x32_bf16 v[76:79], v[48:51], v[154:157], v[76:79]
	v_mfma_f32_16x16x32_bf16 v[72:75], v[64:67], v[154:157], v[72:75]
	v_mfma_f32_16x16x32_bf16 v[60:63], v[48:51], v[180:183], v[60:63]
	v_mfma_f32_16x16x32_bf16 v[56:59], v[64:67], v[180:183], v[56:59]
	v_mfma_f32_16x16x32_bf16 v[44:47], v[48:51], v[188:191], v[44:47]
	v_mfma_f32_16x16x32_bf16 v[40:43], v[64:67], v[188:191], v[40:43]
	v_mfma_f32_16x16x32_bf16 v[12:15], v[48:51], v[196:199], v[12:15]
	v_mfma_f32_16x16x32_bf16 v[8:11], v[64:67], v[196:199], v[8:11]
	v_mfma_f32_16x16x32_bf16 v[76:79], v[52:55], v[158:161], v[76:79]
	v_mfma_f32_16x16x32_bf16 v[72:75], v[68:71], v[158:161], v[72:75]
	v_mfma_f32_16x16x32_bf16 v[60:63], v[52:55], v[184:187], v[60:63]
	v_mfma_f32_16x16x32_bf16 v[56:59], v[68:71], v[184:187], v[56:59]
	v_mfma_f32_16x16x32_bf16 v[44:47], v[52:55], v[192:195], v[44:47]
	v_mfma_f32_16x16x32_bf16 v[40:43], v[68:71], v[192:195], v[40:43]
	v_mfma_f32_16x16x32_bf16 v[12:15], v[52:55], v[200:203], v[12:15]
	v_mfma_f32_16x16x32_bf16 v[8:11], v[68:71], v[200:203], v[8:11]
	s_barrier
	s_mov_b32 m0, s45
	s_nop 0
	global_load_lds_dwordx4 v144, s[100:101]
	s_mov_b32 m0, s46
	s_nop 0
	global_load_lds_dwordx4 v146, s[100:101]
	s_add_i32 m0, s36, 0x1c000
	s_add_u32 s2, s2, 0x40080
	s_addc_u32 s3, s3, 0
	global_load_lds_dwordx4 v168, s[2:3]
	s_add_i32 m0, s36, 0x1e000
	s_add_i32 s52, s52, 2
	global_load_lds_dwordx4 v148, s[2:3]
	s_waitcnt vmcnt(6)
	s_barrier
	v_mfma_f32_16x16x32_bf16 v[24:27], v[204:207], v[154:157], v[24:27]
	v_mfma_f32_16x16x32_bf16 v[68:71], v[208:211], v[158:161], v[24:27]
	v_mfma_f32_16x16x32_bf16 v[24:27], v[212:215], v[154:157], v[28:31]
	v_mfma_f32_16x16x32_bf16 v[64:67], v[216:219], v[158:161], v[24:27]
	v_mfma_f32_16x16x32_bf16 v[24:27], v[204:207], v[180:183], v[32:35]
	v_mfma_f32_16x16x32_bf16 v[52:55], v[208:211], v[184:187], v[24:27]
	v_mfma_f32_16x16x32_bf16 v[24:27], v[212:215], v[180:183], v[36:39]
	v_mfma_f32_16x16x32_bf16 v[20:23], v[204:207], v[188:191], v[20:23]
	v_mfma_f32_16x16x32_bf16 v[16:19], v[212:215], v[188:191], v[16:19]
	v_mfma_f32_16x16x32_bf16 v[4:7], v[204:207], v[196:199], v[4:7]
	v_mfma_f32_16x16x32_bf16 v[0:3], v[212:215], v[196:199], v[0:3]
	v_mfma_f32_16x16x32_bf16 v[48:51], v[216:219], v[184:187], v[24:27]
	v_mfma_f32_16x16x32_bf16 v[20:23], v[208:211], v[192:195], v[20:23]
	v_mfma_f32_16x16x32_bf16 v[16:19], v[216:219], v[192:195], v[16:19]
	v_mfma_f32_16x16x32_bf16 v[4:7], v[208:211], v[200:203], v[4:7]
	v_mfma_f32_16x16x32_bf16 v[0:3], v[216:219], v[200:203], v[0:3]
	s_add_u32 s20, s20, 0x100
	s_addc_u32 s21, s21, 0
	s_add_u32 s50, s50, 0x100
	s_addc_u32 s51, s51, 0
	s_cmp_gt_u32 s52, 13
	s_barrier
	s_cbranch_scc0 .LBB0_123
	s_lshl_b32 s2, s6, 8
	s_add_i32 s3, s2, s43
	s_lshl_b32 s2, s8, 8
	s_cmp_gt_i32 s8, 3
	s_cselect_b64 s[20:21], -1, 0
	s_and_b64 s[22:23], s[20:21], exec
	s_mov_b32 s7, 0x8982000
	s_cselect_b32 s7, s7, 0x7182000
	s_add_u32 s22, s26, s7
	s_addc_u32 s23, s25, 0
	s_add_i32 s7, s6, -16
	v_mov_b32_e32 v160, v163
	v_mov_b32_e32 v24, v162
	s_lshr_b32 s7, s7, 3
	s_add_i32 s96, s7, 1
	v_add_u32_e32 v154, s3, v24
	s_lshl_b64 s[50:51], s[96:97], 11
	v_ashrrev_i32_e32 v155, 31, v154
	s_cmp_gt_i32 s6, 15
	v_lshl_add_u64 v[156:157], v[154:155], 2, s[10:11]
	s_cselect_b32 s7, s51, 0
	s_cselect_b32 s6, s50, 0
	global_load_dword v166, v[156:157], off
	global_load_dword v191, v[156:157], off offset:64
	global_load_dword v192, v[156:157], off offset:128
	global_load_dword v193, v[156:157], off offset:192
	global_load_dword v194, v[156:157], off offset:512
	global_load_dword v195, v[156:157], off offset:576
	global_load_dword v196, v[156:157], off offset:640
	global_load_dword v197, v[156:157], off offset:704
	s_lshl_b64 s[6:7], s[6:7], 2
	s_add_u32 s9, s41, s6
	s_addc_u32 s13, s42, s7
	s_ashr_i32 s3, s2, 31
	s_lshl_b64 s[6:7], s[2:3], 2
	s_add_u32 s3, s9, s6
	s_addc_u32 s7, s13, s7
	v_lshlrev_b32_e32 v158, 3, v160
	s_add_u32 s6, s3, s49
	s_addc_u32 s7, s7, 0
	v_ashrrev_i32_e32 v159, 31, v158
	v_lshl_add_u64 v[24:25], v[158:159], 2, s[6:7]
	global_load_dwordx4 v[36:39], v[24:25], off
	global_load_dwordx4 v[32:35], v[24:25], off offset:16
	global_load_dwordx4 v[28:31], v[24:25], off offset:512
	s_nop 0
	global_load_dwordx4 v[24:27], v[24:25], off offset:528
	s_and_b32 s2, s2, 0x300
	s_or_b32 s2, s2, s44
	v_add_u32_e32 v158, s2, v158
	v_cmp_eq_u32_e64 s[6:7], 0, v160
	v_lshlrev_b64 v[160:161], 11, v[154:155]
	s_cmp_lt_i32 s8, 4
	s_waitcnt vmcnt(0)
	v_ashrrev_i32_e32 v159, 31, v158
	v_lshl_add_u64 v[158:159], v[158:159], 1, s[22:23]
	v_lshl_add_u64 v[160:161], v[158:159], 0, v[160:161]
	v_lshl_add_u64 v[156:157], v[154:155], 2, s[0:1]
	s_and_b64 s[6:7], s[6:7], s[20:21]
	s_mov_b64 s[2:3], 0x8000
	s_mov_b64 s[50:51], 0x28000
	v_mov_b32_e32 v180, 0xc0135761
	v_mov_b32_e32 v181, 0xc0135761
	v_mov_b32_e32 v182, 0xbdd2d3e7
	v_mov_b32_e32 v183, 0xbdd2d3e7
	v_fmamk_f32 v166, v166, 0x3a800000, v225
	v_fmamk_f32 v190, v191, 0x3a800000, v225
	v_fmamk_f32 v192, v192, 0x3a800000, v225
	v_fmamk_f32 v188, v193, 0x3a800000, v225
	v_fmamk_f32 v194, v194, 0x3a800000, v225
	v_fmamk_f32 v186, v195, 0x3a800000, v225
	v_fmamk_f32 v196, v196, 0x3a800000, v225
	v_fmamk_f32 v184, v197, 0x3a800000, v225
	v_rsq_f32_e32 v166, v166
	v_rsq_f32_e32 v190, v190
	v_rsq_f32_e32 v192, v192
	v_rsq_f32_e32 v188, v188
	v_rsq_f32_e32 v194, v194
	v_rsq_f32_e32 v186, v186
	v_rsq_f32_e32 v196, v196
	v_rsq_f32_e32 v184, v184
	v_pk_fma_f32 v[140:141], v[140:141], v[166:167], v[36:37] op_sel_hi:[1,0,1]
	v_pk_fma_f32 v[142:143], v[142:143], v[166:167], v[38:39] op_sel_hi:[1,0,1]
	v_pk_fma_f32 v[136:137], v[136:137], v[166:167], v[32:33] op_sel_hi:[1,0,1]
	v_pk_fma_f32 v[138:139], v[138:139], v[166:167], v[34:35] op_sel_hi:[1,0,1]
	v_pk_fma_f32 v[132:133], v[132:133], v[166:167], v[28:29] op_sel_hi:[1,0,1]
	v_pk_fma_f32 v[134:135], v[134:135], v[166:167], v[30:31] op_sel_hi:[1,0,1]
	v_pk_fma_f32 v[128:129], v[128:129], v[166:167], v[24:25] op_sel_hi:[1,0,1]
	v_pk_fma_f32 v[130:131], v[130:131], v[166:167], v[26:27] op_sel_hi:[1,0,1]
	v_pk_fma_f32 v[124:125], v[124:125], v[190:191], v[36:37] op_sel_hi:[1,0,1]
	v_pk_fma_f32 v[126:127], v[126:127], v[190:191], v[38:39] op_sel_hi:[1,0,1]
	v_pk_fma_f32 v[120:121], v[120:121], v[190:191], v[32:33] op_sel_hi:[1,0,1]
	v_pk_fma_f32 v[122:123], v[122:123], v[190:191], v[34:35] op_sel_hi:[1,0,1]
	v_pk_fma_f32 v[116:117], v[116:117], v[190:191], v[28:29] op_sel_hi:[1,0,1]
	v_pk_fma_f32 v[118:119], v[118:119], v[190:191], v[30:31] op_sel_hi:[1,0,1]
	v_pk_fma_f32 v[112:113], v[112:113], v[190:191], v[24:25] op_sel_hi:[1,0,1]
	v_pk_fma_f32 v[114:115], v[114:115], v[190:191], v[26:27] op_sel_hi:[1,0,1]
	v_pk_fma_f32 v[108:109], v[108:109], v[192:193], v[36:37] op_sel_hi:[1,0,1]
	v_pk_fma_f32 v[110:111], v[110:111], v[192:193], v[38:39] op_sel_hi:[1,0,1]
	v_pk_fma_f32 v[104:105], v[104:105], v[192:193], v[32:33] op_sel_hi:[1,0,1]
	v_pk_fma_f32 v[106:107], v[106:107], v[192:193], v[34:35] op_sel_hi:[1,0,1]
	v_pk_fma_f32 v[100:101], v[100:101], v[192:193], v[28:29] op_sel_hi:[1,0,1]
	v_pk_fma_f32 v[102:103], v[102:103], v[192:193], v[30:31] op_sel_hi:[1,0,1]
	v_pk_fma_f32 v[96:97], v[96:97], v[192:193], v[24:25] op_sel_hi:[1,0,1]
	v_pk_fma_f32 v[98:99], v[98:99], v[192:193], v[26:27] op_sel_hi:[1,0,1]
	v_pk_fma_f32 v[92:93], v[92:93], v[188:189], v[36:37] op_sel_hi:[1,0,1]
	v_pk_fma_f32 v[94:95], v[94:95], v[188:189], v[38:39] op_sel_hi:[1,0,1]
	v_pk_fma_f32 v[88:89], v[88:89], v[188:189], v[32:33] op_sel_hi:[1,0,1]
	v_pk_fma_f32 v[90:91], v[90:91], v[188:189], v[34:35] op_sel_hi:[1,0,1]
	v_pk_fma_f32 v[84:85], v[84:85], v[188:189], v[28:29] op_sel_hi:[1,0,1]
	v_pk_fma_f32 v[86:87], v[86:87], v[188:189], v[30:31] op_sel_hi:[1,0,1]
	v_pk_fma_f32 v[80:81], v[80:81], v[188:189], v[24:25] op_sel_hi:[1,0,1]
	v_pk_fma_f32 v[82:83], v[82:83], v[188:189], v[26:27] op_sel_hi:[1,0,1]
	v_pk_fma_f32 v[76:77], v[76:77], v[194:195], v[36:37] op_sel_hi:[1,0,1]
	v_pk_fma_f32 v[78:79], v[78:79], v[194:195], v[38:39] op_sel_hi:[1,0,1]
	v_pk_fma_f32 v[72:73], v[72:73], v[194:195], v[32:33] op_sel_hi:[1,0,1]
	v_pk_fma_f32 v[74:75], v[74:75], v[194:195], v[34:35] op_sel_hi:[1,0,1]
	v_pk_fma_f32 v[68:69], v[68:69], v[194:195], v[28:29] op_sel_hi:[1,0,1]
	v_pk_fma_f32 v[70:71], v[70:71], v[194:195], v[30:31] op_sel_hi:[1,0,1]
	v_pk_fma_f32 v[64:65], v[64:65], v[194:195], v[24:25] op_sel_hi:[1,0,1]
	v_pk_fma_f32 v[66:67], v[66:67], v[194:195], v[26:27] op_sel_hi:[1,0,1]
	v_pk_fma_f32 v[60:61], v[60:61], v[186:187], v[36:37] op_sel_hi:[1,0,1]
	v_pk_fma_f32 v[62:63], v[62:63], v[186:187], v[38:39] op_sel_hi:[1,0,1]
	v_pk_fma_f32 v[56:57], v[56:57], v[186:187], v[32:33] op_sel_hi:[1,0,1]
	v_pk_fma_f32 v[58:59], v[58:59], v[186:187], v[34:35] op_sel_hi:[1,0,1]
	v_pk_fma_f32 v[52:53], v[52:53], v[186:187], v[28:29] op_sel_hi:[1,0,1]
	v_pk_fma_f32 v[54:55], v[54:55], v[186:187], v[30:31] op_sel_hi:[1,0,1]
	v_pk_fma_f32 v[48:49], v[48:49], v[186:187], v[24:25] op_sel_hi:[1,0,1]
	v_pk_fma_f32 v[50:51], v[50:51], v[186:187], v[26:27] op_sel_hi:[1,0,1]
	v_pk_fma_f32 v[44:45], v[44:45], v[196:197], v[36:37] op_sel_hi:[1,0,1]
	v_pk_fma_f32 v[46:47], v[46:47], v[196:197], v[38:39] op_sel_hi:[1,0,1]
	v_pk_fma_f32 v[40:41], v[40:41], v[196:197], v[32:33] op_sel_hi:[1,0,1]
	v_pk_fma_f32 v[42:43], v[42:43], v[196:197], v[34:35] op_sel_hi:[1,0,1]
	v_pk_fma_f32 v[20:21], v[20:21], v[196:197], v[28:29] op_sel_hi:[1,0,1]
	v_pk_fma_f32 v[22:23], v[22:23], v[196:197], v[30:31] op_sel_hi:[1,0,1]
	v_pk_fma_f32 v[16:17], v[16:17], v[196:197], v[24:25] op_sel_hi:[1,0,1]
	v_pk_fma_f32 v[18:19], v[18:19], v[196:197], v[26:27] op_sel_hi:[1,0,1]
	v_pk_fma_f32 v[12:13], v[12:13], v[184:185], v[36:37] op_sel_hi:[1,0,1]
	v_pk_fma_f32 v[14:15], v[14:15], v[184:185], v[38:39] op_sel_hi:[1,0,1]
	v_pk_fma_f32 v[8:9], v[8:9], v[184:185], v[32:33] op_sel_hi:[1,0,1]
	v_pk_fma_f32 v[10:11], v[10:11], v[184:185], v[34:35] op_sel_hi:[1,0,1]
	v_pk_fma_f32 v[4:5], v[4:5], v[184:185], v[28:29] op_sel_hi:[1,0,1]
	v_pk_fma_f32 v[6:7], v[6:7], v[184:185], v[30:31] op_sel_hi:[1,0,1]
	v_pk_fma_f32 v[0:1], v[0:1], v[184:185], v[24:25] op_sel_hi:[1,0,1]
	v_pk_fma_f32 v[2:3], v[2:3], v[184:185], v[26:27] op_sel_hi:[1,0,1]
	v_pk_mul_f32 v[24:25], v[140:141], v[140:141]
	v_pk_mul_f32 v[26:27], v[142:143], v[142:143]
	v_pk_mul_f32 v[28:29], v[136:137], v[136:137]
	v_pk_mul_f32 v[30:31], v[138:139], v[138:139]
	v_pk_mul_f32 v[32:33], v[132:133], v[132:133]
	v_pk_mul_f32 v[34:35], v[134:135], v[134:135]
	v_pk_mul_f32 v[36:37], v[128:129], v[128:129]
	v_pk_mul_f32 v[38:39], v[130:131], v[130:131]
	v_pk_fma_f32 v[24:25], v[24:25], v[182:183], v[180:181]
	v_pk_fma_f32 v[26:27], v[26:27], v[182:183], v[180:181]
	v_pk_fma_f32 v[28:29], v[28:29], v[182:183], v[180:181]
	v_pk_fma_f32 v[30:31], v[30:31], v[182:183], v[180:181]
	v_pk_fma_f32 v[32:33], v[32:33], v[182:183], v[180:181]
	v_pk_fma_f32 v[34:35], v[34:35], v[182:183], v[180:181]
	v_pk_fma_f32 v[36:37], v[36:37], v[182:183], v[180:181]
	v_pk_fma_f32 v[38:39], v[38:39], v[182:183], v[180:181]
	v_pk_mul_f32 v[24:25], v[24:25], v[140:141]
	v_pk_mul_f32 v[26:27], v[26:27], v[142:143]
	v_pk_mul_f32 v[28:29], v[28:29], v[136:137]
	v_pk_mul_f32 v[30:31], v[30:31], v[138:139]
	v_pk_mul_f32 v[32:33], v[32:33], v[132:133]
	v_pk_mul_f32 v[34:35], v[34:35], v[134:135]
	v_pk_mul_f32 v[36:37], v[36:37], v[128:129]
	v_pk_mul_f32 v[38:39], v[38:39], v[130:131]
	v_exp_f32_e32 v24, v24
	v_exp_f32_e32 v25, v25
	v_exp_f32_e32 v26, v26
	v_exp_f32_e32 v27, v27
	v_exp_f32_e32 v28, v28
	v_exp_f32_e32 v29, v29
	v_exp_f32_e32 v30, v30
	v_exp_f32_e32 v31, v31
	v_exp_f32_e32 v32, v32
	v_exp_f32_e32 v33, v33
	v_exp_f32_e32 v34, v34
	v_exp_f32_e32 v35, v35
	v_exp_f32_e32 v36, v36
	v_exp_f32_e32 v37, v37
	v_exp_f32_e32 v38, v38
	v_exp_f32_e32 v39, v39
	v_pk_add_f32 v[24:25], v[24:25], 1.0 op_sel_hi:[1,0]
	v_pk_add_f32 v[26:27], v[26:27], 1.0 op_sel_hi:[1,0]
	v_pk_add_f32 v[28:29], v[28:29], 1.0 op_sel_hi:[1,0]
	v_pk_add_f32 v[30:31], v[30:31], 1.0 op_sel_hi:[1,0]
	v_pk_add_f32 v[32:33], v[32:33], 1.0 op_sel_hi:[1,0]
	v_pk_add_f32 v[34:35], v[34:35], 1.0 op_sel_hi:[1,0]
	v_pk_add_f32 v[36:37], v[36:37], 1.0 op_sel_hi:[1,0]
	v_pk_add_f32 v[38:39], v[38:39], 1.0 op_sel_hi:[1,0]
	v_rcp_f32_e32 v24, v24
	v_rcp_f32_e32 v25, v25
	v_rcp_f32_e32 v26, v26
	v_rcp_f32_e32 v27, v27
	v_rcp_f32_e32 v28, v28
	v_rcp_f32_e32 v29, v29
	v_rcp_f32_e32 v30, v30
	v_rcp_f32_e32 v31, v31
	v_rcp_f32_e32 v32, v32
	v_rcp_f32_e32 v33, v33
	v_rcp_f32_e32 v34, v34
	v_rcp_f32_e32 v35, v35
	v_rcp_f32_e32 v36, v36
	v_rcp_f32_e32 v37, v37
	v_rcp_f32_e32 v38, v38
	v_rcp_f32_e32 v39, v39
	v_pk_mul_f32 v[140:141], v[140:141], v[24:25]
	v_pk_mul_f32 v[142:143], v[142:143], v[26:27]
	v_pk_mul_f32 v[136:137], v[136:137], v[28:29]
	v_pk_mul_f32 v[138:139], v[138:139], v[30:31]
	v_pk_mul_f32 v[132:133], v[132:133], v[32:33]
	v_pk_mul_f32 v[134:135], v[134:135], v[34:35]
	v_pk_mul_f32 v[128:129], v[128:129], v[36:37]
	v_pk_mul_f32 v[130:131], v[130:131], v[38:39]
	v_cvt_pk_bf16_f32 v24, v140, v141
	v_cvt_pk_bf16_f32 v25, v142, v143
	v_cvt_pk_bf16_f32 v26, v136, v137
	v_cvt_pk_bf16_f32 v27, v138, v139
	v_cvt_pk_bf16_f32 v28, v132, v133
	v_cvt_pk_bf16_f32 v29, v134, v135
	v_cvt_pk_bf16_f32 v30, v128, v129
	v_cvt_pk_bf16_f32 v31, v130, v131
	global_store_dwordx4 v[160:161], v[24:27], off
	global_store_dwordx4 v[160:161], v[28:31], off offset:256
	s_and_b64 vcc, exec, s[20:21]
	s_cbranch_vccz .Lio_skip_0
	v_pk_mul_f32 v[32:33], v[140:141], v[140:141]
	v_pk_fma_f32 v[32:33], v[142:143], v[142:143], v[32:33]
	v_pk_fma_f32 v[32:33], v[136:137], v[136:137], v[32:33]
	v_pk_fma_f32 v[32:33], v[138:139], v[138:139], v[32:33]
	v_pk_fma_f32 v[32:33], v[132:133], v[132:133], v[32:33]
	v_pk_fma_f32 v[32:33], v[134:135], v[134:135], v[32:33]
	v_pk_fma_f32 v[32:33], v[128:129], v[128:129], v[32:33]
	v_pk_fma_f32 v[32:33], v[130:131], v[130:131], v[32:33]
	s_nop 0
	v_add_f32_e32 v32, v32, v33
	v_mov_b32_e32 v33, v32
	s_nop 1
	v_permlane16_swap_b32_e32 v32, v33
	v_add_f32_e32 v32, v32, v33
	v_mov_b32_e32 v33, v32
	s_nop 1
	v_permlane32_swap_b32_e32 v32, v33
	s_and_saveexec_b64 vcc, s[6:7]
	v_add_f32_e32 v32, v32, v33
	global_atomic_add_f32 v[156:157], v32, off
	s_mov_b64 exec, vcc

.Lie_done_b:
.LBB0_354:
	s_ashr_i32 s31, s30, 31
	v_cmp_lt_i64_e32 vcc, s[8:9], v[170:171]
	s_lshl_b64 s[8:9], s[30:31], 19
	s_add_u32 s34, s52, s8
	s_addc_u32 s35, s53, s9
	s_and_b64 s[8:9], vcc, exec
	s_cselect_b32 s1, s35, s7
	s_cselect_b32 s31, s34, s6
	s_ashr_i32 s29, s28, 31
	s_lshl_b64 s[8:9], s[28:29], 19
	s_add_u32 s36, s43, s8
	s_addc_u32 s37, s42, s9
	s_and_b64 s[8:9], vcc, exec
	s_cselect_b32 s29, s37, s3
	s_cselect_b32 s38, s36, s2
	s_add_u32 s6, s6, 0x40080
	s_addc_u32 s7, s7, 0
	s_add_u32 s39, s2, 0x100
	s_addc_u32 s40, s3, 0
	s_mov_b32 s41, -2
	s_add_u32 s2, s6, 0xfffc0080
	s_addc_u32 s3, s7, -1
	ds_read_b128 v[128:131], v208
	ds_read_b128 v[132:135], v208 offset:1024
	ds_read_b128 v[136:139], v208 offset:2048
	ds_read_b128 v[140:143], v208 offset:3072
	s_cmp_eq_u32 s41, 12
	s_cselect_b32 s9, s1, s3
	s_cselect_b32 s8, s31, s2
	s_cselect_b32 s3, s29, s40
	s_cselect_b32 s2, s38, s39
	ds_read_b128 v[144:147], v209
	ds_read_b128 v[148:151], v209 offset:1024
	ds_read_b128 v[152:155], v209 offset:2048
	ds_read_b128 v[156:159], v209 offset:3072
	ds_read_b128 v[180:183], v209 offset:4096
	ds_read_b128 v[184:187], v209 offset:5120
	ds_read_b128 v[188:191], v209 offset:6144
	ds_read_b128 v[192:195], v209 offset:7168
	s_waitcnt lgkmcnt(8)
	s_barrier
	s_waitcnt lgkmcnt(0)
	v_mfma_f32_16x16x32_bf16 v[124:127], v[128:131], v[144:147], 0
	v_mfma_f32_16x16x32_bf16 v[120:123], v[136:139], v[144:147], 0
	v_mfma_f32_16x16x32_bf16 v[116:119], v[128:131], v[152:155], 0
	v_mfma_f32_16x16x32_bf16 v[112:115], v[136:139], v[152:155], 0
	v_mfma_f32_16x16x32_bf16 v[100:103], v[128:131], v[180:183], 0
	v_mfma_f32_16x16x32_bf16 v[96:99], v[136:139], v[180:183], 0
	v_mfma_f32_16x16x32_bf16 v[84:87], v[128:131], v[188:191], 0
	v_mfma_f32_16x16x32_bf16 v[80:83], v[136:139], v[188:191], 0
	v_mfma_f32_16x16x32_bf16 v[124:127], v[132:135], v[148:151], v[124:127]
	v_mfma_f32_16x16x32_bf16 v[120:123], v[140:143], v[148:151], v[120:123]
	v_mfma_f32_16x16x32_bf16 v[116:119], v[132:135], v[156:159], v[116:119]
	v_mfma_f32_16x16x32_bf16 v[112:115], v[140:143], v[156:159], v[112:115]
	v_mfma_f32_16x16x32_bf16 v[100:103], v[132:135], v[184:187], v[100:103]
	v_mfma_f32_16x16x32_bf16 v[96:99], v[140:143], v[184:187], v[96:99]
	v_mfma_f32_16x16x32_bf16 v[84:87], v[132:135], v[192:195], v[84:87]
	v_mfma_f32_16x16x32_bf16 v[80:83], v[140:143], v[192:195], v[80:83]
	s_barrier
	s_add_i32 m0, s21, 0xc000
	ds_read_b128 v[196:199], v208 offset:16384
	ds_read_b128 v[200:203], v208 offset:17408
	ds_read_b128 v[210:213], v208 offset:18432
	global_load_lds_dwordx4 v164, s[6:7]
	s_add_i32 m0, s21, 0xe000
	ds_read_b128 v[214:217], v208 offset:19456
	global_load_lds_dwordx4 v166, s[6:7]
	s_add_u32 s98, s2, 0x80
	s_addc_u32 s99, s3, 0
	s_add_i32 m0, s54, 0x10000
	s_nop 0
	global_load_lds_dwordx4 v160, s[2:3]
	s_add_i32 m0, s54, 0x12000
	s_nop 0
	global_load_lds_dwordx4 v162, s[2:3]
	s_barrier
	s_waitcnt lgkmcnt(0)
	v_mfma_f32_16x16x32_bf16 v[108:111], v[196:199], v[144:147], 0
	v_mfma_f32_16x16x32_bf16 v[104:107], v[210:213], v[144:147], 0
	v_mfma_f32_16x16x32_bf16 v[92:95], v[196:199], v[152:155], 0
	v_mfma_f32_16x16x32_bf16 v[88:91], v[210:213], v[152:155], 0
	v_mfma_f32_16x16x32_bf16 v[76:79], v[196:199], v[180:183], 0
	v_mfma_f32_16x16x32_bf16 v[72:75], v[210:213], v[180:183], 0
	v_mfma_f32_16x16x32_bf16 v[68:71], v[196:199], v[188:191], 0
	v_mfma_f32_16x16x32_bf16 v[64:67], v[210:213], v[188:191], 0
	v_mfma_f32_16x16x32_bf16 v[108:111], v[200:203], v[148:151], v[108:111]
	v_mfma_f32_16x16x32_bf16 v[104:107], v[214:217], v[148:151], v[104:107]
	v_mfma_f32_16x16x32_bf16 v[92:95], v[200:203], v[156:159], v[92:95]
	v_mfma_f32_16x16x32_bf16 v[88:91], v[214:217], v[156:159], v[88:91]
	v_mfma_f32_16x16x32_bf16 v[76:79], v[200:203], v[184:187], v[76:79]
	v_mfma_f32_16x16x32_bf16 v[72:75], v[214:217], v[184:187], v[72:75]
	v_mfma_f32_16x16x32_bf16 v[68:71], v[200:203], v[192:195], v[68:71]
	v_mfma_f32_16x16x32_bf16 v[64:67], v[214:217], v[192:195], v[64:67]
	s_add_u32 s100, s8, 0x80
	s_addc_u32 s101, s9, 0
	s_barrier
	ds_read_b128 v[144:147], v209 offset:16384
	ds_read_b128 v[148:151], v209 offset:17408
	ds_read_b128 v[152:155], v209 offset:18432
	ds_read_b128 v[156:159], v209 offset:19456
	ds_read_b128 v[180:183], v209 offset:20480
	ds_read_b128 v[184:187], v209 offset:21504
	ds_read_b128 v[188:191], v209 offset:22528
	ds_read_b128 v[192:195], v209 offset:23552
	s_barrier
	s_waitcnt lgkmcnt(0)
	v_mfma_f32_16x16x32_bf16 v[60:63], v[128:131], v[144:147], 0
	v_mfma_f32_16x16x32_bf16 v[56:59], v[136:139], v[144:147], 0
	v_mfma_f32_16x16x32_bf16 v[52:55], v[128:131], v[152:155], 0
	v_mfma_f32_16x16x32_bf16 v[48:51], v[136:139], v[152:155], 0
	v_mfma_f32_16x16x32_bf16 v[36:39], v[128:131], v[180:183], 0
	v_mfma_f32_16x16x32_bf16 v[32:35], v[136:139], v[180:183], 0
	v_mfma_f32_16x16x32_bf16 v[20:23], v[128:131], v[188:191], 0
	v_mfma_f32_16x16x32_bf16 v[16:19], v[136:139], v[188:191], 0
	v_mfma_f32_16x16x32_bf16 v[60:63], v[132:135], v[148:151], v[60:63]
	v_mfma_f32_16x16x32_bf16 v[56:59], v[140:143], v[148:151], v[56:59]
	v_mfma_f32_16x16x32_bf16 v[52:55], v[132:135], v[156:159], v[52:55]
	v_mfma_f32_16x16x32_bf16 v[48:51], v[140:143], v[156:159], v[48:51]
	v_mfma_f32_16x16x32_bf16 v[36:39], v[132:135], v[184:187], v[36:39]
	v_mfma_f32_16x16x32_bf16 v[32:35], v[140:143], v[184:187], v[32:35]
	v_mfma_f32_16x16x32_bf16 v[20:23], v[132:135], v[192:195], v[20:23]
	v_mfma_f32_16x16x32_bf16 v[16:19], v[140:143], v[192:195], v[16:19]
	s_barrier
	s_mov_b32 m0, s21
	s_nop 0
	global_load_lds_dwordx4 v160, s[8:9]
	s_mov_b32 m0, s55
	s_nop 0
	global_load_lds_dwordx4 v162, s[8:9]
	s_add_i32 m0, s54, 0x14000
	s_add_u32 s64, s2, 0x40000
	s_addc_u32 s65, s3, 0
	global_load_lds_dwordx4 v160, s[64:65]
	s_add_i32 m0, s54, 0x16000
	s_add_u32 s8, s8, 0x40000
	s_addc_u32 s9, s9, 0
	global_load_lds_dwordx4 v162, s[64:65]
	s_waitcnt vmcnt(6)
	s_barrier
	v_mfma_f32_16x16x32_bf16 v[44:47], v[196:199], v[144:147], 0
	v_mfma_f32_16x16x32_bf16 v[40:43], v[210:213], v[144:147], 0
	v_mfma_f32_16x16x32_bf16 v[28:31], v[196:199], v[152:155], 0
	v_mfma_f32_16x16x32_bf16 v[24:27], v[210:213], v[152:155], 0
	v_mfma_f32_16x16x32_bf16 v[12:15], v[196:199], v[180:183], 0
	v_mfma_f32_16x16x32_bf16 v[8:11], v[210:213], v[180:183], 0
	v_mfma_f32_16x16x32_bf16 v[4:7], v[196:199], v[188:191], 0
	v_mfma_f32_16x16x32_bf16 v[0:3], v[210:213], v[188:191], 0
	v_mfma_f32_16x16x32_bf16 v[44:47], v[200:203], v[148:151], v[44:47]
	v_mfma_f32_16x16x32_bf16 v[40:43], v[214:217], v[148:151], v[40:43]
	v_mfma_f32_16x16x32_bf16 v[28:31], v[200:203], v[156:159], v[28:31]
	v_mfma_f32_16x16x32_bf16 v[24:27], v[214:217], v[156:159], v[24:27]
	v_mfma_f32_16x16x32_bf16 v[12:15], v[200:203], v[184:187], v[12:15]
	v_mfma_f32_16x16x32_bf16 v[8:11], v[214:217], v[184:187], v[8:11]
	v_mfma_f32_16x16x32_bf16 v[4:7], v[200:203], v[192:195], v[4:7]
	v_mfma_f32_16x16x32_bf16 v[0:3], v[214:217], v[192:195], v[0:3]
	s_barrier
	ds_read_b128 v[128:131], v208 offset:32768
	ds_read_b128 v[132:135], v208 offset:33792
	ds_read_b128 v[136:139], v208 offset:34816
	ds_read_b128 v[140:143], v208 offset:35840
	ds_read_b128 v[144:147], v209 offset:32768
	ds_read_b128 v[148:151], v209 offset:33792
	ds_read_b128 v[152:155], v209 offset:34816
	ds_read_b128 v[156:159], v209 offset:35840
	ds_read_b128 v[180:183], v209 offset:36864
	ds_read_b128 v[184:187], v209 offset:37888
	ds_read_b128 v[188:191], v209 offset:38912
	ds_read_b128 v[192:195], v209 offset:39936
	s_waitcnt lgkmcnt(8)
	s_barrier
	s_waitcnt lgkmcnt(0)
	v_mfma_f32_16x16x32_bf16 v[124:127], v[128:131], v[144:147], v[124:127]
	v_mfma_f32_16x16x32_bf16 v[120:123], v[136:139], v[144:147], v[120:123]
	v_mfma_f32_16x16x32_bf16 v[116:119], v[128:131], v[152:155], v[116:119]
	v_mfma_f32_16x16x32_bf16 v[112:115], v[136:139], v[152:155], v[112:115]
	v_mfma_f32_16x16x32_bf16 v[100:103], v[128:131], v[180:183], v[100:103]
	v_mfma_f32_16x16x32_bf16 v[96:99], v[136:139], v[180:183], v[96:99]
	v_mfma_f32_16x16x32_bf16 v[84:87], v[128:131], v[188:191], v[84:87]
	v_mfma_f32_16x16x32_bf16 v[80:83], v[136:139], v[188:191], v[80:83]
	v_mfma_f32_16x16x32_bf16 v[124:127], v[132:135], v[148:151], v[124:127]
	v_mfma_f32_16x16x32_bf16 v[120:123], v[140:143], v[148:151], v[120:123]
	v_mfma_f32_16x16x32_bf16 v[116:119], v[132:135], v[156:159], v[116:119]
	v_mfma_f32_16x16x32_bf16 v[112:115], v[140:143], v[156:159], v[112:115]
	v_mfma_f32_16x16x32_bf16 v[100:103], v[132:135], v[184:187], v[100:103]
	v_mfma_f32_16x16x32_bf16 v[96:99], v[140:143], v[184:187], v[96:99]
	v_mfma_f32_16x16x32_bf16 v[84:87], v[132:135], v[192:195], v[84:87]
	v_mfma_f32_16x16x32_bf16 v[80:83], v[140:143], v[192:195], v[80:83]
	s_barrier
	s_mov_b32 m0, s56
	ds_read_b128 v[196:199], v208 offset:49152
	ds_read_b128 v[200:203], v208 offset:50176
	ds_read_b128 v[210:213], v208 offset:51200
	global_load_lds_dwordx4 v160, s[8:9]
	s_mov_b32 m0, s57
	ds_read_b128 v[214:217], v208 offset:52224
	global_load_lds_dwordx4 v162, s[8:9]
	s_add_i32 m0, s54, 0x18000
	s_nop 0
	global_load_lds_dwordx4 v160, s[98:99]
	s_add_i32 m0, s54, 0x1a000
	s_nop 0
	global_load_lds_dwordx4 v162, s[98:99]
	s_barrier
	s_waitcnt lgkmcnt(0)
	v_mfma_f32_16x16x32_bf16 v[108:111], v[196:199], v[144:147], v[108:111]
	v_mfma_f32_16x16x32_bf16 v[104:107], v[210:213], v[144:147], v[104:107]
	v_mfma_f32_16x16x32_bf16 v[92:95], v[196:199], v[152:155], v[92:95]
	v_mfma_f32_16x16x32_bf16 v[88:91], v[210:213], v[152:155], v[88:91]
	v_mfma_f32_16x16x32_bf16 v[76:79], v[196:199], v[180:183], v[76:79]
	v_mfma_f32_16x16x32_bf16 v[72:75], v[210:213], v[180:183], v[72:75]
	v_mfma_f32_16x16x32_bf16 v[68:71], v[196:199], v[188:191], v[68:71]
	v_mfma_f32_16x16x32_bf16 v[64:67], v[210:213], v[188:191], v[64:67]
	v_mfma_f32_16x16x32_bf16 v[108:111], v[200:203], v[148:151], v[108:111]
	v_mfma_f32_16x16x32_bf16 v[104:107], v[214:217], v[148:151], v[104:107]
	v_mfma_f32_16x16x32_bf16 v[92:95], v[200:203], v[156:159], v[92:95]
	v_mfma_f32_16x16x32_bf16 v[88:91], v[214:217], v[156:159], v[88:91]
	v_mfma_f32_16x16x32_bf16 v[76:79], v[200:203], v[184:187], v[76:79]
	v_mfma_f32_16x16x32_bf16 v[72:75], v[214:217], v[184:187], v[72:75]
	v_mfma_f32_16x16x32_bf16 v[68:71], v[200:203], v[192:195], v[68:71]
	v_mfma_f32_16x16x32_bf16 v[64:67], v[214:217], v[192:195], v[64:67]
	s_barrier
	ds_read_b128 v[144:147], v209 offset:49152
	ds_read_b128 v[148:151], v209 offset:50176
	ds_read_b128 v[152:155], v209 offset:51200
	ds_read_b128 v[156:159], v209 offset:52224
	ds_read_b128 v[180:183], v209 offset:53248
	ds_read_b128 v[184:187], v209 offset:54272
	ds_read_b128 v[188:191], v209 offset:55296
	ds_read_b128 v[192:195], v209 offset:56320
	s_barrier
	s_waitcnt lgkmcnt(0)
	v_mfma_f32_16x16x32_bf16 v[60:63], v[128:131], v[144:147], v[60:63]
	v_mfma_f32_16x16x32_bf16 v[56:59], v[136:139], v[144:147], v[56:59]
	v_mfma_f32_16x16x32_bf16 v[52:55], v[128:131], v[152:155], v[52:55]
	v_mfma_f32_16x16x32_bf16 v[48:51], v[136:139], v[152:155], v[48:51]
	v_mfma_f32_16x16x32_bf16 v[36:39], v[128:131], v[180:183], v[36:39]
	v_mfma_f32_16x16x32_bf16 v[32:35], v[136:139], v[180:183], v[32:35]
	v_mfma_f32_16x16x32_bf16 v[20:23], v[128:131], v[188:191], v[20:23]
	v_mfma_f32_16x16x32_bf16 v[16:19], v[136:139], v[188:191], v[16:19]
	v_mfma_f32_16x16x32_bf16 v[60:63], v[132:135], v[148:151], v[60:63]
	v_mfma_f32_16x16x32_bf16 v[56:59], v[140:143], v[148:151], v[56:59]
	v_mfma_f32_16x16x32_bf16 v[52:55], v[132:135], v[156:159], v[52:55]
	v_mfma_f32_16x16x32_bf16 v[48:51], v[140:143], v[156:159], v[48:51]
	v_mfma_f32_16x16x32_bf16 v[36:39], v[132:135], v[184:187], v[36:39]
	v_mfma_f32_16x16x32_bf16 v[32:35], v[140:143], v[184:187], v[32:35]
	v_mfma_f32_16x16x32_bf16 v[20:23], v[132:135], v[192:195], v[20:23]
	v_mfma_f32_16x16x32_bf16 v[16:19], v[140:143], v[192:195], v[16:19]
	s_barrier
	s_mov_b32 m0, s60
	s_nop 0
	global_load_lds_dwordx4 v160, s[100:101]
	s_mov_b32 m0, s61
	s_nop 0
	global_load_lds_dwordx4 v162, s[100:101]
	s_add_i32 m0, s54, 0x1c000
	s_add_u32 s2, s2, 0x40080
	s_addc_u32 s3, s3, 0
	global_load_lds_dwordx4 v160, s[2:3]
	s_add_i32 m0, s54, 0x1e000
	s_add_i32 s41, s41, 2
	global_load_lds_dwordx4 v162, s[2:3]
	s_waitcnt vmcnt(6)
	s_barrier
	v_mfma_f32_16x16x32_bf16 v[44:47], v[196:199], v[144:147], v[44:47]
	v_mfma_f32_16x16x32_bf16 v[40:43], v[210:213], v[144:147], v[40:43]
	v_mfma_f32_16x16x32_bf16 v[28:31], v[196:199], v[152:155], v[28:31]
	v_mfma_f32_16x16x32_bf16 v[24:27], v[210:213], v[152:155], v[24:27]
	v_mfma_f32_16x16x32_bf16 v[12:15], v[196:199], v[180:183], v[12:15]
	v_mfma_f32_16x16x32_bf16 v[8:11], v[210:213], v[180:183], v[8:11]
	v_mfma_f32_16x16x32_bf16 v[4:7], v[196:199], v[188:191], v[4:7]
	v_mfma_f32_16x16x32_bf16 v[0:3], v[210:213], v[188:191], v[0:3]
	v_mfma_f32_16x16x32_bf16 v[44:47], v[200:203], v[148:151], v[44:47]
	v_mfma_f32_16x16x32_bf16 v[40:43], v[214:217], v[148:151], v[40:43]
	v_mfma_f32_16x16x32_bf16 v[28:31], v[200:203], v[156:159], v[28:31]
	v_mfma_f32_16x16x32_bf16 v[24:27], v[214:217], v[156:159], v[24:27]
	v_mfma_f32_16x16x32_bf16 v[12:15], v[200:203], v[184:187], v[12:15]
	v_mfma_f32_16x16x32_bf16 v[8:11], v[214:217], v[184:187], v[8:11]
	v_mfma_f32_16x16x32_bf16 v[4:7], v[200:203], v[192:195], v[4:7]
	v_mfma_f32_16x16x32_bf16 v[0:3], v[214:217], v[192:195], v[0:3]
	s_add_u32 s6, s6, 0x100
	s_addc_u32 s7, s7, 0
	s_add_u32 s39, s39, 0x100
	s_addc_u32 s40, s40, 0
	s_cmp_gt_u32 s41, 13
	s_barrier
.LBB0_355:
	s_add_u32 s2, s6, 0xfffc0080
	s_addc_u32 s3, s7, -1
	ds_read_b128 v[128:131], v208
	ds_read_b128 v[132:135], v208 offset:1024
	ds_read_b128 v[136:139], v208 offset:2048
	ds_read_b128 v[140:143], v208 offset:3072
	s_cmp_eq_u32 s41, 12
	s_cselect_b32 s9, s1, s3
	s_cselect_b32 s8, s31, s2
	s_cselect_b32 s3, s29, s40
	s_cselect_b32 s2, s38, s39
	ds_read_b128 v[144:147], v209
	ds_read_b128 v[148:151], v209 offset:1024
	ds_read_b128 v[152:155], v209 offset:2048
	ds_read_b128 v[156:159], v209 offset:3072
	ds_read_b128 v[180:183], v209 offset:4096
	ds_read_b128 v[184:187], v209 offset:5120
	ds_read_b128 v[188:191], v209 offset:6144
	ds_read_b128 v[192:195], v209 offset:7168
	s_waitcnt lgkmcnt(8)
	s_barrier
	s_waitcnt lgkmcnt(0)
	v_mfma_f32_16x16x32_bf16 v[124:127], v[128:131], v[144:147], v[124:127]
	v_mfma_f32_16x16x32_bf16 v[120:123], v[136:139], v[144:147], v[120:123]
	v_mfma_f32_16x16x32_bf16 v[116:119], v[128:131], v[152:155], v[116:119]
	v_mfma_f32_16x16x32_bf16 v[112:115], v[136:139], v[152:155], v[112:115]
	v_mfma_f32_16x16x32_bf16 v[100:103], v[128:131], v[180:183], v[100:103]
	v_mfma_f32_16x16x32_bf16 v[96:99], v[136:139], v[180:183], v[96:99]
	v_mfma_f32_16x16x32_bf16 v[84:87], v[128:131], v[188:191], v[84:87]
	v_mfma_f32_16x16x32_bf16 v[80:83], v[136:139], v[188:191], v[80:83]
	v_mfma_f32_16x16x32_bf16 v[124:127], v[132:135], v[148:151], v[124:127]
	v_mfma_f32_16x16x32_bf16 v[120:123], v[140:143], v[148:151], v[120:123]
	v_mfma_f32_16x16x32_bf16 v[116:119], v[132:135], v[156:159], v[116:119]
	v_mfma_f32_16x16x32_bf16 v[112:115], v[140:143], v[156:159], v[112:115]
	v_mfma_f32_16x16x32_bf16 v[100:103], v[132:135], v[184:187], v[100:103]
	v_mfma_f32_16x16x32_bf16 v[96:99], v[140:143], v[184:187], v[96:99]
	v_mfma_f32_16x16x32_bf16 v[84:87], v[132:135], v[192:195], v[84:87]
	v_mfma_f32_16x16x32_bf16 v[80:83], v[140:143], v[192:195], v[80:83]
	s_barrier
	s_add_i32 m0, s21, 0xc000
	ds_read_b128 v[196:199], v208 offset:16384
	ds_read_b128 v[200:203], v208 offset:17408
	ds_read_b128 v[210:213], v208 offset:18432
	global_load_lds_dwordx4 v164, s[6:7]
	s_add_i32 m0, s21, 0xe000
	ds_read_b128 v[214:217], v208 offset:19456
	global_load_lds_dwordx4 v166, s[6:7]
	s_add_u32 s98, s2, 0x80
	s_addc_u32 s99, s3, 0
	s_add_i32 m0, s54, 0x10000
	s_nop 0
	global_load_lds_dwordx4 v160, s[2:3]
	s_add_i32 m0, s54, 0x12000
	s_nop 0
	global_load_lds_dwordx4 v162, s[2:3]
	s_barrier
	s_waitcnt lgkmcnt(0)
	v_mfma_f32_16x16x32_bf16 v[108:111], v[196:199], v[144:147], v[108:111]
	v_mfma_f32_16x16x32_bf16 v[104:107], v[210:213], v[144:147], v[104:107]
	v_mfma_f32_16x16x32_bf16 v[92:95], v[196:199], v[152:155], v[92:95]
	v_mfma_f32_16x16x32_bf16 v[88:91], v[210:213], v[152:155], v[88:91]
	v_mfma_f32_16x16x32_bf16 v[76:79], v[196:199], v[180:183], v[76:79]
	v_mfma_f32_16x16x32_bf16 v[72:75], v[210:213], v[180:183], v[72:75]
	v_mfma_f32_16x16x32_bf16 v[68:71], v[196:199], v[188:191], v[68:71]
	v_mfma_f32_16x16x32_bf16 v[64:67], v[210:213], v[188:191], v[64:67]
	v_mfma_f32_16x16x32_bf16 v[108:111], v[200:203], v[148:151], v[108:111]
	v_mfma_f32_16x16x32_bf16 v[104:107], v[214:217], v[148:151], v[104:107]
	v_mfma_f32_16x16x32_bf16 v[92:95], v[200:203], v[156:159], v[92:95]
	v_mfma_f32_16x16x32_bf16 v[88:91], v[214:217], v[156:159], v[88:91]
	v_mfma_f32_16x16x32_bf16 v[76:79], v[200:203], v[184:187], v[76:79]
	v_mfma_f32_16x16x32_bf16 v[72:75], v[214:217], v[184:187], v[72:75]
	v_mfma_f32_16x16x32_bf16 v[68:71], v[200:203], v[192:195], v[68:71]
	v_mfma_f32_16x16x32_bf16 v[64:67], v[214:217], v[192:195], v[64:67]
	s_add_u32 s100, s8, 0x80
	s_addc_u32 s101, s9, 0
	s_barrier
	ds_read_b128 v[144:147], v209 offset:16384
	ds_read_b128 v[148:151], v209 offset:17408
	ds_read_b128 v[152:155], v209 offset:18432
	ds_read_b128 v[156:159], v209 offset:19456
	ds_read_b128 v[180:183], v209 offset:20480
	ds_read_b128 v[184:187], v209 offset:21504
	ds_read_b128 v[188:191], v209 offset:22528
	ds_read_b128 v[192:195], v209 offset:23552
	s_barrier
	s_waitcnt lgkmcnt(0)
	v_mfma_f32_16x16x32_bf16 v[60:63], v[128:131], v[144:147], v[60:63]
	v_mfma_f32_16x16x32_bf16 v[56:59], v[136:139], v[144:147], v[56:59]
	v_mfma_f32_16x16x32_bf16 v[52:55], v[128:131], v[152:155], v[52:55]
	v_mfma_f32_16x16x32_bf16 v[48:51], v[136:139], v[152:155], v[48:51]
	v_mfma_f32_16x16x32_bf16 v[36:39], v[128:131], v[180:183], v[36:39]
	v_mfma_f32_16x16x32_bf16 v[32:35], v[136:139], v[180:183], v[32:35]
	v_mfma_f32_16x16x32_bf16 v[20:23], v[128:131], v[188:191], v[20:23]
	v_mfma_f32_16x16x32_bf16 v[16:19], v[136:139], v[188:191], v[16:19]
	v_mfma_f32_16x16x32_bf16 v[60:63], v[132:135], v[148:151], v[60:63]
	v_mfma_f32_16x16x32_bf16 v[56:59], v[140:143], v[148:151], v[56:59]
	v_mfma_f32_16x16x32_bf16 v[52:55], v[132:135], v[156:159], v[52:55]
	v_mfma_f32_16x16x32_bf16 v[48:51], v[140:143], v[156:159], v[48:51]
	v_mfma_f32_16x16x32_bf16 v[36:39], v[132:135], v[184:187], v[36:39]
	v_mfma_f32_16x16x32_bf16 v[32:35], v[140:143], v[184:187], v[32:35]
	v_mfma_f32_16x16x32_bf16 v[20:23], v[132:135], v[192:195], v[20:23]
	v_mfma_f32_16x16x32_bf16 v[16:19], v[140:143], v[192:195], v[16:19]
	s_barrier
	s_mov_b32 m0, s21
	s_nop 0
	global_load_lds_dwordx4 v160, s[8:9]
	s_mov_b32 m0, s55
	s_nop 0
	global_load_lds_dwordx4 v162, s[8:9]
	s_add_i32 m0, s54, 0x14000
	s_add_u32 s64, s2, 0x40000
	s_addc_u32 s65, s3, 0
	global_load_lds_dwordx4 v160, s[64:65]
	s_add_i32 m0, s54, 0x16000
	s_add_u32 s8, s8, 0x40000
	s_addc_u32 s9, s9, 0
	global_load_lds_dwordx4 v162, s[64:65]
	s_waitcnt vmcnt(6)
	s_barrier
	v_mfma_f32_16x16x32_bf16 v[44:47], v[196:199], v[144:147], v[44:47]
	v_mfma_f32_16x16x32_bf16 v[40:43], v[210:213], v[144:147], v[40:43]
	v_mfma_f32_16x16x32_bf16 v[28:31], v[196:199], v[152:155], v[28:31]
	v_mfma_f32_16x16x32_bf16 v[24:27], v[210:213], v[152:155], v[24:27]
	v_mfma_f32_16x16x32_bf16 v[12:15], v[196:199], v[180:183], v[12:15]
	v_mfma_f32_16x16x32_bf16 v[8:11], v[210:213], v[180:183], v[8:11]
	v_mfma_f32_16x16x32_bf16 v[4:7], v[196:199], v[188:191], v[4:7]
	v_mfma_f32_16x16x32_bf16 v[0:3], v[210:213], v[188:191], v[0:3]
	v_mfma_f32_16x16x32_bf16 v[44:47], v[200:203], v[148:151], v[44:47]
	v_mfma_f32_16x16x32_bf16 v[40:43], v[214:217], v[148:151], v[40:43]
	v_mfma_f32_16x16x32_bf16 v[28:31], v[200:203], v[156:159], v[28:31]
	v_mfma_f32_16x16x32_bf16 v[24:27], v[214:217], v[156:159], v[24:27]
	v_mfma_f32_16x16x32_bf16 v[12:15], v[200:203], v[184:187], v[12:15]
	v_mfma_f32_16x16x32_bf16 v[8:11], v[214:217], v[184:187], v[8:11]
	v_mfma_f32_16x16x32_bf16 v[4:7], v[200:203], v[192:195], v[4:7]
	v_mfma_f32_16x16x32_bf16 v[0:3], v[214:217], v[192:195], v[0:3]
	s_barrier
	ds_read_b128 v[128:131], v208 offset:32768
	ds_read_b128 v[132:135], v208 offset:33792
	ds_read_b128 v[136:139], v208 offset:34816
	ds_read_b128 v[140:143], v208 offset:35840
	ds_read_b128 v[144:147], v209 offset:32768
	ds_read_b128 v[148:151], v209 offset:33792
	ds_read_b128 v[152:155], v209 offset:34816
	ds_read_b128 v[156:159], v209 offset:35840
	ds_read_b128 v[180:183], v209 offset:36864
	ds_read_b128 v[184:187], v209 offset:37888
	ds_read_b128 v[188:191], v209 offset:38912
	ds_read_b128 v[192:195], v209 offset:39936
	s_waitcnt lgkmcnt(8)
	s_barrier
	s_waitcnt lgkmcnt(0)
	v_mfma_f32_16x16x32_bf16 v[124:127], v[128:131], v[144:147], v[124:127]
	v_mfma_f32_16x16x32_bf16 v[120:123], v[136:139], v[144:147], v[120:123]
	v_mfma_f32_16x16x32_bf16 v[116:119], v[128:131], v[152:155], v[116:119]
	v_mfma_f32_16x16x32_bf16 v[112:115], v[136:139], v[152:155], v[112:115]
	v_mfma_f32_16x16x32_bf16 v[100:103], v[128:131], v[180:183], v[100:103]
	v_mfma_f32_16x16x32_bf16 v[96:99], v[136:139], v[180:183], v[96:99]
	v_mfma_f32_16x16x32_bf16 v[84:87], v[128:131], v[188:191], v[84:87]
	v_mfma_f32_16x16x32_bf16 v[80:83], v[136:139], v[188:191], v[80:83]
	v_mfma_f32_16x16x32_bf16 v[124:127], v[132:135], v[148:151], v[124:127]
	v_mfma_f32_16x16x32_bf16 v[120:123], v[140:143], v[148:151], v[120:123]
	v_mfma_f32_16x16x32_bf16 v[116:119], v[132:135], v[156:159], v[116:119]
	v_mfma_f32_16x16x32_bf16 v[112:115], v[140:143], v[156:159], v[112:115]
	v_mfma_f32_16x16x32_bf16 v[100:103], v[132:135], v[184:187], v[100:103]
	v_mfma_f32_16x16x32_bf16 v[96:99], v[140:143], v[184:187], v[96:99]
	v_mfma_f32_16x16x32_bf16 v[84:87], v[132:135], v[192:195], v[84:87]
	v_mfma_f32_16x16x32_bf16 v[80:83], v[140:143], v[192:195], v[80:83]
	s_barrier
	s_mov_b32 m0, s56
	ds_read_b128 v[196:199], v208 offset:49152
	ds_read_b128 v[200:203], v208 offset:50176
	ds_read_b128 v[210:213], v208 offset:51200
	global_load_lds_dwordx4 v160, s[8:9]
	s_mov_b32 m0, s57
	ds_read_b128 v[214:217], v208 offset:52224
	global_load_lds_dwordx4 v162, s[8:9]
	s_add_i32 m0, s54, 0x18000
	s_nop 0
	global_load_lds_dwordx4 v160, s[98:99]
	s_add_i32 m0, s54, 0x1a000
	s_nop 0
	global_load_lds_dwordx4 v162, s[98:99]
	s_barrier
	s_waitcnt lgkmcnt(0)
	v_mfma_f32_16x16x32_bf16 v[108:111], v[196:199], v[144:147], v[108:111]
	v_mfma_f32_16x16x32_bf16 v[104:107], v[210:213], v[144:147], v[104:107]
	v_mfma_f32_16x16x32_bf16 v[92:95], v[196:199], v[152:155], v[92:95]
	v_mfma_f32_16x16x32_bf16 v[88:91], v[210:213], v[152:155], v[88:91]
	v_mfma_f32_16x16x32_bf16 v[76:79], v[196:199], v[180:183], v[76:79]
	v_mfma_f32_16x16x32_bf16 v[72:75], v[210:213], v[180:183], v[72:75]
	v_mfma_f32_16x16x32_bf16 v[68:71], v[196:199], v[188:191], v[68:71]
	v_mfma_f32_16x16x32_bf16 v[64:67], v[210:213], v[188:191], v[64:67]
	v_mfma_f32_16x16x32_bf16 v[108:111], v[200:203], v[148:151], v[108:111]
	v_mfma_f32_16x16x32_bf16 v[104:107], v[214:217], v[148:151], v[104:107]
	v_mfma_f32_16x16x32_bf16 v[92:95], v[200:203], v[156:159], v[92:95]
	v_mfma_f32_16x16x32_bf16 v[88:91], v[214:217], v[156:159], v[88:91]
	v_mfma_f32_16x16x32_bf16 v[76:79], v[200:203], v[184:187], v[76:79]
	v_mfma_f32_16x16x32_bf16 v[72:75], v[214:217], v[184:187], v[72:75]
	v_mfma_f32_16x16x32_bf16 v[68:71], v[200:203], v[192:195], v[68:71]
	v_mfma_f32_16x16x32_bf16 v[64:67], v[214:217], v[192:195], v[64:67]
	s_barrier
	ds_read_b128 v[144:147], v209 offset:49152
	ds_read_b128 v[148:151], v209 offset:50176
	ds_read_b128 v[152:155], v209 offset:51200
	ds_read_b128 v[156:159], v209 offset:52224
	ds_read_b128 v[180:183], v209 offset:53248
	ds_read_b128 v[184:187], v209 offset:54272
	ds_read_b128 v[188:191], v209 offset:55296
	ds_read_b128 v[192:195], v209 offset:56320
	s_barrier
	s_waitcnt lgkmcnt(0)
	v_mfma_f32_16x16x32_bf16 v[60:63], v[128:131], v[144:147], v[60:63]
	v_mfma_f32_16x16x32_bf16 v[56:59], v[136:139], v[144:147], v[56:59]
	v_mfma_f32_16x16x32_bf16 v[52:55], v[128:131], v[152:155], v[52:55]
	v_mfma_f32_16x16x32_bf16 v[48:51], v[136:139], v[152:155], v[48:51]
	v_mfma_f32_16x16x32_bf16 v[36:39], v[128:131], v[180:183], v[36:39]
	v_mfma_f32_16x16x32_bf16 v[32:35], v[136:139], v[180:183], v[32:35]
	v_mfma_f32_16x16x32_bf16 v[20:23], v[128:131], v[188:191], v[20:23]
	v_mfma_f32_16x16x32_bf16 v[16:19], v[136:139], v[188:191], v[16:19]
	v_mfma_f32_16x16x32_bf16 v[60:63], v[132:135], v[148:151], v[60:63]
	v_mfma_f32_16x16x32_bf16 v[56:59], v[140:143], v[148:151], v[56:59]
	v_mfma_f32_16x16x32_bf16 v[52:55], v[132:135], v[156:159], v[52:55]
	v_mfma_f32_16x16x32_bf16 v[48:51], v[140:143], v[156:159], v[48:51]
	v_mfma_f32_16x16x32_bf16 v[36:39], v[132:135], v[184:187], v[36:39]
	v_mfma_f32_16x16x32_bf16 v[32:35], v[140:143], v[184:187], v[32:35]
	v_mfma_f32_16x16x32_bf16 v[20:23], v[132:135], v[192:195], v[20:23]
	v_mfma_f32_16x16x32_bf16 v[16:19], v[140:143], v[192:195], v[16:19]
	s_barrier
	s_mov_b32 m0, s60
	s_nop 0
	global_load_lds_dwordx4 v160, s[100:101]
	s_mov_b32 m0, s61
	s_nop 0
	global_load_lds_dwordx4 v162, s[100:101]
	s_add_i32 m0, s54, 0x1c000
	s_add_u32 s2, s2, 0x40080
	s_addc_u32 s3, s3, 0
	global_load_lds_dwordx4 v160, s[2:3]
	s_add_i32 m0, s54, 0x1e000
	s_add_i32 s41, s41, 2
	global_load_lds_dwordx4 v162, s[2:3]
	s_waitcnt vmcnt(6)
	s_barrier
	v_mfma_f32_16x16x32_bf16 v[44:47], v[196:199], v[144:147], v[44:47]
	v_mfma_f32_16x16x32_bf16 v[40:43], v[210:213], v[144:147], v[40:43]
	v_mfma_f32_16x16x32_bf16 v[28:31], v[196:199], v[152:155], v[28:31]
	v_mfma_f32_16x16x32_bf16 v[24:27], v[210:213], v[152:155], v[24:27]
	v_mfma_f32_16x16x32_bf16 v[12:15], v[196:199], v[180:183], v[12:15]
	v_mfma_f32_16x16x32_bf16 v[8:11], v[210:213], v[180:183], v[8:11]
	v_mfma_f32_16x16x32_bf16 v[4:7], v[196:199], v[188:191], v[4:7]
	v_mfma_f32_16x16x32_bf16 v[0:3], v[210:213], v[188:191], v[0:3]
	v_mfma_f32_16x16x32_bf16 v[44:47], v[200:203], v[148:151], v[44:47]
	v_mfma_f32_16x16x32_bf16 v[40:43], v[214:217], v[148:151], v[40:43]
	v_mfma_f32_16x16x32_bf16 v[28:31], v[200:203], v[156:159], v[28:31]
	v_mfma_f32_16x16x32_bf16 v[24:27], v[214:217], v[156:159], v[24:27]
	v_mfma_f32_16x16x32_bf16 v[12:15], v[200:203], v[184:187], v[12:15]
	v_mfma_f32_16x16x32_bf16 v[8:11], v[214:217], v[184:187], v[8:11]
	v_mfma_f32_16x16x32_bf16 v[4:7], v[200:203], v[192:195], v[4:7]
	v_mfma_f32_16x16x32_bf16 v[0:3], v[214:217], v[192:195], v[0:3]
	s_add_u32 s6, s6, 0x100
	s_addc_u32 s7, s7, 0
	s_add_u32 s39, s39, 0x100
	s_addc_u32 s40, s40, 0
	s_cmp_gt_u32 s41, 13
	s_barrier
	s_cbranch_scc0 .LBB0_355
	s_lshl_b32 s1, s0, 8
	v_mov_b32_e32 v211, v206
	v_mov_b32_e32 v210, v207
	s_add_i32 s1, s1, s59
	s_cmp_lt_i32 s20, 3
	v_add_u32_e32 v180, s1, v211
	s_mov_b64 s[2:3], -1
	s_cbranch_scc0 .LBB0_490
	s_cmp_gt_i32 s0, 15
	s_cselect_b64 s[2:3], -1, 0
	s_cmp_lt_i32 s0, 16
	s_cselect_b64 s[38:39], -1, 0
	s_cmp_eq_u32 s20, 2
	s_cselect_b64 s[8:9], -1, 0
	s_cmp_lg_u32 s20, 2
	s_cselect_b64 s[0:1], -1, 0
	s_and_b64 s[40:41], s[8:9], s[22:23]
	v_lshlrev_b32_e32 v182, 2, v210
	s_mov_b64 s[6:7], -1
	s_and_b64 vcc, exec, s[40:41]
	v_ashrrev_i32_e32 v183, 31, v182
	s_cbranch_vccnz .LBB0_447
	s_and_b64 s[6:7], s[8:9], exec
	s_cselect_b32 s6, s46, s44
	s_cselect_b32 s7, s47, s45
	v_mov_b32_e32 v128, s7
	v_mov_b32_e32 v129, s6
	v_lshl_add_u64 v[128:129], v[182:183], 2, v[128:129]
	global_load_dwordx4 v[140:143], v[128:129], off
	global_load_dwordx4 v[136:139], v[128:129], off offset:64
	global_load_dwordx4 v[132:135], v[128:129], off offset:128
	s_nop 0
	global_load_dwordx4 v[128:131], v[128:129], off offset:192
	v_mul_f32_e32 v144, v125, v125
	v_mul_f32_e32 v145, v127, v127
	v_fmac_f32_e32 v144, v124, v124
	v_fmac_f32_e32 v145, v126, v126
	v_add_f32_e32 v144, v144, v145
	v_mul_f32_e32 v145, v121, v121
	v_mul_f32_e32 v146, v123, v123
	v_fmac_f32_e32 v145, v120, v120
	v_fmac_f32_e32 v146, v122, v122
	v_add_f32_e32 v145, v145, v146
	v_add_f32_e32 v144, v144, v145
	v_mul_f32_e32 v145, v109, v109
	v_mul_f32_e32 v146, v111, v111
	v_fmac_f32_e32 v145, v108, v108
	v_fmac_f32_e32 v146, v110, v110
	v_add_f32_e32 v145, v145, v146
	v_add_f32_e32 v144, v144, v145
	v_mul_f32_e32 v145, v105, v105
	v_mul_f32_e32 v146, v107, v107
	v_fmac_f32_e32 v145, v104, v104
	v_fmac_f32_e32 v146, v106, v106
	v_add_f32_e32 v145, v145, v146
	v_add_f32_e32 v144, v144, v145
	v_mov_b32_e32 v145, v144
	s_nop 1
	v_permlane16_swap_b32_e32 v144, v145
	v_add_f32_e32 v144, v144, v145
	v_mov_b32_e32 v145, v144
	s_nop 1
	v_permlane32_swap_b32_e32 v144, v145
	v_add_f32_e32 v144, v144, v145
	v_fmamk_f32 v144, v144, 0x3c800000, v225
	v_cmp_gt_f32_e32 vcc, s93, v144
	v_mul_f32_e32 v145, 0x4b800000, v144
	v_and_b32_e32 v202, 63, v211
	v_cndmask_b32_e32 v144, v144, v145, vcc
	v_rsq_f32_e32 v144, v144
	v_cndmask_b32_e64 v168, 0, 1, s[2:3]
	v_cmp_ne_u32_e64 s[6:7], 1, v168
	v_lshlrev_b32_e32 v186, 7, v202
	v_mul_f32_e32 v145, 0x45800000, v144
	v_cndmask_b32_e32 v152, v144, v145, vcc
	v_pk_mul_f32 v[144:145], v[124:125], v[152:153] op_sel_hi:[1,0]
	v_pk_mul_f32 v[146:147], v[126:127], v[152:153] op_sel_hi:[1,0]
	v_pk_mul_f32 v[148:149], v[108:109], v[152:153] op_sel_hi:[1,0]
	v_pk_mul_f32 v[150:151], v[110:111], v[152:153] op_sel_hi:[1,0]
	v_pk_mul_f32 v[184:185], v[104:105], v[152:153] op_sel_hi:[1,0]
	s_andn2_b64 vcc, exec, s[2:3]
	s_waitcnt vmcnt(0)
	v_pk_mul_f32 v[158:159], v[142:143], v[146:147]
	v_pk_mul_f32 v[156:157], v[140:141], v[144:145]
	v_pk_mul_f32 v[144:145], v[120:121], v[152:153] op_sel_hi:[1,0]
	v_pk_mul_f32 v[146:147], v[122:123], v[152:153] op_sel_hi:[1,0]
	v_pk_mul_f32 v[152:153], v[106:107], v[152:153] op_sel_hi:[1,0]
	v_pk_mul_f32 v[146:147], v[138:139], v[146:147]
	v_pk_mul_f32 v[144:145], v[136:137], v[144:145]
	v_pk_mul_f32 v[150:151], v[134:135], v[150:151]
	v_pk_mul_f32 v[148:149], v[132:133], v[148:149]
	v_pk_mul_f32 v[154:155], v[130:131], v[152:153]
	v_pk_mul_f32 v[152:153], v[128:129], v[184:185]
	v_lshl_add_u64 v[184:185], v[182:183], 3, s[18:19]
	s_cbranch_vccnz .LBB0_360
	v_lshlrev_b32_e32 v168, 1, v180
	v_and_b32_e32 v168, 0xf80, v168
	v_lshl_add_u64 v[188:189], v[184:185], 0, v[168:169]
	global_load_dwordx4 v[190:193], v[188:189], off offset:16
	global_load_dwordx4 v[194:197], v[188:189], off
	v_mov_b32_e32 v187, v169
	s_waitcnt vmcnt(0)
	v_mul_f32_e32 v198, v158, v190
	v_mov_b32_e32 v188, v194
	v_mov_b32_e32 v189, v196
	v_mov_b32_e32 v196, v195
	v_mul_f32_e32 v200, v146, v191
	v_mul_f32_e32 v204, v146, v190
	v_mul_f32_e32 v212, v158, v191
	v_mov_b32_e32 v146, v159
	v_mov_b32_e32 v158, v147
	v_pk_mul_f32 v[194:195], v[144:145], v[196:197]
	v_pk_mul_f32 v[144:145], v[144:145], v[188:189]
	v_pk_mul_f32 v[190:191], v[146:147], v[192:193]
	v_pk_mul_f32 v[146:147], v[158:159], v[192:193]
	v_lshl_add_u64 v[192:193], v[184:185], 0, v[186:187]
	v_mov_b32_e32 v199, v190
	v_mov_b32_e32 v201, v191
	v_pk_fma_f32 v[190:191], v[156:157], v[188:189], v[194:195] neg_lo:[0,0,1] neg_hi:[0,0,1]
	v_pk_fma_f32 v[144:145], v[156:157], v[196:197], v[144:145]
	global_load_dwordx4 v[156:159], v[192:193], off offset:16
	s_nop 0
	global_load_dwordx4 v[192:195], v[192:193], off
	v_pk_add_f32 v[188:189], v[198:199], v[200:201] neg_lo:[0,1] neg_hi:[0,1]
	v_mov_b32_e32 v213, v147
	v_mov_b32_e32 v205, v146
	v_pk_add_f32 v[146:147], v[212:213], v[204:205]
	s_waitcnt vmcnt(0)
	v_mul_f32_e32 v198, v150, v156
	v_mul_f32_e32 v200, v154, v157
	v_mul_f32_e32 v156, v154, v156
	v_mov_b32_e32 v154, v151
	v_mov_b32_e32 v197, v194
	v_mov_b32_e32 v194, v193
	v_mul_f32_e32 v204, v150, v157
	v_pk_mul_f32 v[212:213], v[154:155], v[158:159]
	v_mov_b32_e32 v150, v155
	v_mov_b32_e32 v196, v192
	v_pk_mul_f32 v[192:193], v[152:153], v[194:195]
	v_mov_b32_e32 v199, v212
	v_mov_b32_e32 v201, v213
	v_pk_mul_f32 v[150:151], v[150:151], v[158:159]
	v_pk_mul_f32 v[152:153], v[152:153], v[196:197]
	v_pk_fma_f32 v[192:193], v[148:149], v[196:197], v[192:193] neg_lo:[0,0,1] neg_hi:[0,0,1]
	v_pk_add_f32 v[196:197], v[198:199], v[200:201] neg_lo:[0,1] neg_hi:[0,1]
	v_mov_b32_e32 v205, v151
	v_mov_b32_e32 v157, v150
	v_pk_fma_f32 v[152:153], v[148:149], v[194:195], v[152:153]
	v_pk_add_f32 v[154:155], v[204:205], v[156:157]
	v_mov_b32_e32 v148, v192
	v_mov_b32_e32 v149, v193
	v_mov_b32_e32 v150, v196
	v_mov_b32_e32 v151, v197
	v_mov_b32_e32 v156, v190
	v_mov_b32_e32 v157, v191
	v_mov_b32_e32 v158, v188
	v_mov_b32_e32 v159, v189

.LBB0_677:
	s_ashr_i32 s23, s22, 31
	v_cmp_lt_i64_e32 vcc, s[24:25], v[174:175]
	s_lshl_b64 s[24:25], s[22:23], 19
	s_add_u32 s24, s36, s24
	s_addc_u32 s25, s37, s25
	s_and_b64 s[26:27], vcc, exec
	s_cselect_b32 s1, s25, s9
	s_cselect_b32 s7, s24, s8
	s_ashr_i32 s21, s20, 31
	s_lshl_b64 s[26:27], s[20:21], 19
	s_add_u32 s26, s38, s26
	s_addc_u32 s27, s39, s27
	s_and_b64 s[28:29], vcc, exec
	s_cselect_b32 s21, s27, s3
	s_cselect_b32 s23, s26, s2
	s_add_u32 s8, s8, 0x40080
	s_addc_u32 s9, s9, 0
	s_add_u32 s56, s2, 0x100
	s_addc_u32 s57, s3, 0
	s_mov_b32 s58, -2
	s_add_u32 s2, s8, 0xfffc0080
	s_addc_u32 s3, s9, -1
	ds_read_b128 v[48:51], v206
	ds_read_b128 v[52:55], v206 offset:1024
	ds_read_b128 v[60:63], v206 offset:2048
	ds_read_b128 v[68:71], v206 offset:3072
	s_cmp_eq_u32 s58, 12
	s_cselect_b32 s29, s1, s3
	s_cselect_b32 s28, s7, s2
	s_cselect_b32 s3, s21, s57
	s_cselect_b32 s2, s23, s56
	ds_read_b128 v[72:75], v207
	ds_read_b128 v[76:79], v207 offset:1024
	ds_read_b128 v[80:83], v207 offset:2048
	ds_read_b128 v[84:87], v207 offset:3072
	ds_read_b128 v[160:163], v207 offset:4096
	ds_read_b128 v[164:167], v207 offset:5120
	ds_read_b128 v[192:195], v207 offset:6144
	ds_read_b128 v[196:199], v207 offset:7168
	s_waitcnt lgkmcnt(8)
	s_barrier
	s_waitcnt lgkmcnt(0)
	v_mfma_f32_16x16x32_bf16 v[156:159], v[48:51], v[72:75], 0
	v_mfma_f32_16x16x32_bf16 v[152:155], v[60:63], v[72:75], 0
	v_mfma_f32_16x16x32_bf16 v[140:143], v[48:51], v[80:83], 0
	v_mfma_f32_16x16x32_bf16 v[136:139], v[60:63], v[80:83], 0
	v_mfma_f32_16x16x32_bf16 v[124:127], v[48:51], v[160:163], 0
	v_mfma_f32_16x16x32_bf16 v[120:123], v[60:63], v[160:163], 0
	v_mfma_f32_16x16x32_bf16 v[108:111], v[48:51], v[192:195], 0
	v_mfma_f32_16x16x32_bf16 v[104:107], v[60:63], v[192:195], 0
	v_mfma_f32_16x16x32_bf16 v[156:159], v[52:55], v[76:79], v[156:159]
	v_mfma_f32_16x16x32_bf16 v[152:155], v[68:71], v[76:79], v[152:155]
	v_mfma_f32_16x16x32_bf16 v[140:143], v[52:55], v[84:87], v[140:143]
	v_mfma_f32_16x16x32_bf16 v[136:139], v[68:71], v[84:87], v[136:139]
	v_mfma_f32_16x16x32_bf16 v[124:127], v[52:55], v[164:167], v[124:127]
	v_mfma_f32_16x16x32_bf16 v[120:123], v[68:71], v[164:167], v[120:123]
	v_mfma_f32_16x16x32_bf16 v[108:111], v[52:55], v[196:199], v[108:111]
	v_mfma_f32_16x16x32_bf16 v[104:107], v[68:71], v[196:199], v[104:107]
	s_barrier
	s_add_i32 m0, s41, 0xc000
	ds_read_b128 v[200:203], v206 offset:16384
	ds_read_b128 v[208:211], v206 offset:17408
	ds_read_b128 v[212:215], v206 offset:18432
	global_load_lds_dwordx4 v188, s[8:9]
	s_add_i32 m0, s41, 0xe000
	ds_read_b128 v[216:219], v206 offset:19456
	global_load_lds_dwordx4 v190, s[8:9]
	s_add_u32 s98, s2, 0x80
	s_addc_u32 s99, s3, 0
	s_add_i32 m0, s40, 0x10000
	s_nop 0
	global_load_lds_dwordx4 v182, s[2:3]
	s_add_i32 m0, s40, 0x12000
	s_nop 0
	global_load_lds_dwordx4 v186, s[2:3]
	s_barrier
	s_waitcnt lgkmcnt(0)
	v_mfma_f32_16x16x32_bf16 v[148:151], v[200:203], v[72:75], 0
	v_mfma_f32_16x16x32_bf16 v[72:75], v[212:215], v[72:75], 0
	v_mfma_f32_16x16x32_bf16 v[148:151], v[208:211], v[76:79], v[148:151]
	v_mfma_f32_16x16x32_bf16 v[72:75], v[216:219], v[76:79], v[72:75]
	v_mfma_f32_16x16x32_bf16 v[76:79], v[200:203], v[80:83], 0
	v_mfma_f32_16x16x32_bf16 v[80:83], v[212:215], v[80:83], 0
	v_mfma_f32_16x16x32_bf16 v[112:115], v[212:215], v[160:163], 0
	v_mfma_f32_16x16x32_bf16 v[100:103], v[200:203], v[192:195], 0
	v_mfma_f32_16x16x32_bf16 v[96:99], v[212:215], v[192:195], 0
	v_mfma_f32_16x16x32_bf16 v[76:79], v[208:211], v[84:87], v[76:79]
	v_mfma_f32_16x16x32_bf16 v[80:83], v[216:219], v[84:87], v[80:83]
	v_mfma_f32_16x16x32_bf16 v[84:87], v[200:203], v[160:163], 0
	v_mfma_f32_16x16x32_bf16 v[112:115], v[216:219], v[164:167], v[112:115]
	v_mfma_f32_16x16x32_bf16 v[100:103], v[208:211], v[196:199], v[100:103]
	v_mfma_f32_16x16x32_bf16 v[96:99], v[216:219], v[196:199], v[96:99]
	v_mfma_f32_16x16x32_bf16 v[84:87], v[208:211], v[164:167], v[84:87]
	s_add_u32 s100, s28, 0x80
	s_addc_u32 s101, s29, 0
	s_barrier
	ds_read_b128 v[116:119], v207 offset:16384
	ds_read_b128 v[128:131], v207 offset:17408
	ds_read_b128 v[132:135], v207 offset:18432
	ds_read_b128 v[144:147], v207 offset:19456
	ds_read_b128 v[160:163], v207 offset:20480
	ds_read_b128 v[164:167], v207 offset:21504
	ds_read_b128 v[192:195], v207 offset:22528
	ds_read_b128 v[196:199], v207 offset:23552
	s_barrier
	s_waitcnt lgkmcnt(0)
	v_mfma_f32_16x16x32_bf16 v[92:95], v[48:51], v[116:119], 0
	v_mfma_f32_16x16x32_bf16 v[88:91], v[60:63], v[116:119], 0
	v_mfma_f32_16x16x32_bf16 v[44:47], v[48:51], v[132:135], 0
	v_mfma_f32_16x16x32_bf16 v[40:43], v[60:63], v[132:135], 0
	v_mfma_f32_16x16x32_bf16 v[28:31], v[48:51], v[160:163], 0
	v_mfma_f32_16x16x32_bf16 v[24:27], v[60:63], v[160:163], 0
	v_mfma_f32_16x16x32_bf16 v[12:15], v[48:51], v[192:195], 0
	v_mfma_f32_16x16x32_bf16 v[8:11], v[60:63], v[192:195], 0
	v_mfma_f32_16x16x32_bf16 v[92:95], v[52:55], v[128:131], v[92:95]
	v_mfma_f32_16x16x32_bf16 v[88:91], v[68:71], v[128:131], v[88:91]
	v_mfma_f32_16x16x32_bf16 v[44:47], v[52:55], v[144:147], v[44:47]
	v_mfma_f32_16x16x32_bf16 v[40:43], v[68:71], v[144:147], v[40:43]
	v_mfma_f32_16x16x32_bf16 v[28:31], v[52:55], v[164:167], v[28:31]
	v_mfma_f32_16x16x32_bf16 v[24:27], v[68:71], v[164:167], v[24:27]
	v_mfma_f32_16x16x32_bf16 v[12:15], v[52:55], v[196:199], v[12:15]
	v_mfma_f32_16x16x32_bf16 v[8:11], v[68:71], v[196:199], v[8:11]
	s_barrier
	s_mov_b32 m0, s41
	s_nop 0
	global_load_lds_dwordx4 v180, s[28:29]
	s_mov_b32 m0, s42
	s_nop 0
	global_load_lds_dwordx4 v184, s[28:29]
	s_add_i32 m0, s40, 0x14000
	s_add_u32 s60, s2, 0x40000
	s_addc_u32 s61, s3, 0
	global_load_lds_dwordx4 v182, s[60:61]
	s_add_i32 m0, s40, 0x16000
	s_add_u32 s28, s28, 0x40000
	s_addc_u32 s29, s29, 0
	global_load_lds_dwordx4 v186, s[60:61]
	s_waitcnt vmcnt(6)
	s_barrier
	v_mfma_f32_16x16x32_bf16 v[36:39], v[200:203], v[132:135], 0
	v_mfma_f32_16x16x32_bf16 v[32:35], v[212:215], v[132:135], 0
	v_mfma_f32_16x16x32_bf16 v[20:23], v[200:203], v[160:163], 0
	v_mfma_f32_16x16x32_bf16 v[16:19], v[212:215], v[160:163], 0
	v_mfma_f32_16x16x32_bf16 v[4:7], v[200:203], v[192:195], 0
	v_mfma_f32_16x16x32_bf16 v[0:3], v[212:215], v[192:195], 0
	v_mfma_f32_16x16x32_bf16 v[48:51], v[200:203], v[116:119], 0
	v_mfma_f32_16x16x32_bf16 v[52:55], v[212:215], v[116:119], 0
	v_mfma_f32_16x16x32_bf16 v[36:39], v[208:211], v[144:147], v[36:39]
	v_mfma_f32_16x16x32_bf16 v[32:35], v[216:219], v[144:147], v[32:35]
	v_mfma_f32_16x16x32_bf16 v[20:23], v[208:211], v[164:167], v[20:23]
	v_mfma_f32_16x16x32_bf16 v[16:19], v[216:219], v[164:167], v[16:19]
	v_mfma_f32_16x16x32_bf16 v[4:7], v[208:211], v[196:199], v[4:7]
	v_mfma_f32_16x16x32_bf16 v[0:3], v[216:219], v[196:199], v[0:3]
	v_mfma_f32_16x16x32_bf16 v[48:51], v[208:211], v[128:131], v[48:51]
	v_mfma_f32_16x16x32_bf16 v[52:55], v[216:219], v[128:131], v[52:55]
	s_barrier
	ds_read_b128 v[56:59], v206 offset:32768
	ds_read_b128 v[60:63], v206 offset:33792
	ds_read_b128 v[64:67], v206 offset:34816
	ds_read_b128 v[68:71], v206 offset:35840
	ds_read_b128 v[116:119], v207 offset:32768
	ds_read_b128 v[128:131], v207 offset:33792
	ds_read_b128 v[160:163], v207 offset:34816
	ds_read_b128 v[164:167], v207 offset:35840
	ds_read_b128 v[192:195], v207 offset:36864
	ds_read_b128 v[196:199], v207 offset:37888
	ds_read_b128 v[200:203], v207 offset:38912
	ds_read_b128 v[208:211], v207 offset:39936
	s_waitcnt lgkmcnt(8)
	s_barrier
	s_waitcnt lgkmcnt(0)
	v_mfma_f32_16x16x32_bf16 v[132:135], v[56:59], v[116:119], v[156:159]
	v_mfma_f32_16x16x32_bf16 v[156:159], v[60:63], v[128:131], v[132:135]
	v_mfma_f32_16x16x32_bf16 v[132:135], v[64:67], v[116:119], v[152:155]
	v_mfma_f32_16x16x32_bf16 v[152:155], v[68:71], v[128:131], v[132:135]
	v_mfma_f32_16x16x32_bf16 v[132:135], v[56:59], v[160:163], v[140:143]
	v_mfma_f32_16x16x32_bf16 v[140:143], v[60:63], v[164:167], v[132:135]
	v_mfma_f32_16x16x32_bf16 v[132:135], v[64:67], v[160:163], v[136:139]
	v_mfma_f32_16x16x32_bf16 v[124:127], v[56:59], v[192:195], v[124:127]
	v_mfma_f32_16x16x32_bf16 v[120:123], v[64:67], v[192:195], v[120:123]
	v_mfma_f32_16x16x32_bf16 v[108:111], v[56:59], v[200:203], v[108:111]
	v_mfma_f32_16x16x32_bf16 v[104:107], v[64:67], v[200:203], v[104:107]
	v_mfma_f32_16x16x32_bf16 v[136:139], v[68:71], v[164:167], v[132:135]
	v_mfma_f32_16x16x32_bf16 v[124:127], v[60:63], v[196:199], v[124:127]
	v_mfma_f32_16x16x32_bf16 v[120:123], v[68:71], v[196:199], v[120:123]
	v_mfma_f32_16x16x32_bf16 v[108:111], v[60:63], v[208:211], v[108:111]
	v_mfma_f32_16x16x32_bf16 v[104:107], v[68:71], v[208:211], v[104:107]
	s_barrier
	s_mov_b32 m0, s43
	ds_read_b128 v[212:215], v206 offset:49152
	ds_read_b128 v[216:219], v206 offset:50176
	ds_read_b128 v[220:223], v206 offset:51200
	global_load_lds_dwordx4 v180, s[28:29]
	s_mov_b32 m0, s44
	ds_read_b128 v[236:239], v206 offset:52224
	global_load_lds_dwordx4 v184, s[28:29]
	s_add_i32 m0, s40, 0x18000
	s_nop 0
	global_load_lds_dwordx4 v182, s[98:99]
	s_add_i32 m0, s40, 0x1a000
	s_nop 0
	global_load_lds_dwordx4 v186, s[98:99]
	s_barrier
	s_waitcnt lgkmcnt(0)
	v_mfma_f32_16x16x32_bf16 v[72:75], v[220:223], v[116:119], v[72:75]
	v_mfma_f32_16x16x32_bf16 v[132:135], v[212:215], v[116:119], v[148:151]
	v_mfma_f32_16x16x32_bf16 v[144:147], v[236:239], v[128:131], v[72:75]
	v_mfma_f32_16x16x32_bf16 v[72:75], v[212:215], v[160:163], v[76:79]
	v_mfma_f32_16x16x32_bf16 v[148:151], v[216:219], v[128:131], v[132:135]
	v_mfma_f32_16x16x32_bf16 v[132:135], v[216:219], v[164:167], v[72:75]
	v_mfma_f32_16x16x32_bf16 v[72:75], v[220:223], v[160:163], v[80:83]
	v_mfma_f32_16x16x32_bf16 v[128:131], v[236:239], v[164:167], v[72:75]
	v_mfma_f32_16x16x32_bf16 v[72:75], v[212:215], v[192:195], v[84:87]
	v_mfma_f32_16x16x32_bf16 v[116:119], v[216:219], v[196:199], v[72:75]
	v_mfma_f32_16x16x32_bf16 v[72:75], v[220:223], v[192:195], v[112:115]
	v_mfma_f32_16x16x32_bf16 v[112:115], v[236:239], v[196:199], v[72:75]
	v_mfma_f32_16x16x32_bf16 v[72:75], v[212:215], v[200:203], v[100:103]
	v_mfma_f32_16x16x32_bf16 v[100:103], v[216:219], v[208:211], v[72:75]
	v_mfma_f32_16x16x32_bf16 v[72:75], v[220:223], v[200:203], v[96:99]
	v_mfma_f32_16x16x32_bf16 v[96:99], v[236:239], v[208:211], v[72:75]
	s_barrier
	s_nop 2
	ds_read_b128 v[72:75], v207 offset:49152
	ds_read_b128 v[76:79], v207 offset:50176
	ds_read_b128 v[80:83], v207 offset:51200
	ds_read_b128 v[84:87], v207 offset:52224
	ds_read_b128 v[160:163], v207 offset:53248
	ds_read_b128 v[164:167], v207 offset:54272
	ds_read_b128 v[192:195], v207 offset:55296
	ds_read_b128 v[196:199], v207 offset:56320
	s_barrier
	s_waitcnt lgkmcnt(0)
	v_mfma_f32_16x16x32_bf16 v[92:95], v[56:59], v[72:75], v[92:95]
	v_mfma_f32_16x16x32_bf16 v[88:91], v[64:67], v[72:75], v[88:91]
	v_mfma_f32_16x16x32_bf16 v[44:47], v[56:59], v[80:83], v[44:47]
	v_mfma_f32_16x16x32_bf16 v[40:43], v[64:67], v[80:83], v[40:43]
	v_mfma_f32_16x16x32_bf16 v[28:31], v[56:59], v[160:163], v[28:31]
	v_mfma_f32_16x16x32_bf16 v[24:27], v[64:67], v[160:163], v[24:27]
	v_mfma_f32_16x16x32_bf16 v[12:15], v[56:59], v[192:195], v[12:15]
	v_mfma_f32_16x16x32_bf16 v[8:11], v[64:67], v[192:195], v[8:11]
	v_mfma_f32_16x16x32_bf16 v[92:95], v[60:63], v[76:79], v[92:95]
	v_mfma_f32_16x16x32_bf16 v[88:91], v[68:71], v[76:79], v[88:91]
	v_mfma_f32_16x16x32_bf16 v[44:47], v[60:63], v[84:87], v[44:47]
	v_mfma_f32_16x16x32_bf16 v[40:43], v[68:71], v[84:87], v[40:43]
	v_mfma_f32_16x16x32_bf16 v[28:31], v[60:63], v[164:167], v[28:31]
	v_mfma_f32_16x16x32_bf16 v[24:27], v[68:71], v[164:167], v[24:27]
	v_mfma_f32_16x16x32_bf16 v[12:15], v[60:63], v[196:199], v[12:15]
	v_mfma_f32_16x16x32_bf16 v[8:11], v[68:71], v[196:199], v[8:11]
	s_barrier
	s_mov_b32 m0, s53
	s_nop 0
	global_load_lds_dwordx4 v180, s[100:101]
	s_mov_b32 m0, s54
	s_nop 0
	global_load_lds_dwordx4 v184, s[100:101]
	s_add_i32 m0, s40, 0x1c000
	s_add_u32 s2, s2, 0x40080
	s_addc_u32 s3, s3, 0
	global_load_lds_dwordx4 v182, s[2:3]
	s_add_i32 m0, s40, 0x1e000
	s_add_i32 s58, s58, 2
	global_load_lds_dwordx4 v186, s[2:3]
	s_waitcnt vmcnt(6)
	s_barrier
	v_mfma_f32_16x16x32_bf16 v[48:51], v[212:215], v[72:75], v[48:51]
	v_mfma_f32_16x16x32_bf16 v[64:67], v[216:219], v[76:79], v[48:51]
	v_mfma_f32_16x16x32_bf16 v[48:51], v[220:223], v[72:75], v[52:55]
	v_mfma_f32_16x16x32_bf16 v[36:39], v[212:215], v[80:83], v[36:39]
	v_mfma_f32_16x16x32_bf16 v[32:35], v[220:223], v[80:83], v[32:35]
	v_mfma_f32_16x16x32_bf16 v[20:23], v[212:215], v[160:163], v[20:23]
	v_mfma_f32_16x16x32_bf16 v[16:19], v[220:223], v[160:163], v[16:19]
	v_mfma_f32_16x16x32_bf16 v[4:7], v[212:215], v[192:195], v[4:7]
	v_mfma_f32_16x16x32_bf16 v[0:3], v[220:223], v[192:195], v[0:3]
	v_mfma_f32_16x16x32_bf16 v[56:59], v[236:239], v[76:79], v[48:51]
	v_mfma_f32_16x16x32_bf16 v[36:39], v[216:219], v[84:87], v[36:39]
	v_mfma_f32_16x16x32_bf16 v[32:35], v[236:239], v[84:87], v[32:35]
	v_mfma_f32_16x16x32_bf16 v[20:23], v[216:219], v[164:167], v[20:23]
	v_mfma_f32_16x16x32_bf16 v[16:19], v[236:239], v[164:167], v[16:19]
	v_mfma_f32_16x16x32_bf16 v[4:7], v[216:219], v[196:199], v[4:7]
	v_mfma_f32_16x16x32_bf16 v[0:3], v[236:239], v[196:199], v[0:3]
	s_add_u32 s8, s8, 0x100
	s_addc_u32 s9, s9, 0
	s_add_u32 s56, s56, 0x100
	s_addc_u32 s57, s57, 0
	s_cmp_gt_u32 s58, 13
	s_barrier
.LBB0_678:
	s_add_u32 s2, s8, 0xfffc0080
	s_addc_u32 s3, s9, -1
	ds_read_b128 v[48:51], v206
	ds_read_b128 v[52:55], v206 offset:1024
	ds_read_b128 v[60:63], v206 offset:2048
	ds_read_b128 v[68:71], v206 offset:3072
	s_cmp_eq_u32 s58, 12
	s_cselect_b32 s29, s1, s3
	s_cselect_b32 s28, s7, s2
	s_cselect_b32 s3, s21, s57
	s_cselect_b32 s2, s23, s56
	ds_read_b128 v[72:75], v207
	ds_read_b128 v[76:79], v207 offset:1024
	ds_read_b128 v[80:83], v207 offset:2048
	ds_read_b128 v[84:87], v207 offset:3072
	ds_read_b128 v[160:163], v207 offset:4096
	ds_read_b128 v[164:167], v207 offset:5120
	ds_read_b128 v[192:195], v207 offset:6144
	ds_read_b128 v[196:199], v207 offset:7168
	s_waitcnt lgkmcnt(8)
	s_barrier
	s_waitcnt lgkmcnt(0)
	v_mfma_f32_16x16x32_bf16 v[156:159], v[48:51], v[72:75], v[156:159]
	v_mfma_f32_16x16x32_bf16 v[152:155], v[60:63], v[72:75], v[152:155]
	v_mfma_f32_16x16x32_bf16 v[140:143], v[48:51], v[80:83], v[140:143]
	v_mfma_f32_16x16x32_bf16 v[136:139], v[60:63], v[80:83], v[136:139]
	v_mfma_f32_16x16x32_bf16 v[124:127], v[48:51], v[160:163], v[124:127]
	v_mfma_f32_16x16x32_bf16 v[120:123], v[60:63], v[160:163], v[120:123]
	v_mfma_f32_16x16x32_bf16 v[108:111], v[48:51], v[192:195], v[108:111]
	v_mfma_f32_16x16x32_bf16 v[104:107], v[60:63], v[192:195], v[104:107]
	v_mfma_f32_16x16x32_bf16 v[156:159], v[52:55], v[76:79], v[156:159]
	v_mfma_f32_16x16x32_bf16 v[152:155], v[68:71], v[76:79], v[152:155]
	v_mfma_f32_16x16x32_bf16 v[140:143], v[52:55], v[84:87], v[140:143]
	v_mfma_f32_16x16x32_bf16 v[136:139], v[68:71], v[84:87], v[136:139]
	v_mfma_f32_16x16x32_bf16 v[124:127], v[52:55], v[164:167], v[124:127]
	v_mfma_f32_16x16x32_bf16 v[120:123], v[68:71], v[164:167], v[120:123]
	v_mfma_f32_16x16x32_bf16 v[108:111], v[52:55], v[196:199], v[108:111]
	v_mfma_f32_16x16x32_bf16 v[104:107], v[68:71], v[196:199], v[104:107]
	s_barrier
	s_add_i32 m0, s41, 0xc000
	ds_read_b128 v[200:203], v206 offset:16384
	ds_read_b128 v[208:211], v206 offset:17408
	ds_read_b128 v[212:215], v206 offset:18432
	global_load_lds_dwordx4 v188, s[8:9]
	s_add_i32 m0, s41, 0xe000
	ds_read_b128 v[216:219], v206 offset:19456
	global_load_lds_dwordx4 v190, s[8:9]
	s_add_u32 s98, s2, 0x80
	s_addc_u32 s99, s3, 0
	s_add_i32 m0, s40, 0x10000
	s_nop 0
	global_load_lds_dwordx4 v182, s[2:3]
	s_add_i32 m0, s40, 0x12000
	s_nop 0
	global_load_lds_dwordx4 v186, s[2:3]
	s_barrier
	s_waitcnt lgkmcnt(0)
	v_mfma_f32_16x16x32_bf16 v[148:151], v[200:203], v[72:75], v[148:151]
	v_mfma_f32_16x16x32_bf16 v[72:75], v[212:215], v[72:75], v[144:147]
	v_mfma_f32_16x16x32_bf16 v[148:151], v[208:211], v[76:79], v[148:151]
	v_mfma_f32_16x16x32_bf16 v[72:75], v[216:219], v[76:79], v[72:75]
	v_mfma_f32_16x16x32_bf16 v[76:79], v[200:203], v[80:83], v[132:135]
	v_mfma_f32_16x16x32_bf16 v[80:83], v[212:215], v[80:83], v[128:131]
	v_mfma_f32_16x16x32_bf16 v[112:115], v[212:215], v[160:163], v[112:115]
	v_mfma_f32_16x16x32_bf16 v[100:103], v[200:203], v[192:195], v[100:103]
	v_mfma_f32_16x16x32_bf16 v[96:99], v[212:215], v[192:195], v[96:99]
	v_mfma_f32_16x16x32_bf16 v[76:79], v[208:211], v[84:87], v[76:79]
	v_mfma_f32_16x16x32_bf16 v[80:83], v[216:219], v[84:87], v[80:83]
	v_mfma_f32_16x16x32_bf16 v[84:87], v[200:203], v[160:163], v[116:119]
	v_mfma_f32_16x16x32_bf16 v[112:115], v[216:219], v[164:167], v[112:115]
	v_mfma_f32_16x16x32_bf16 v[100:103], v[208:211], v[196:199], v[100:103]
	v_mfma_f32_16x16x32_bf16 v[96:99], v[216:219], v[196:199], v[96:99]
	v_mfma_f32_16x16x32_bf16 v[84:87], v[208:211], v[164:167], v[84:87]
	s_add_u32 s100, s28, 0x80
	s_addc_u32 s101, s29, 0
	s_barrier
	ds_read_b128 v[116:119], v207 offset:16384
	ds_read_b128 v[128:131], v207 offset:17408
	ds_read_b128 v[132:135], v207 offset:18432
	ds_read_b128 v[144:147], v207 offset:19456
	ds_read_b128 v[160:163], v207 offset:20480
	ds_read_b128 v[164:167], v207 offset:21504
	ds_read_b128 v[192:195], v207 offset:22528
	ds_read_b128 v[196:199], v207 offset:23552
	s_barrier
	s_waitcnt lgkmcnt(0)
	v_mfma_f32_16x16x32_bf16 v[92:95], v[48:51], v[116:119], v[92:95]
	v_mfma_f32_16x16x32_bf16 v[88:91], v[60:63], v[116:119], v[88:91]
	v_mfma_f32_16x16x32_bf16 v[44:47], v[48:51], v[132:135], v[44:47]
	v_mfma_f32_16x16x32_bf16 v[40:43], v[60:63], v[132:135], v[40:43]
	v_mfma_f32_16x16x32_bf16 v[28:31], v[48:51], v[160:163], v[28:31]
	v_mfma_f32_16x16x32_bf16 v[24:27], v[60:63], v[160:163], v[24:27]
	v_mfma_f32_16x16x32_bf16 v[12:15], v[48:51], v[192:195], v[12:15]
	v_mfma_f32_16x16x32_bf16 v[8:11], v[60:63], v[192:195], v[8:11]
	v_mfma_f32_16x16x32_bf16 v[92:95], v[52:55], v[128:131], v[92:95]
	v_mfma_f32_16x16x32_bf16 v[88:91], v[68:71], v[128:131], v[88:91]
	v_mfma_f32_16x16x32_bf16 v[44:47], v[52:55], v[144:147], v[44:47]
	v_mfma_f32_16x16x32_bf16 v[40:43], v[68:71], v[144:147], v[40:43]
	v_mfma_f32_16x16x32_bf16 v[28:31], v[52:55], v[164:167], v[28:31]
	v_mfma_f32_16x16x32_bf16 v[24:27], v[68:71], v[164:167], v[24:27]
	v_mfma_f32_16x16x32_bf16 v[12:15], v[52:55], v[196:199], v[12:15]
	v_mfma_f32_16x16x32_bf16 v[8:11], v[68:71], v[196:199], v[8:11]
	s_barrier
	s_mov_b32 m0, s41
	s_nop 0
	global_load_lds_dwordx4 v180, s[28:29]
	s_mov_b32 m0, s42
	s_nop 0
	global_load_lds_dwordx4 v184, s[28:29]
	s_add_i32 m0, s40, 0x14000
	s_add_u32 s60, s2, 0x40000
	s_addc_u32 s61, s3, 0
	global_load_lds_dwordx4 v182, s[60:61]
	s_add_i32 m0, s40, 0x16000
	s_add_u32 s28, s28, 0x40000
	s_addc_u32 s29, s29, 0
	global_load_lds_dwordx4 v186, s[60:61]
	s_waitcnt vmcnt(6)
	s_barrier
	v_mfma_f32_16x16x32_bf16 v[36:39], v[200:203], v[132:135], v[36:39]
	v_mfma_f32_16x16x32_bf16 v[32:35], v[212:215], v[132:135], v[32:35]
	v_mfma_f32_16x16x32_bf16 v[20:23], v[200:203], v[160:163], v[20:23]
	v_mfma_f32_16x16x32_bf16 v[16:19], v[212:215], v[160:163], v[16:19]
	v_mfma_f32_16x16x32_bf16 v[4:7], v[200:203], v[192:195], v[4:7]
	v_mfma_f32_16x16x32_bf16 v[0:3], v[212:215], v[192:195], v[0:3]
	v_mfma_f32_16x16x32_bf16 v[48:51], v[200:203], v[116:119], v[64:67]
	v_mfma_f32_16x16x32_bf16 v[52:55], v[212:215], v[116:119], v[56:59]
	v_mfma_f32_16x16x32_bf16 v[36:39], v[208:211], v[144:147], v[36:39]
	v_mfma_f32_16x16x32_bf16 v[32:35], v[216:219], v[144:147], v[32:35]
	v_mfma_f32_16x16x32_bf16 v[20:23], v[208:211], v[164:167], v[20:23]
	v_mfma_f32_16x16x32_bf16 v[16:19], v[216:219], v[164:167], v[16:19]
	v_mfma_f32_16x16x32_bf16 v[4:7], v[208:211], v[196:199], v[4:7]
	v_mfma_f32_16x16x32_bf16 v[0:3], v[216:219], v[196:199], v[0:3]
	v_mfma_f32_16x16x32_bf16 v[48:51], v[208:211], v[128:131], v[48:51]
	v_mfma_f32_16x16x32_bf16 v[52:55], v[216:219], v[128:131], v[52:55]
	s_barrier
	ds_read_b128 v[56:59], v206 offset:32768
	ds_read_b128 v[60:63], v206 offset:33792
	ds_read_b128 v[64:67], v206 offset:34816
	ds_read_b128 v[68:71], v206 offset:35840
	ds_read_b128 v[116:119], v207 offset:32768
	ds_read_b128 v[128:131], v207 offset:33792
	ds_read_b128 v[160:163], v207 offset:34816
	ds_read_b128 v[164:167], v207 offset:35840
	ds_read_b128 v[192:195], v207 offset:36864
	ds_read_b128 v[196:199], v207 offset:37888
	ds_read_b128 v[200:203], v207 offset:38912
	ds_read_b128 v[208:211], v207 offset:39936
	s_waitcnt lgkmcnt(8)
	s_barrier
	s_waitcnt lgkmcnt(0)
	v_mfma_f32_16x16x32_bf16 v[132:135], v[56:59], v[116:119], v[156:159]
	v_mfma_f32_16x16x32_bf16 v[156:159], v[60:63], v[128:131], v[132:135]
	v_mfma_f32_16x16x32_bf16 v[132:135], v[64:67], v[116:119], v[152:155]
	v_mfma_f32_16x16x32_bf16 v[152:155], v[68:71], v[128:131], v[132:135]
	v_mfma_f32_16x16x32_bf16 v[132:135], v[56:59], v[160:163], v[140:143]
	v_mfma_f32_16x16x32_bf16 v[140:143], v[60:63], v[164:167], v[132:135]
	v_mfma_f32_16x16x32_bf16 v[132:135], v[64:67], v[160:163], v[136:139]
	v_mfma_f32_16x16x32_bf16 v[124:127], v[56:59], v[192:195], v[124:127]
	v_mfma_f32_16x16x32_bf16 v[120:123], v[64:67], v[192:195], v[120:123]
	v_mfma_f32_16x16x32_bf16 v[108:111], v[56:59], v[200:203], v[108:111]
	v_mfma_f32_16x16x32_bf16 v[104:107], v[64:67], v[200:203], v[104:107]
	v_mfma_f32_16x16x32_bf16 v[136:139], v[68:71], v[164:167], v[132:135]
	v_mfma_f32_16x16x32_bf16 v[124:127], v[60:63], v[196:199], v[124:127]
	v_mfma_f32_16x16x32_bf16 v[120:123], v[68:71], v[196:199], v[120:123]
	v_mfma_f32_16x16x32_bf16 v[108:111], v[60:63], v[208:211], v[108:111]
	v_mfma_f32_16x16x32_bf16 v[104:107], v[68:71], v[208:211], v[104:107]
	s_barrier
	s_mov_b32 m0, s43
	ds_read_b128 v[212:215], v206 offset:49152
	ds_read_b128 v[216:219], v206 offset:50176
	ds_read_b128 v[220:223], v206 offset:51200
	global_load_lds_dwordx4 v180, s[28:29]
	s_mov_b32 m0, s44
	ds_read_b128 v[236:239], v206 offset:52224
	global_load_lds_dwordx4 v184, s[28:29]
	s_add_i32 m0, s40, 0x18000
	s_nop 0
	global_load_lds_dwordx4 v182, s[98:99]
	s_add_i32 m0, s40, 0x1a000
	s_nop 0
	global_load_lds_dwordx4 v186, s[98:99]
	s_barrier
	s_waitcnt lgkmcnt(0)
	v_mfma_f32_16x16x32_bf16 v[72:75], v[220:223], v[116:119], v[72:75]
	v_mfma_f32_16x16x32_bf16 v[132:135], v[212:215], v[116:119], v[148:151]
	v_mfma_f32_16x16x32_bf16 v[144:147], v[236:239], v[128:131], v[72:75]
	v_mfma_f32_16x16x32_bf16 v[72:75], v[212:215], v[160:163], v[76:79]
	v_mfma_f32_16x16x32_bf16 v[148:151], v[216:219], v[128:131], v[132:135]
	v_mfma_f32_16x16x32_bf16 v[132:135], v[216:219], v[164:167], v[72:75]
	v_mfma_f32_16x16x32_bf16 v[72:75], v[220:223], v[160:163], v[80:83]
	v_mfma_f32_16x16x32_bf16 v[128:131], v[236:239], v[164:167], v[72:75]
	v_mfma_f32_16x16x32_bf16 v[72:75], v[212:215], v[192:195], v[84:87]
	v_mfma_f32_16x16x32_bf16 v[116:119], v[216:219], v[196:199], v[72:75]
	v_mfma_f32_16x16x32_bf16 v[72:75], v[220:223], v[192:195], v[112:115]
	v_mfma_f32_16x16x32_bf16 v[112:115], v[236:239], v[196:199], v[72:75]
	v_mfma_f32_16x16x32_bf16 v[72:75], v[212:215], v[200:203], v[100:103]
	v_mfma_f32_16x16x32_bf16 v[100:103], v[216:219], v[208:211], v[72:75]
	v_mfma_f32_16x16x32_bf16 v[72:75], v[220:223], v[200:203], v[96:99]
	v_mfma_f32_16x16x32_bf16 v[96:99], v[236:239], v[208:211], v[72:75]
	s_barrier
	s_nop 2
	ds_read_b128 v[72:75], v207 offset:49152
	ds_read_b128 v[76:79], v207 offset:50176
	ds_read_b128 v[80:83], v207 offset:51200
	ds_read_b128 v[84:87], v207 offset:52224
	ds_read_b128 v[160:163], v207 offset:53248
	ds_read_b128 v[164:167], v207 offset:54272
	ds_read_b128 v[192:195], v207 offset:55296
	ds_read_b128 v[196:199], v207 offset:56320
	s_barrier
	s_waitcnt lgkmcnt(0)
	v_mfma_f32_16x16x32_bf16 v[92:95], v[56:59], v[72:75], v[92:95]
	v_mfma_f32_16x16x32_bf16 v[88:91], v[64:67], v[72:75], v[88:91]
	v_mfma_f32_16x16x32_bf16 v[44:47], v[56:59], v[80:83], v[44:47]
	v_mfma_f32_16x16x32_bf16 v[40:43], v[64:67], v[80:83], v[40:43]
	v_mfma_f32_16x16x32_bf16 v[28:31], v[56:59], v[160:163], v[28:31]
	v_mfma_f32_16x16x32_bf16 v[24:27], v[64:67], v[160:163], v[24:27]
	v_mfma_f32_16x16x32_bf16 v[12:15], v[56:59], v[192:195], v[12:15]
	v_mfma_f32_16x16x32_bf16 v[8:11], v[64:67], v[192:195], v[8:11]
	v_mfma_f32_16x16x32_bf16 v[92:95], v[60:63], v[76:79], v[92:95]
	v_mfma_f32_16x16x32_bf16 v[88:91], v[68:71], v[76:79], v[88:91]
	v_mfma_f32_16x16x32_bf16 v[44:47], v[60:63], v[84:87], v[44:47]
	v_mfma_f32_16x16x32_bf16 v[40:43], v[68:71], v[84:87], v[40:43]
	v_mfma_f32_16x16x32_bf16 v[28:31], v[60:63], v[164:167], v[28:31]
	v_mfma_f32_16x16x32_bf16 v[24:27], v[68:71], v[164:167], v[24:27]
	v_mfma_f32_16x16x32_bf16 v[12:15], v[60:63], v[196:199], v[12:15]
	v_mfma_f32_16x16x32_bf16 v[8:11], v[68:71], v[196:199], v[8:11]
	s_barrier
	s_mov_b32 m0, s53
	s_nop 0
	global_load_lds_dwordx4 v180, s[100:101]
	s_mov_b32 m0, s54
	s_nop 0
	global_load_lds_dwordx4 v184, s[100:101]
	s_add_i32 m0, s40, 0x1c000
	s_add_u32 s2, s2, 0x40080
	s_addc_u32 s3, s3, 0
	global_load_lds_dwordx4 v182, s[2:3]
	s_add_i32 m0, s40, 0x1e000
	s_add_i32 s58, s58, 2
	global_load_lds_dwordx4 v186, s[2:3]
	s_waitcnt vmcnt(6)
	s_barrier
	v_mfma_f32_16x16x32_bf16 v[48:51], v[212:215], v[72:75], v[48:51]
	v_mfma_f32_16x16x32_bf16 v[64:67], v[216:219], v[76:79], v[48:51]
	v_mfma_f32_16x16x32_bf16 v[48:51], v[220:223], v[72:75], v[52:55]
	v_mfma_f32_16x16x32_bf16 v[36:39], v[212:215], v[80:83], v[36:39]
	v_mfma_f32_16x16x32_bf16 v[32:35], v[220:223], v[80:83], v[32:35]
	v_mfma_f32_16x16x32_bf16 v[20:23], v[212:215], v[160:163], v[20:23]
	v_mfma_f32_16x16x32_bf16 v[16:19], v[220:223], v[160:163], v[16:19]
	v_mfma_f32_16x16x32_bf16 v[4:7], v[212:215], v[192:195], v[4:7]
	v_mfma_f32_16x16x32_bf16 v[0:3], v[220:223], v[192:195], v[0:3]
	v_mfma_f32_16x16x32_bf16 v[56:59], v[236:239], v[76:79], v[48:51]
	v_mfma_f32_16x16x32_bf16 v[36:39], v[216:219], v[84:87], v[36:39]
	v_mfma_f32_16x16x32_bf16 v[32:35], v[236:239], v[84:87], v[32:35]
	v_mfma_f32_16x16x32_bf16 v[20:23], v[216:219], v[164:167], v[20:23]
	v_mfma_f32_16x16x32_bf16 v[16:19], v[236:239], v[164:167], v[16:19]
	v_mfma_f32_16x16x32_bf16 v[4:7], v[216:219], v[196:199], v[4:7]
	v_mfma_f32_16x16x32_bf16 v[0:3], v[236:239], v[196:199], v[0:3]
	s_add_u32 s8, s8, 0x100
	s_addc_u32 s9, s9, 0
	s_add_u32 s56, s56, 0x100
	s_addc_u32 s57, s57, 0
	s_cmp_gt_u32 s58, 13
	s_barrier
	s_cbranch_scc0 .LBB0_678
	s_lshl_b32 s1, s0, 8
	s_add_i32 s2, s1, s51
	s_lshl_b32 s1, s6, 8
	v_mov_b32_e32 v160, v205
	v_mov_b32_e32 v208, v204
	s_or_b32 s1, s1, s52
	s_nop 0
	v_lshl_add_u32 v192, v208, 3, s1
	s_add_i32 s1, s0, -16
	s_lshr_b32 s1, s1, 3
	s_add_i32 s1, s1, 1
	s_cmp_gt_i32 s0, 15
	s_cselect_b32 s3, s1, 0
	s_mul_i32 s96, s3, 0x1800
	s_lshl_b64 s[0:1], s[96:97], 2
	s_add_u32 s0, s45, s0
	v_ashrrev_i32_e32 v193, 31, v192
	s_addc_u32 s1, s46, s1
	v_lshlrev_b64 v[196:197], 2, v[192:193]
	s_lshl_b32 s96, s3, 10
	v_lshl_add_u64 v[48:49], s[0:1], 0, v[196:197]
	s_lshl_b64 s[0:1], s[96:97], 2
	s_add_u32 s0, s49, s0
	s_addc_u32 s1, s50, s1
	v_lshl_add_u64 v[52:53], s[0:1], 0, v[196:197]
	global_load_dwordx4 v[80:83], v[48:49], off offset:16
	global_load_dwordx4 v[84:87], v[48:49], off
	global_load_dwordx4 v[72:75], v[52:53], off offset:16
	global_load_dwordx4 v[76:79], v[52:53], off
	global_load_dwordx4 v[60:63], v[48:49], off offset:528
	global_load_dwordx4 v[68:71], v[48:49], off offset:512
	s_nop 0
	global_load_dwordx4 v[48:51], v[52:53], off offset:528
	s_nop 0
	global_load_dwordx4 v[52:55], v[52:53], off offset:512
	v_add_u32_e32 v194, s2, v160
	v_ashrrev_i32_e32 v195, 31, v194
	v_lshlrev_b64 v[160:161], 10, v[194:195]
	v_lshl_add_u64 v[198:199], v[160:161], 0, v[192:193]
	v_cndmask_b32_e64 v160, 0, 1, s[74:75]
	v_cmp_gt_i32_e64 s[0:1], s71, v194
	v_cmp_ne_u32_e64 s[6:7], 1, v160
	s_andn2_b64 vcc, exec, s[74:75]
	s_mov_b64 s[2:3], -1
	s_cbranch_vccnz .LBB0_681
	v_lshl_add_u64 v[160:161], v[198:199], 1, s[14:15]
	v_mov_b32_e32 v222, v160
	v_mov_b32_e32 v223, v161
	global_load_dwordx4 v[210:213], v[222:223], off
	global_load_dwordx4 v[214:217], v[222:223], off offset:256
	s_mov_b64 s[80:81], 0x8000
	v_lshl_add_u64 v[222:223], v[222:223], 0, s[80:81]
	global_load_dwordx4 v[218:221], v[222:223], off
	global_load_dwordx4 v[236:239], v[222:223], off offset:256
	s_mov_b64 s[2:3], 0
	s_waitcnt vmcnt(3)
	v_lshlrev_b32_e32 v164, 16, v210
	v_and_b32_e32 v165, 0xffff0000, v210
	v_lshlrev_b32_e32 v166, 16, v211
	v_and_b32_e32 v167, 0xffff0000, v211
	v_lshlrev_b32_e32 v160, 16, v212
	v_and_b32_e32 v161, 0xffff0000, v212
	v_lshlrev_b32_e32 v162, 16, v213
	v_and_b32_e32 v163, 0xffff0000, v213
	s_mov_b64 s[80:81], 0x8000
	v_lshl_add_u64 v[222:223], v[222:223], 0, s[80:81]
	global_load_dwordx4 v[210:213], v[222:223], off

.LBB0_879:
	s_ashr_i32 s39, s38, 31
	v_cmp_lt_i64_e32 vcc, s[12:13], v[178:179]
	s_lshl_b64 s[12:13], s[38:39], 19
	s_add_u32 s40, s49, s12
	s_addc_u32 s41, s50, s13
	s_lshl_b32 s84, s82, 18
	s_add_u32 s40, s40, s84
	s_addc_u32 s41, s41, 0
	s_and_b64 s[12:13], vcc, exec
	s_cselect_b32 s1, s41, s11
	s_cselect_b32 s9, s40, s10
	s_ashr_i32 s37, s36, 31
	s_lshl_b64 s[12:13], s[36:37], 19
	s_add_u32 s42, s51, s12
	s_addc_u32 s43, s52, s13
	s_and_b64 s[12:13], vcc, exec
	s_cselect_b32 s14, s43, s3
	s_cselect_b32 s15, s42, s2
	s_add_u32 s10, s10, 0x40080
	s_addc_u32 s11, s11, 0
	s_add_u32 s37, s2, 0x100
	s_addc_u32 s39, s3, 0
	s_mov_b32 s67, -2
	s_cmp_lg_u32 s83, 0
	s_cbranch_scc1 .Lup_half_peel
	s_add_u32 s2, s10, 0xfffc0080
	s_addc_u32 s3, s11, -1
	ds_read_b128 v[48:51], v237
	ds_read_b128 v[52:55], v237 offset:1024
	ds_read_b128 v[104:107], v237 offset:2048
	ds_read_b128 v[108:111], v237 offset:3072
	s_cmp_eq_u32 s67, 12
	s_cselect_b32 s13, s1, s3
	s_cselect_b32 s12, s9, s2
	s_cselect_b32 s3, s14, s39
	s_cselect_b32 s2, s15, s37
	ds_read_b128 v[112:115], v238
	ds_read_b128 v[116:119], v238 offset:1024
	ds_read_b128 v[120:123], v238 offset:2048
	ds_read_b128 v[156:159], v238 offset:3072
	ds_read_b128 v[160:163], v238 offset:4096
	ds_read_b128 v[164:167], v238 offset:5120
	ds_read_b128 v[190:193], v238 offset:6144
	ds_read_b128 v[194:197], v238 offset:7168
	s_waitcnt lgkmcnt(8)
	s_barrier
	s_waitcnt lgkmcnt(0)
	v_mfma_f32_16x16x32_bf16 v[152:155], v[48:51], v[112:115], 0
	v_mfma_f32_16x16x32_bf16 v[68:71], v[104:107], v[112:115], 0
	v_mfma_f32_16x16x32_bf16 v[148:151], v[48:51], v[120:123], 0
	v_mfma_f32_16x16x32_bf16 v[64:67], v[104:107], v[120:123], 0
	v_mfma_f32_16x16x32_bf16 v[136:139], v[48:51], v[160:163], 0
	v_mfma_f32_16x16x32_bf16 v[44:47], v[104:107], v[160:163], 0
	v_mfma_f32_16x16x32_bf16 v[128:131], v[48:51], v[190:193], 0
	v_mfma_f32_16x16x32_bf16 v[40:43], v[104:107], v[190:193], 0
	v_mfma_f32_16x16x32_bf16 v[152:155], v[52:55], v[116:119], v[152:155]
	v_mfma_f32_16x16x32_bf16 v[68:71], v[108:111], v[116:119], v[68:71]
	v_mfma_f32_16x16x32_bf16 v[148:151], v[52:55], v[156:159], v[148:151]
	v_mfma_f32_16x16x32_bf16 v[64:67], v[108:111], v[156:159], v[64:67]
	v_mfma_f32_16x16x32_bf16 v[136:139], v[52:55], v[164:167], v[136:139]
	v_mfma_f32_16x16x32_bf16 v[44:47], v[108:111], v[164:167], v[44:47]
	v_mfma_f32_16x16x32_bf16 v[128:131], v[52:55], v[194:197], v[128:131]
	v_mfma_f32_16x16x32_bf16 v[40:43], v[108:111], v[194:197], v[40:43]
	s_barrier
	s_add_i32 m0, s54, 0xc000
	ds_read_b128 v[198:201], v237 offset:16384
	ds_read_b128 v[202:205], v237 offset:17408
	ds_read_b128 v[206:209], v237 offset:18432
	global_load_lds_dwordx4 v186, s[10:11]
	s_add_i32 m0, s54, 0xe000
	ds_read_b128 v[210:213], v237 offset:19456
	global_load_lds_dwordx4 v188, s[10:11]
	s_add_u32 s98, s2, 0x80
	s_addc_u32 s99, s3, 0
	s_add_i32 m0, s53, 0x10000
	s_nop 0
	global_load_lds_dwordx4 v168, s[2:3]
	s_add_i32 m0, s53, 0x12000
	s_nop 0
	global_load_lds_dwordx4 v184, s[2:3]
	s_barrier
	s_waitcnt lgkmcnt(0)
	v_mfma_f32_16x16x32_bf16 v[144:147], v[198:201], v[112:115], 0
	v_mfma_f32_16x16x32_bf16 v[60:63], v[206:209], v[112:115], 0
	v_mfma_f32_16x16x32_bf16 v[56:59], v[206:209], v[120:123], 0
	v_mfma_f32_16x16x32_bf16 v[36:39], v[206:209], v[160:163], 0
	v_mfma_f32_16x16x32_bf16 v[32:35], v[206:209], v[190:193], 0
	v_mfma_f32_16x16x32_bf16 v[144:147], v[202:205], v[116:119], v[144:147]
	v_mfma_f32_16x16x32_bf16 v[60:63], v[210:213], v[116:119], v[60:63]
	v_mfma_f32_16x16x32_bf16 v[112:115], v[198:201], v[120:123], 0
	v_mfma_f32_16x16x32_bf16 v[56:59], v[210:213], v[156:159], v[56:59]
	v_mfma_f32_16x16x32_bf16 v[116:119], v[198:201], v[160:163], 0
	v_mfma_f32_16x16x32_bf16 v[36:39], v[210:213], v[164:167], v[36:39]
	v_mfma_f32_16x16x32_bf16 v[120:123], v[198:201], v[190:193], 0
	v_mfma_f32_16x16x32_bf16 v[32:35], v[210:213], v[194:197], v[32:35]
	v_mfma_f32_16x16x32_bf16 v[112:115], v[202:205], v[156:159], v[112:115]
	v_mfma_f32_16x16x32_bf16 v[116:119], v[202:205], v[164:167], v[116:119]
	v_mfma_f32_16x16x32_bf16 v[120:123], v[202:205], v[194:197], v[120:123]
	s_add_u32 s100, s12, 0x80
	s_addc_u32 s101, s13, 0
	s_barrier
	ds_read_b128 v[124:127], v238 offset:16384
	ds_read_b128 v[132:135], v238 offset:17408
	ds_read_b128 v[140:143], v238 offset:18432
	ds_read_b128 v[156:159], v238 offset:19456
	ds_read_b128 v[160:163], v238 offset:20480
	ds_read_b128 v[164:167], v238 offset:21504
	ds_read_b128 v[190:193], v238 offset:22528
	ds_read_b128 v[194:197], v238 offset:23552
	s_barrier
	s_waitcnt lgkmcnt(0)
	v_mfma_f32_16x16x32_bf16 v[100:103], v[48:51], v[124:127], 0
	v_mfma_f32_16x16x32_bf16 v[28:31], v[104:107], v[124:127], 0
	v_mfma_f32_16x16x32_bf16 v[96:99], v[48:51], v[140:143], 0
	v_mfma_f32_16x16x32_bf16 v[24:27], v[104:107], v[140:143], 0
	v_mfma_f32_16x16x32_bf16 v[84:87], v[48:51], v[160:163], 0
	v_mfma_f32_16x16x32_bf16 v[12:15], v[104:107], v[160:163], 0
	v_mfma_f32_16x16x32_bf16 v[8:11], v[104:107], v[190:193], 0
	v_mfma_f32_16x16x32_bf16 v[100:103], v[52:55], v[132:135], v[100:103]
	v_mfma_f32_16x16x32_bf16 v[28:31], v[108:111], v[132:135], v[28:31]
	v_mfma_f32_16x16x32_bf16 v[96:99], v[52:55], v[156:159], v[96:99]
	v_mfma_f32_16x16x32_bf16 v[24:27], v[108:111], v[156:159], v[24:27]
	v_mfma_f32_16x16x32_bf16 v[84:87], v[52:55], v[164:167], v[84:87]
	v_mfma_f32_16x16x32_bf16 v[12:15], v[108:111], v[164:167], v[12:15]
	v_mfma_f32_16x16x32_bf16 v[48:51], v[48:51], v[190:193], 0
	v_mfma_f32_16x16x32_bf16 v[8:11], v[108:111], v[194:197], v[8:11]
	v_mfma_f32_16x16x32_bf16 v[48:51], v[52:55], v[194:197], v[48:51]
	s_barrier
	s_mov_b32 m0, s54
	s_nop 0
	global_load_lds_dwordx4 v180, s[12:13]
	s_mov_b32 m0, s55
	s_nop 0
	global_load_lds_dwordx4 v182, s[12:13]
	s_add_i32 m0, s53, 0x14000
	s_add_u32 s68, s2, 0x40000
	s_addc_u32 s69, s3, 0
	global_load_lds_dwordx4 v168, s[68:69]
	s_add_i32 m0, s53, 0x16000
	s_add_u32 s12, s12, 0x40000
	s_addc_u32 s13, s13, 0
	global_load_lds_dwordx4 v184, s[68:69]
	s_waitcnt vmcnt(6)
	s_barrier
	v_mfma_f32_16x16x32_bf16 v[76:79], v[198:201], v[140:143], 0
	v_mfma_f32_16x16x32_bf16 v[20:23], v[206:209], v[124:127], 0
	v_mfma_f32_16x16x32_bf16 v[88:91], v[202:205], v[156:159], v[76:79]
	v_mfma_f32_16x16x32_bf16 v[16:19], v[206:209], v[140:143], 0
	v_mfma_f32_16x16x32_bf16 v[76:79], v[198:201], v[160:163], 0
	v_mfma_f32_16x16x32_bf16 v[4:7], v[206:209], v[160:163], 0
	v_mfma_f32_16x16x32_bf16 v[72:75], v[198:201], v[190:193], 0
	v_mfma_f32_16x16x32_bf16 v[0:3], v[206:209], v[190:193], 0
	v_mfma_f32_16x16x32_bf16 v[52:55], v[198:201], v[124:127], 0
	v_mfma_f32_16x16x32_bf16 v[20:23], v[210:213], v[132:135], v[20:23]
	v_mfma_f32_16x16x32_bf16 v[16:19], v[210:213], v[156:159], v[16:19]
	v_mfma_f32_16x16x32_bf16 v[80:83], v[202:205], v[164:167], v[76:79]
	v_mfma_f32_16x16x32_bf16 v[4:7], v[210:213], v[164:167], v[4:7]
	v_mfma_f32_16x16x32_bf16 v[72:75], v[202:205], v[194:197], v[72:75]
	v_mfma_f32_16x16x32_bf16 v[0:3], v[210:213], v[194:197], v[0:3]
	v_mfma_f32_16x16x32_bf16 v[52:55], v[202:205], v[132:135], v[52:55]
	s_barrier
	ds_read_b128 v[76:79], v237 offset:32768
	ds_read_b128 v[92:95], v237 offset:33792
	ds_read_b128 v[104:107], v237 offset:34816
	ds_read_b128 v[108:111], v237 offset:35840
	ds_read_b128 v[124:127], v238 offset:32768
	ds_read_b128 v[132:135], v238 offset:33792
	ds_read_b128 v[156:159], v238 offset:34816
	ds_read_b128 v[160:163], v238 offset:35840
	ds_read_b128 v[164:167], v238 offset:36864
	ds_read_b128 v[190:193], v238 offset:37888
	ds_read_b128 v[194:197], v238 offset:38912
	ds_read_b128 v[198:201], v238 offset:39936
	s_waitcnt lgkmcnt(8)
	s_barrier
	s_waitcnt lgkmcnt(0)
	v_mfma_f32_16x16x32_bf16 v[140:143], v[76:79], v[124:127], v[152:155]
	v_mfma_f32_16x16x32_bf16 v[152:155], v[92:95], v[132:135], v[140:143]
	v_mfma_f32_16x16x32_bf16 v[68:71], v[104:107], v[124:127], v[68:71]
	v_mfma_f32_16x16x32_bf16 v[140:143], v[76:79], v[156:159], v[148:151]
	v_mfma_f32_16x16x32_bf16 v[64:67], v[104:107], v[156:159], v[64:67]
	v_mfma_f32_16x16x32_bf16 v[136:139], v[76:79], v[164:167], v[136:139]
	v_mfma_f32_16x16x32_bf16 v[44:47], v[104:107], v[164:167], v[44:47]
	v_mfma_f32_16x16x32_bf16 v[128:131], v[76:79], v[194:197], v[128:131]
	v_mfma_f32_16x16x32_bf16 v[40:43], v[104:107], v[194:197], v[40:43]
	v_mfma_f32_16x16x32_bf16 v[68:71], v[108:111], v[132:135], v[68:71]
	v_mfma_f32_16x16x32_bf16 v[148:151], v[92:95], v[160:163], v[140:143]
	v_mfma_f32_16x16x32_bf16 v[64:67], v[108:111], v[160:163], v[64:67]
	v_mfma_f32_16x16x32_bf16 v[136:139], v[92:95], v[190:193], v[136:139]
	v_mfma_f32_16x16x32_bf16 v[44:47], v[108:111], v[190:193], v[44:47]
	v_mfma_f32_16x16x32_bf16 v[128:131], v[92:95], v[198:201], v[128:131]
	v_mfma_f32_16x16x32_bf16 v[40:43], v[108:111], v[198:201], v[40:43]
	s_barrier
	s_mov_b32 m0, s56
	ds_read_b128 v[202:205], v237 offset:49152
	ds_read_b128 v[206:209], v237 offset:50176
	ds_read_b128 v[210:213], v237 offset:51200
	global_load_lds_dwordx4 v180, s[12:13]
	s_mov_b32 m0, s57
	ds_read_b128 v[214:217], v237 offset:52224
	global_load_lds_dwordx4 v182, s[12:13]
	s_add_i32 m0, s53, 0x18000
	s_nop 0
	global_load_lds_dwordx4 v168, s[98:99]
	s_add_i32 m0, s53, 0x1a000
	s_nop 0
	global_load_lds_dwordx4 v184, s[98:99]
	s_barrier
	s_waitcnt lgkmcnt(0)
	v_mfma_f32_16x16x32_bf16 v[140:143], v[202:205], v[124:127], v[144:147]
	v_mfma_f32_16x16x32_bf16 v[112:115], v[202:205], v[156:159], v[112:115]
	v_mfma_f32_16x16x32_bf16 v[144:147], v[206:209], v[132:135], v[140:143]
	v_mfma_f32_16x16x32_bf16 v[60:63], v[210:213], v[124:127], v[60:63]
	v_mfma_f32_16x16x32_bf16 v[140:143], v[206:209], v[160:163], v[112:115]
	v_mfma_f32_16x16x32_bf16 v[112:115], v[202:205], v[164:167], v[116:119]
	v_mfma_f32_16x16x32_bf16 v[60:63], v[214:217], v[132:135], v[60:63]
	v_mfma_f32_16x16x32_bf16 v[56:59], v[210:213], v[156:159], v[56:59]
	v_mfma_f32_16x16x32_bf16 v[132:135], v[206:209], v[190:193], v[112:115]
	v_mfma_f32_16x16x32_bf16 v[36:39], v[210:213], v[164:167], v[36:39]
	v_mfma_f32_16x16x32_bf16 v[112:115], v[202:205], v[194:197], v[120:123]
	v_mfma_f32_16x16x32_bf16 v[32:35], v[210:213], v[194:197], v[32:35]
	v_mfma_f32_16x16x32_bf16 v[56:59], v[214:217], v[160:163], v[56:59]
	v_mfma_f32_16x16x32_bf16 v[36:39], v[214:217], v[190:193], v[36:39]
	v_mfma_f32_16x16x32_bf16 v[124:127], v[206:209], v[198:201], v[112:115]
	v_mfma_f32_16x16x32_bf16 v[32:35], v[214:217], v[198:201], v[32:35]
	s_barrier
	ds_read_b128 v[112:115], v238 offset:49152
	ds_read_b128 v[116:119], v238 offset:50176
	ds_read_b128 v[120:123], v238 offset:51200
	ds_read_b128 v[156:159], v238 offset:52224
	ds_read_b128 v[160:163], v238 offset:53248
	ds_read_b128 v[164:167], v238 offset:54272
	ds_read_b128 v[190:193], v238 offset:55296
	ds_read_b128 v[194:197], v238 offset:56320
	s_barrier
	s_waitcnt lgkmcnt(0)
	v_mfma_f32_16x16x32_bf16 v[100:103], v[76:79], v[112:115], v[100:103]
	v_mfma_f32_16x16x32_bf16 v[28:31], v[104:107], v[112:115], v[28:31]
	v_mfma_f32_16x16x32_bf16 v[96:99], v[76:79], v[120:123], v[96:99]
	v_mfma_f32_16x16x32_bf16 v[24:27], v[104:107], v[120:123], v[24:27]
	v_mfma_f32_16x16x32_bf16 v[84:87], v[76:79], v[160:163], v[84:87]
	v_mfma_f32_16x16x32_bf16 v[12:15], v[104:107], v[160:163], v[12:15]
	v_mfma_f32_16x16x32_bf16 v[48:51], v[76:79], v[190:193], v[48:51]
	v_mfma_f32_16x16x32_bf16 v[8:11], v[104:107], v[190:193], v[8:11]
	v_mfma_f32_16x16x32_bf16 v[100:103], v[92:95], v[116:119], v[100:103]
	v_mfma_f32_16x16x32_bf16 v[28:31], v[108:111], v[116:119], v[28:31]
	v_mfma_f32_16x16x32_bf16 v[96:99], v[92:95], v[156:159], v[96:99]
	v_mfma_f32_16x16x32_bf16 v[24:27], v[108:111], v[156:159], v[24:27]
	v_mfma_f32_16x16x32_bf16 v[84:87], v[92:95], v[164:167], v[84:87]
	v_mfma_f32_16x16x32_bf16 v[12:15], v[108:111], v[164:167], v[12:15]
	v_mfma_f32_16x16x32_bf16 v[76:79], v[92:95], v[194:197], v[48:51]
	v_mfma_f32_16x16x32_bf16 v[8:11], v[108:111], v[194:197], v[8:11]
	s_barrier
	s_mov_b32 m0, s62
	s_nop 0
	global_load_lds_dwordx4 v180, s[100:101]
	s_mov_b32 m0, s63
	s_nop 0
	global_load_lds_dwordx4 v182, s[100:101]
	s_add_i32 m0, s53, 0x1c000
	s_add_u32 s2, s2, 0x40080
	s_addc_u32 s3, s3, 0
	global_load_lds_dwordx4 v168, s[2:3]
	s_add_i32 m0, s53, 0x1e000
	s_add_i32 s67, s67, 2
	global_load_lds_dwordx4 v184, s[2:3]
	s_waitcnt vmcnt(6)
	s_barrier
	v_mfma_f32_16x16x32_bf16 v[48:51], v[202:205], v[112:115], v[52:55]
	v_mfma_f32_16x16x32_bf16 v[92:95], v[206:209], v[116:119], v[48:51]
	v_mfma_f32_16x16x32_bf16 v[48:51], v[202:205], v[120:123], v[88:91]
	v_mfma_f32_16x16x32_bf16 v[88:91], v[206:209], v[156:159], v[48:51]
	v_mfma_f32_16x16x32_bf16 v[48:51], v[202:205], v[160:163], v[80:83]
	v_mfma_f32_16x16x32_bf16 v[20:23], v[210:213], v[112:115], v[20:23]
	v_mfma_f32_16x16x32_bf16 v[16:19], v[210:213], v[120:123], v[16:19]
	v_mfma_f32_16x16x32_bf16 v[80:83], v[206:209], v[164:167], v[48:51]
	v_mfma_f32_16x16x32_bf16 v[4:7], v[210:213], v[160:163], v[4:7]
	v_mfma_f32_16x16x32_bf16 v[48:51], v[202:205], v[190:193], v[72:75]
	v_mfma_f32_16x16x32_bf16 v[0:3], v[210:213], v[190:193], v[0:3]
	v_mfma_f32_16x16x32_bf16 v[20:23], v[214:217], v[116:119], v[20:23]
	v_mfma_f32_16x16x32_bf16 v[16:19], v[214:217], v[156:159], v[16:19]
	v_mfma_f32_16x16x32_bf16 v[4:7], v[214:217], v[164:167], v[4:7]
	v_mfma_f32_16x16x32_bf16 v[72:75], v[206:209], v[194:197], v[48:51]
	v_mfma_f32_16x16x32_bf16 v[0:3], v[214:217], v[194:197], v[0:3]
	s_add_u32 s10, s10, 0x100
	s_addc_u32 s11, s11, 0
	s_add_u32 s37, s37, 0x100
	s_addc_u32 s39, s39, 0
	s_cmp_gt_u32 s67, 13
	s_barrier
.LBB0_880:
	s_add_u32 s2, s10, 0xfffc0080
	s_addc_u32 s3, s11, -1
	ds_read_b128 v[48:51], v237
	ds_read_b128 v[52:55], v237 offset:1024
	ds_read_b128 v[104:107], v237 offset:2048
	ds_read_b128 v[108:111], v237 offset:3072
	s_cmp_eq_u32 s67, 12
	s_cselect_b32 s13, s1, s3
	s_cselect_b32 s12, s9, s2
	s_cselect_b32 s3, s14, s39
	s_cselect_b32 s2, s15, s37
	ds_read_b128 v[112:115], v238
	ds_read_b128 v[116:119], v238 offset:1024
	ds_read_b128 v[120:123], v238 offset:2048
	ds_read_b128 v[156:159], v238 offset:3072
	ds_read_b128 v[160:163], v238 offset:4096
	ds_read_b128 v[164:167], v238 offset:5120
	ds_read_b128 v[190:193], v238 offset:6144
	ds_read_b128 v[194:197], v238 offset:7168
	s_waitcnt lgkmcnt(8)
	s_barrier
	s_waitcnt lgkmcnt(0)
	v_mfma_f32_16x16x32_bf16 v[152:155], v[48:51], v[112:115], v[152:155]
	v_mfma_f32_16x16x32_bf16 v[68:71], v[104:107], v[112:115], v[68:71]
	v_mfma_f32_16x16x32_bf16 v[148:151], v[48:51], v[120:123], v[148:151]
	v_mfma_f32_16x16x32_bf16 v[64:67], v[104:107], v[120:123], v[64:67]
	v_mfma_f32_16x16x32_bf16 v[136:139], v[48:51], v[160:163], v[136:139]
	v_mfma_f32_16x16x32_bf16 v[44:47], v[104:107], v[160:163], v[44:47]
	v_mfma_f32_16x16x32_bf16 v[128:131], v[48:51], v[190:193], v[128:131]
	v_mfma_f32_16x16x32_bf16 v[40:43], v[104:107], v[190:193], v[40:43]
	v_mfma_f32_16x16x32_bf16 v[152:155], v[52:55], v[116:119], v[152:155]
	v_mfma_f32_16x16x32_bf16 v[68:71], v[108:111], v[116:119], v[68:71]
	v_mfma_f32_16x16x32_bf16 v[148:151], v[52:55], v[156:159], v[148:151]
	v_mfma_f32_16x16x32_bf16 v[64:67], v[108:111], v[156:159], v[64:67]
	v_mfma_f32_16x16x32_bf16 v[136:139], v[52:55], v[164:167], v[136:139]
	v_mfma_f32_16x16x32_bf16 v[44:47], v[108:111], v[164:167], v[44:47]
	v_mfma_f32_16x16x32_bf16 v[128:131], v[52:55], v[194:197], v[128:131]
	v_mfma_f32_16x16x32_bf16 v[40:43], v[108:111], v[194:197], v[40:43]
	s_barrier
	s_add_i32 m0, s54, 0xc000
	ds_read_b128 v[198:201], v237 offset:16384
	ds_read_b128 v[202:205], v237 offset:17408
	ds_read_b128 v[206:209], v237 offset:18432
	global_load_lds_dwordx4 v186, s[10:11]
	s_add_i32 m0, s54, 0xe000
	ds_read_b128 v[210:213], v237 offset:19456
	global_load_lds_dwordx4 v188, s[10:11]
	s_add_u32 s98, s2, 0x80
	s_addc_u32 s99, s3, 0
	s_add_i32 m0, s53, 0x10000
	s_nop 0
	global_load_lds_dwordx4 v168, s[2:3]
	s_add_i32 m0, s53, 0x12000
	s_nop 0
	global_load_lds_dwordx4 v184, s[2:3]
	s_barrier
	s_waitcnt lgkmcnt(0)
	v_mfma_f32_16x16x32_bf16 v[144:147], v[198:201], v[112:115], v[144:147]
	v_mfma_f32_16x16x32_bf16 v[60:63], v[206:209], v[112:115], v[60:63]
	v_mfma_f32_16x16x32_bf16 v[56:59], v[206:209], v[120:123], v[56:59]
	v_mfma_f32_16x16x32_bf16 v[36:39], v[206:209], v[160:163], v[36:39]
	v_mfma_f32_16x16x32_bf16 v[32:35], v[206:209], v[190:193], v[32:35]
	v_mfma_f32_16x16x32_bf16 v[144:147], v[202:205], v[116:119], v[144:147]
	v_mfma_f32_16x16x32_bf16 v[60:63], v[210:213], v[116:119], v[60:63]
	v_mfma_f32_16x16x32_bf16 v[112:115], v[198:201], v[120:123], v[140:143]
	v_mfma_f32_16x16x32_bf16 v[56:59], v[210:213], v[156:159], v[56:59]
	v_mfma_f32_16x16x32_bf16 v[116:119], v[198:201], v[160:163], v[132:135]
	v_mfma_f32_16x16x32_bf16 v[36:39], v[210:213], v[164:167], v[36:39]
	v_mfma_f32_16x16x32_bf16 v[120:123], v[198:201], v[190:193], v[124:127]
	v_mfma_f32_16x16x32_bf16 v[32:35], v[210:213], v[194:197], v[32:35]
	v_mfma_f32_16x16x32_bf16 v[112:115], v[202:205], v[156:159], v[112:115]
	v_mfma_f32_16x16x32_bf16 v[116:119], v[202:205], v[164:167], v[116:119]
	v_mfma_f32_16x16x32_bf16 v[120:123], v[202:205], v[194:197], v[120:123]
	s_add_u32 s100, s12, 0x80
	s_addc_u32 s101, s13, 0
	s_barrier
	ds_read_b128 v[124:127], v238 offset:16384
	ds_read_b128 v[132:135], v238 offset:17408
	ds_read_b128 v[140:143], v238 offset:18432
	ds_read_b128 v[156:159], v238 offset:19456
	ds_read_b128 v[160:163], v238 offset:20480
	ds_read_b128 v[164:167], v238 offset:21504
	ds_read_b128 v[190:193], v238 offset:22528
	ds_read_b128 v[194:197], v238 offset:23552
	s_barrier
	s_waitcnt lgkmcnt(0)
	v_mfma_f32_16x16x32_bf16 v[100:103], v[48:51], v[124:127], v[100:103]
	v_mfma_f32_16x16x32_bf16 v[28:31], v[104:107], v[124:127], v[28:31]
	v_mfma_f32_16x16x32_bf16 v[96:99], v[48:51], v[140:143], v[96:99]
	v_mfma_f32_16x16x32_bf16 v[24:27], v[104:107], v[140:143], v[24:27]
	v_mfma_f32_16x16x32_bf16 v[84:87], v[48:51], v[160:163], v[84:87]
	v_mfma_f32_16x16x32_bf16 v[12:15], v[104:107], v[160:163], v[12:15]
	v_mfma_f32_16x16x32_bf16 v[8:11], v[104:107], v[190:193], v[8:11]
	v_mfma_f32_16x16x32_bf16 v[100:103], v[52:55], v[132:135], v[100:103]
	v_mfma_f32_16x16x32_bf16 v[28:31], v[108:111], v[132:135], v[28:31]
	v_mfma_f32_16x16x32_bf16 v[96:99], v[52:55], v[156:159], v[96:99]
	v_mfma_f32_16x16x32_bf16 v[24:27], v[108:111], v[156:159], v[24:27]
	v_mfma_f32_16x16x32_bf16 v[84:87], v[52:55], v[164:167], v[84:87]
	v_mfma_f32_16x16x32_bf16 v[12:15], v[108:111], v[164:167], v[12:15]
	v_mfma_f32_16x16x32_bf16 v[48:51], v[48:51], v[190:193], v[76:79]
	v_mfma_f32_16x16x32_bf16 v[8:11], v[108:111], v[194:197], v[8:11]
	v_mfma_f32_16x16x32_bf16 v[48:51], v[52:55], v[194:197], v[48:51]
	s_barrier
	s_mov_b32 m0, s54
	s_nop 0
	global_load_lds_dwordx4 v180, s[12:13]
	s_mov_b32 m0, s55
	s_nop 0
	global_load_lds_dwordx4 v182, s[12:13]
	s_add_i32 m0, s53, 0x14000
	s_add_u32 s68, s2, 0x40000
	s_addc_u32 s69, s3, 0
	global_load_lds_dwordx4 v168, s[68:69]
	s_add_i32 m0, s53, 0x16000
	s_add_u32 s12, s12, 0x40000
	s_addc_u32 s13, s13, 0
	global_load_lds_dwordx4 v184, s[68:69]
	s_waitcnt vmcnt(6)
	s_barrier
	v_mfma_f32_16x16x32_bf16 v[76:79], v[198:201], v[140:143], v[88:91]
	v_mfma_f32_16x16x32_bf16 v[20:23], v[206:209], v[124:127], v[20:23]
	v_mfma_f32_16x16x32_bf16 v[88:91], v[202:205], v[156:159], v[76:79]
	v_mfma_f32_16x16x32_bf16 v[16:19], v[206:209], v[140:143], v[16:19]
	v_mfma_f32_16x16x32_bf16 v[76:79], v[198:201], v[160:163], v[80:83]
	v_mfma_f32_16x16x32_bf16 v[4:7], v[206:209], v[160:163], v[4:7]
	v_mfma_f32_16x16x32_bf16 v[72:75], v[198:201], v[190:193], v[72:75]
	v_mfma_f32_16x16x32_bf16 v[0:3], v[206:209], v[190:193], v[0:3]
	v_mfma_f32_16x16x32_bf16 v[52:55], v[198:201], v[124:127], v[92:95]
	v_mfma_f32_16x16x32_bf16 v[20:23], v[210:213], v[132:135], v[20:23]
	v_mfma_f32_16x16x32_bf16 v[16:19], v[210:213], v[156:159], v[16:19]
	v_mfma_f32_16x16x32_bf16 v[80:83], v[202:205], v[164:167], v[76:79]
	v_mfma_f32_16x16x32_bf16 v[4:7], v[210:213], v[164:167], v[4:7]
	v_mfma_f32_16x16x32_bf16 v[72:75], v[202:205], v[194:197], v[72:75]
	v_mfma_f32_16x16x32_bf16 v[0:3], v[210:213], v[194:197], v[0:3]
	v_mfma_f32_16x16x32_bf16 v[52:55], v[202:205], v[132:135], v[52:55]
	s_barrier
	ds_read_b128 v[76:79], v237 offset:32768
	ds_read_b128 v[92:95], v237 offset:33792
	ds_read_b128 v[104:107], v237 offset:34816
	ds_read_b128 v[108:111], v237 offset:35840
	ds_read_b128 v[124:127], v238 offset:32768
	ds_read_b128 v[132:135], v238 offset:33792
	ds_read_b128 v[156:159], v238 offset:34816
	ds_read_b128 v[160:163], v238 offset:35840
	ds_read_b128 v[164:167], v238 offset:36864
	ds_read_b128 v[190:193], v238 offset:37888
	ds_read_b128 v[194:197], v238 offset:38912
	ds_read_b128 v[198:201], v238 offset:39936
	s_waitcnt lgkmcnt(8)
	s_barrier
	s_waitcnt lgkmcnt(0)
	v_mfma_f32_16x16x32_bf16 v[140:143], v[76:79], v[124:127], v[152:155]
	v_mfma_f32_16x16x32_bf16 v[152:155], v[92:95], v[132:135], v[140:143]
	v_mfma_f32_16x16x32_bf16 v[68:71], v[104:107], v[124:127], v[68:71]
	v_mfma_f32_16x16x32_bf16 v[140:143], v[76:79], v[156:159], v[148:151]
	v_mfma_f32_16x16x32_bf16 v[64:67], v[104:107], v[156:159], v[64:67]
	v_mfma_f32_16x16x32_bf16 v[136:139], v[76:79], v[164:167], v[136:139]
	v_mfma_f32_16x16x32_bf16 v[44:47], v[104:107], v[164:167], v[44:47]
	v_mfma_f32_16x16x32_bf16 v[128:131], v[76:79], v[194:197], v[128:131]
	v_mfma_f32_16x16x32_bf16 v[40:43], v[104:107], v[194:197], v[40:43]
	v_mfma_f32_16x16x32_bf16 v[68:71], v[108:111], v[132:135], v[68:71]
	v_mfma_f32_16x16x32_bf16 v[148:151], v[92:95], v[160:163], v[140:143]
	v_mfma_f32_16x16x32_bf16 v[64:67], v[108:111], v[160:163], v[64:67]
	v_mfma_f32_16x16x32_bf16 v[136:139], v[92:95], v[190:193], v[136:139]
	v_mfma_f32_16x16x32_bf16 v[44:47], v[108:111], v[190:193], v[44:47]
	v_mfma_f32_16x16x32_bf16 v[128:131], v[92:95], v[198:201], v[128:131]
	v_mfma_f32_16x16x32_bf16 v[40:43], v[108:111], v[198:201], v[40:43]
	s_barrier
	s_mov_b32 m0, s56
	ds_read_b128 v[202:205], v237 offset:49152
	ds_read_b128 v[206:209], v237 offset:50176
	ds_read_b128 v[210:213], v237 offset:51200
	global_load_lds_dwordx4 v180, s[12:13]
	s_mov_b32 m0, s57
	ds_read_b128 v[214:217], v237 offset:52224
	global_load_lds_dwordx4 v182, s[12:13]
	s_add_i32 m0, s53, 0x18000
	s_nop 0
	global_load_lds_dwordx4 v168, s[98:99]
	s_add_i32 m0, s53, 0x1a000
	s_nop 0
	global_load_lds_dwordx4 v184, s[98:99]
	s_barrier
	s_waitcnt lgkmcnt(0)
	v_mfma_f32_16x16x32_bf16 v[140:143], v[202:205], v[124:127], v[144:147]
	v_mfma_f32_16x16x32_bf16 v[112:115], v[202:205], v[156:159], v[112:115]
	v_mfma_f32_16x16x32_bf16 v[144:147], v[206:209], v[132:135], v[140:143]
	v_mfma_f32_16x16x32_bf16 v[60:63], v[210:213], v[124:127], v[60:63]
	v_mfma_f32_16x16x32_bf16 v[140:143], v[206:209], v[160:163], v[112:115]
	v_mfma_f32_16x16x32_bf16 v[112:115], v[202:205], v[164:167], v[116:119]
	v_mfma_f32_16x16x32_bf16 v[60:63], v[214:217], v[132:135], v[60:63]
	v_mfma_f32_16x16x32_bf16 v[56:59], v[210:213], v[156:159], v[56:59]
	v_mfma_f32_16x16x32_bf16 v[132:135], v[206:209], v[190:193], v[112:115]
	v_mfma_f32_16x16x32_bf16 v[36:39], v[210:213], v[164:167], v[36:39]
	v_mfma_f32_16x16x32_bf16 v[112:115], v[202:205], v[194:197], v[120:123]
	v_mfma_f32_16x16x32_bf16 v[32:35], v[210:213], v[194:197], v[32:35]
	v_mfma_f32_16x16x32_bf16 v[56:59], v[214:217], v[160:163], v[56:59]
	v_mfma_f32_16x16x32_bf16 v[36:39], v[214:217], v[190:193], v[36:39]
	v_mfma_f32_16x16x32_bf16 v[124:127], v[206:209], v[198:201], v[112:115]
	v_mfma_f32_16x16x32_bf16 v[32:35], v[214:217], v[198:201], v[32:35]
	s_barrier
	ds_read_b128 v[112:115], v238 offset:49152
	ds_read_b128 v[116:119], v238 offset:50176
	ds_read_b128 v[120:123], v238 offset:51200
	ds_read_b128 v[156:159], v238 offset:52224
	ds_read_b128 v[160:163], v238 offset:53248
	ds_read_b128 v[164:167], v238 offset:54272
	ds_read_b128 v[190:193], v238 offset:55296
	ds_read_b128 v[194:197], v238 offset:56320
	s_barrier
	s_waitcnt lgkmcnt(0)
	v_mfma_f32_16x16x32_bf16 v[100:103], v[76:79], v[112:115], v[100:103]
	v_mfma_f32_16x16x32_bf16 v[28:31], v[104:107], v[112:115], v[28:31]
	v_mfma_f32_16x16x32_bf16 v[96:99], v[76:79], v[120:123], v[96:99]
	v_mfma_f32_16x16x32_bf16 v[24:27], v[104:107], v[120:123], v[24:27]
	v_mfma_f32_16x16x32_bf16 v[84:87], v[76:79], v[160:163], v[84:87]
	v_mfma_f32_16x16x32_bf16 v[12:15], v[104:107], v[160:163], v[12:15]
	v_mfma_f32_16x16x32_bf16 v[48:51], v[76:79], v[190:193], v[48:51]
	v_mfma_f32_16x16x32_bf16 v[8:11], v[104:107], v[190:193], v[8:11]
	v_mfma_f32_16x16x32_bf16 v[100:103], v[92:95], v[116:119], v[100:103]
	v_mfma_f32_16x16x32_bf16 v[28:31], v[108:111], v[116:119], v[28:31]
	v_mfma_f32_16x16x32_bf16 v[96:99], v[92:95], v[156:159], v[96:99]
	v_mfma_f32_16x16x32_bf16 v[24:27], v[108:111], v[156:159], v[24:27]
	v_mfma_f32_16x16x32_bf16 v[84:87], v[92:95], v[164:167], v[84:87]
	v_mfma_f32_16x16x32_bf16 v[12:15], v[108:111], v[164:167], v[12:15]
	v_mfma_f32_16x16x32_bf16 v[76:79], v[92:95], v[194:197], v[48:51]
	v_mfma_f32_16x16x32_bf16 v[8:11], v[108:111], v[194:197], v[8:11]
	s_barrier
	s_mov_b32 m0, s62
	s_nop 0
	global_load_lds_dwordx4 v180, s[100:101]
	s_mov_b32 m0, s63
	s_nop 0
	global_load_lds_dwordx4 v182, s[100:101]
	s_add_i32 m0, s53, 0x1c000
	s_add_u32 s2, s2, 0x40080
	s_addc_u32 s3, s3, 0
	global_load_lds_dwordx4 v168, s[2:3]
	s_add_i32 m0, s53, 0x1e000
	s_add_i32 s67, s67, 2
	global_load_lds_dwordx4 v184, s[2:3]
	s_waitcnt vmcnt(6)
	s_barrier
	v_mfma_f32_16x16x32_bf16 v[48:51], v[202:205], v[112:115], v[52:55]
	v_mfma_f32_16x16x32_bf16 v[92:95], v[206:209], v[116:119], v[48:51]
	v_mfma_f32_16x16x32_bf16 v[48:51], v[202:205], v[120:123], v[88:91]
	v_mfma_f32_16x16x32_bf16 v[88:91], v[206:209], v[156:159], v[48:51]
	v_mfma_f32_16x16x32_bf16 v[48:51], v[202:205], v[160:163], v[80:83]
	v_mfma_f32_16x16x32_bf16 v[20:23], v[210:213], v[112:115], v[20:23]
	v_mfma_f32_16x16x32_bf16 v[16:19], v[210:213], v[120:123], v[16:19]
	v_mfma_f32_16x16x32_bf16 v[80:83], v[206:209], v[164:167], v[48:51]
	v_mfma_f32_16x16x32_bf16 v[4:7], v[210:213], v[160:163], v[4:7]
	v_mfma_f32_16x16x32_bf16 v[48:51], v[202:205], v[190:193], v[72:75]
	v_mfma_f32_16x16x32_bf16 v[0:3], v[210:213], v[190:193], v[0:3]
	v_mfma_f32_16x16x32_bf16 v[20:23], v[214:217], v[116:119], v[20:23]
	v_mfma_f32_16x16x32_bf16 v[16:19], v[214:217], v[156:159], v[16:19]
	v_mfma_f32_16x16x32_bf16 v[4:7], v[214:217], v[164:167], v[4:7]
	v_mfma_f32_16x16x32_bf16 v[72:75], v[206:209], v[194:197], v[48:51]
	v_mfma_f32_16x16x32_bf16 v[0:3], v[214:217], v[194:197], v[0:3]
	s_add_u32 s10, s10, 0x100
	s_addc_u32 s11, s11, 0
	s_add_u32 s37, s37, 0x100
	s_addc_u32 s39, s39, 0
	s_cmp_gt_u32 s67, 13
	s_barrier
	s_cbranch_scc0 .LBB0_880

.LBB0_1048:
	s_add_u32 s56, s2, 0x100
	s_addc_u32 s57, s3, 0
	s_mov_b32 s58, -2
	s_add_u32 s2, s24, 0x100
	s_addc_u32 s3, s25, 0
	ds_read_b128 v[40:43], v194
	ds_read_b128 v[44:47], v194 offset:1024
	ds_read_b128 v[48:51], v194 offset:2048
	ds_read_b128 v[52:55], v194 offset:3072
	s_cmp_eq_u32 s58, 40
	s_cselect_b32 s27, s1, s3
	s_cselect_b32 s26, s0, s2
	s_cselect_b32 s9, s23, s57
	s_cselect_b32 s8, s22, s56
	ds_read_b128 v[56:59], v195
	ds_read_b128 v[60:63], v195 offset:1024
	ds_read_b128 v[72:75], v195 offset:2048
	ds_read_b128 v[84:87], v195 offset:3072
	ds_read_b128 v[182:185], v195 offset:4096
	ds_read_b128 v[186:189], v195 offset:5120
	ds_read_b128 v[196:199], v195 offset:6144
	ds_read_b128 v[200:203], v195 offset:7168
	s_waitcnt lgkmcnt(8)
	s_barrier
	s_waitcnt lgkmcnt(0)
	v_mfma_f32_16x16x32_bf16 v[156:159], v[40:43], v[56:59], 0
	v_mfma_f32_16x16x32_bf16 v[152:155], v[48:51], v[56:59], 0
	v_mfma_f32_16x16x32_bf16 v[140:143], v[40:43], v[72:75], 0
	v_mfma_f32_16x16x32_bf16 v[136:139], v[48:51], v[72:75], 0
	v_mfma_f32_16x16x32_bf16 v[124:127], v[40:43], v[182:185], 0
	v_mfma_f32_16x16x32_bf16 v[120:123], v[48:51], v[182:185], 0
	v_mfma_f32_16x16x32_bf16 v[108:111], v[40:43], v[196:199], 0
	v_mfma_f32_16x16x32_bf16 v[104:107], v[48:51], v[196:199], 0
	v_mfma_f32_16x16x32_bf16 v[156:159], v[44:47], v[60:63], v[156:159]
	v_mfma_f32_16x16x32_bf16 v[152:155], v[52:55], v[60:63], v[152:155]
	v_mfma_f32_16x16x32_bf16 v[140:143], v[44:47], v[84:87], v[140:143]
	v_mfma_f32_16x16x32_bf16 v[136:139], v[52:55], v[84:87], v[136:139]
	v_mfma_f32_16x16x32_bf16 v[124:127], v[44:47], v[186:189], v[124:127]
	v_mfma_f32_16x16x32_bf16 v[120:123], v[52:55], v[186:189], v[120:123]
	v_mfma_f32_16x16x32_bf16 v[108:111], v[44:47], v[200:203], v[108:111]
	v_mfma_f32_16x16x32_bf16 v[104:107], v[52:55], v[200:203], v[104:107]
	s_barrier
	s_add_i32 m0, s37, 0xc000
	ds_read_b128 v[204:207], v194 offset:16384
	ds_read_b128 v[208:211], v194 offset:17408
	ds_read_b128 v[212:215], v194 offset:18432
	global_load_lds_dwordx4 v166, s[24:25]
	s_add_i32 m0, s37, 0xe000
	ds_read_b128 v[216:219], v194 offset:19456
	global_load_lds_dwordx4 v180, s[24:25]
	s_add_u32 s98, s8, 0x80
	s_addc_u32 s99, s9, 0
	s_add_i32 m0, s36, 0x10000
	s_nop 0
	global_load_lds_dwordx4 v168, s[8:9]
	s_add_i32 m0, s36, 0x12000
	s_nop 0
	global_load_lds_dwordx4 v164, s[8:9]
	s_barrier
	s_waitcnt lgkmcnt(0)
	v_mfma_f32_16x16x32_bf16 v[148:151], v[204:207], v[56:59], 0
	v_mfma_f32_16x16x32_bf16 v[56:59], v[212:215], v[56:59], 0
	v_mfma_f32_16x16x32_bf16 v[148:151], v[208:211], v[60:63], v[148:151]
	v_mfma_f32_16x16x32_bf16 v[56:59], v[216:219], v[60:63], v[56:59]
	v_mfma_f32_16x16x32_bf16 v[60:63], v[204:207], v[72:75], 0
	v_mfma_f32_16x16x32_bf16 v[72:75], v[212:215], v[72:75], 0
	v_mfma_f32_16x16x32_bf16 v[112:115], v[212:215], v[182:185], 0
	v_mfma_f32_16x16x32_bf16 v[100:103], v[204:207], v[196:199], 0
	v_mfma_f32_16x16x32_bf16 v[96:99], v[212:215], v[196:199], 0
	v_mfma_f32_16x16x32_bf16 v[60:63], v[208:211], v[84:87], v[60:63]
	v_mfma_f32_16x16x32_bf16 v[72:75], v[216:219], v[84:87], v[72:75]
	v_mfma_f32_16x16x32_bf16 v[84:87], v[204:207], v[182:185], 0
	v_mfma_f32_16x16x32_bf16 v[112:115], v[216:219], v[186:189], v[112:115]
	v_mfma_f32_16x16x32_bf16 v[100:103], v[208:211], v[200:203], v[100:103]
	v_mfma_f32_16x16x32_bf16 v[96:99], v[216:219], v[200:203], v[96:99]
	v_mfma_f32_16x16x32_bf16 v[84:87], v[208:211], v[186:189], v[84:87]
	s_add_u32 s100, s26, 0x80
	s_addc_u32 s101, s27, 0
	s_barrier
	ds_read_b128 v[116:119], v195 offset:16384
	ds_read_b128 v[128:131], v195 offset:17408
	ds_read_b128 v[132:135], v195 offset:18432
	ds_read_b128 v[144:147], v195 offset:19456
	ds_read_b128 v[182:185], v195 offset:20480
	ds_read_b128 v[186:189], v195 offset:21504
	ds_read_b128 v[196:199], v195 offset:22528
	ds_read_b128 v[200:203], v195 offset:23552
	s_barrier
	s_waitcnt lgkmcnt(0)
	v_mfma_f32_16x16x32_bf16 v[92:95], v[40:43], v[116:119], 0
	v_mfma_f32_16x16x32_bf16 v[88:91], v[48:51], v[116:119], 0
	v_mfma_f32_16x16x32_bf16 v[68:71], v[40:43], v[132:135], 0
	v_mfma_f32_16x16x32_bf16 v[64:67], v[48:51], v[132:135], 0
	v_mfma_f32_16x16x32_bf16 v[28:31], v[40:43], v[182:185], 0
	v_mfma_f32_16x16x32_bf16 v[24:27], v[48:51], v[182:185], 0
	v_mfma_f32_16x16x32_bf16 v[12:15], v[40:43], v[196:199], 0
	v_mfma_f32_16x16x32_bf16 v[8:11], v[48:51], v[196:199], 0
	v_mfma_f32_16x16x32_bf16 v[92:95], v[44:47], v[128:131], v[92:95]
	v_mfma_f32_16x16x32_bf16 v[88:91], v[52:55], v[128:131], v[88:91]
	v_mfma_f32_16x16x32_bf16 v[68:71], v[44:47], v[144:147], v[68:71]
	v_mfma_f32_16x16x32_bf16 v[64:67], v[52:55], v[144:147], v[64:67]
	v_mfma_f32_16x16x32_bf16 v[28:31], v[44:47], v[186:189], v[28:31]
	v_mfma_f32_16x16x32_bf16 v[24:27], v[52:55], v[186:189], v[24:27]
	v_mfma_f32_16x16x32_bf16 v[12:15], v[44:47], v[200:203], v[12:15]
	v_mfma_f32_16x16x32_bf16 v[8:11], v[52:55], v[200:203], v[8:11]
	s_barrier
	s_mov_b32 m0, s37
	s_nop 0
	global_load_lds_dwordx4 v160, s[26:27]
	s_mov_b32 m0, s38
	s_nop 0
	global_load_lds_dwordx4 v162, s[26:27]
	s_add_i32 m0, s36, 0x14000
	s_add_u32 s24, s8, 0xb0000
	s_addc_u32 s25, s9, 0
	global_load_lds_dwordx4 v168, s[24:25]
	s_add_i32 m0, s36, 0x16000
	s_nop 0
	global_load_lds_dwordx4 v164, s[24:25]
	s_waitcnt vmcnt(6)
	s_barrier
	v_mfma_f32_16x16x32_bf16 v[36:39], v[204:207], v[132:135], 0
	v_mfma_f32_16x16x32_bf16 v[32:35], v[212:215], v[132:135], 0
	v_mfma_f32_16x16x32_bf16 v[20:23], v[204:207], v[182:185], 0
	v_mfma_f32_16x16x32_bf16 v[16:19], v[212:215], v[182:185], 0
	v_mfma_f32_16x16x32_bf16 v[4:7], v[204:207], v[196:199], 0
	v_mfma_f32_16x16x32_bf16 v[0:3], v[212:215], v[196:199], 0
	v_mfma_f32_16x16x32_bf16 v[40:43], v[204:207], v[116:119], 0
	v_mfma_f32_16x16x32_bf16 v[44:47], v[212:215], v[116:119], 0
	v_mfma_f32_16x16x32_bf16 v[36:39], v[208:211], v[144:147], v[36:39]
	v_mfma_f32_16x16x32_bf16 v[32:35], v[216:219], v[144:147], v[32:35]
	v_mfma_f32_16x16x32_bf16 v[20:23], v[208:211], v[186:189], v[20:23]
	v_mfma_f32_16x16x32_bf16 v[16:19], v[216:219], v[186:189], v[16:19]
	v_mfma_f32_16x16x32_bf16 v[4:7], v[208:211], v[200:203], v[4:7]
	v_mfma_f32_16x16x32_bf16 v[0:3], v[216:219], v[200:203], v[0:3]
	v_mfma_f32_16x16x32_bf16 v[40:43], v[208:211], v[128:131], v[40:43]
	v_mfma_f32_16x16x32_bf16 v[44:47], v[216:219], v[128:131], v[44:47]
	s_barrier
	ds_read_b128 v[48:51], v194 offset:32768
	ds_read_b128 v[52:55], v194 offset:33792
	ds_read_b128 v[76:79], v194 offset:34816
	ds_read_b128 v[80:83], v194 offset:35840
	s_add_u32 s24, s26, 0xb0000
	s_addc_u32 s25, s27, 0
	ds_read_b128 v[116:119], v195 offset:32768
	ds_read_b128 v[128:131], v195 offset:33792
	ds_read_b128 v[182:185], v195 offset:34816
	ds_read_b128 v[186:189], v195 offset:35840
	ds_read_b128 v[196:199], v195 offset:36864
	ds_read_b128 v[200:203], v195 offset:37888
	ds_read_b128 v[204:207], v195 offset:38912
	ds_read_b128 v[208:211], v195 offset:39936
	s_waitcnt lgkmcnt(8)
	s_barrier
	s_waitcnt lgkmcnt(0)
	v_mfma_f32_16x16x32_bf16 v[132:135], v[48:51], v[116:119], v[156:159]
	v_mfma_f32_16x16x32_bf16 v[156:159], v[52:55], v[128:131], v[132:135]
	v_mfma_f32_16x16x32_bf16 v[132:135], v[76:79], v[116:119], v[152:155]
	v_mfma_f32_16x16x32_bf16 v[152:155], v[80:83], v[128:131], v[132:135]
	v_mfma_f32_16x16x32_bf16 v[132:135], v[48:51], v[182:185], v[140:143]
	v_mfma_f32_16x16x32_bf16 v[140:143], v[52:55], v[186:189], v[132:135]
	v_mfma_f32_16x16x32_bf16 v[132:135], v[76:79], v[182:185], v[136:139]
	v_mfma_f32_16x16x32_bf16 v[124:127], v[48:51], v[196:199], v[124:127]
	v_mfma_f32_16x16x32_bf16 v[120:123], v[76:79], v[196:199], v[120:123]
	v_mfma_f32_16x16x32_bf16 v[108:111], v[48:51], v[204:207], v[108:111]
	v_mfma_f32_16x16x32_bf16 v[104:107], v[76:79], v[204:207], v[104:107]
	v_mfma_f32_16x16x32_bf16 v[136:139], v[80:83], v[186:189], v[132:135]
	v_mfma_f32_16x16x32_bf16 v[124:127], v[52:55], v[200:203], v[124:127]
	v_mfma_f32_16x16x32_bf16 v[120:123], v[80:83], v[200:203], v[120:123]
	v_mfma_f32_16x16x32_bf16 v[108:111], v[52:55], v[208:211], v[108:111]
	v_mfma_f32_16x16x32_bf16 v[104:107], v[80:83], v[208:211], v[104:107]
	s_barrier
	s_mov_b32 m0, s39
	ds_read_b128 v[212:215], v194 offset:49152
	ds_read_b128 v[216:219], v194 offset:50176
	ds_read_b128 v[220:223], v194 offset:51200
	global_load_lds_dwordx4 v160, s[24:25]
	s_mov_b32 m0, s40
	ds_read_b128 v[236:239], v194 offset:52224
	global_load_lds_dwordx4 v162, s[24:25]
	s_add_i32 m0, s36, 0x18000
	s_nop 0
	global_load_lds_dwordx4 v168, s[98:99]
	s_add_i32 m0, s36, 0x1a000
	s_nop 0
	global_load_lds_dwordx4 v164, s[98:99]
	s_barrier
	s_waitcnt lgkmcnt(0)
	v_mfma_f32_16x16x32_bf16 v[56:59], v[220:223], v[116:119], v[56:59]
	v_mfma_f32_16x16x32_bf16 v[132:135], v[212:215], v[116:119], v[148:151]
	v_mfma_f32_16x16x32_bf16 v[144:147], v[236:239], v[128:131], v[56:59]
	v_mfma_f32_16x16x32_bf16 v[56:59], v[212:215], v[182:185], v[60:63]
	v_mfma_f32_16x16x32_bf16 v[148:151], v[216:219], v[128:131], v[132:135]
	v_mfma_f32_16x16x32_bf16 v[132:135], v[216:219], v[186:189], v[56:59]
	v_mfma_f32_16x16x32_bf16 v[56:59], v[220:223], v[182:185], v[72:75]
	v_mfma_f32_16x16x32_bf16 v[128:131], v[236:239], v[186:189], v[56:59]
	v_mfma_f32_16x16x32_bf16 v[56:59], v[212:215], v[196:199], v[84:87]
	v_mfma_f32_16x16x32_bf16 v[116:119], v[216:219], v[200:203], v[56:59]
	v_mfma_f32_16x16x32_bf16 v[56:59], v[220:223], v[196:199], v[112:115]
	v_mfma_f32_16x16x32_bf16 v[112:115], v[236:239], v[200:203], v[56:59]
	v_mfma_f32_16x16x32_bf16 v[56:59], v[212:215], v[204:207], v[100:103]
	v_mfma_f32_16x16x32_bf16 v[100:103], v[216:219], v[208:211], v[56:59]
	v_mfma_f32_16x16x32_bf16 v[56:59], v[220:223], v[204:207], v[96:99]
	v_mfma_f32_16x16x32_bf16 v[96:99], v[236:239], v[208:211], v[56:59]
	s_barrier
	s_nop 2
	ds_read_b128 v[56:59], v195 offset:49152
	ds_read_b128 v[60:63], v195 offset:50176
	ds_read_b128 v[72:75], v195 offset:51200
	ds_read_b128 v[84:87], v195 offset:52224
	ds_read_b128 v[182:185], v195 offset:53248
	ds_read_b128 v[186:189], v195 offset:54272
	ds_read_b128 v[196:199], v195 offset:55296
	ds_read_b128 v[200:203], v195 offset:56320
	s_barrier
	s_waitcnt lgkmcnt(0)
	v_mfma_f32_16x16x32_bf16 v[92:95], v[48:51], v[56:59], v[92:95]
	v_mfma_f32_16x16x32_bf16 v[88:91], v[76:79], v[56:59], v[88:91]
	v_mfma_f32_16x16x32_bf16 v[68:71], v[48:51], v[72:75], v[68:71]
	v_mfma_f32_16x16x32_bf16 v[64:67], v[76:79], v[72:75], v[64:67]
	v_mfma_f32_16x16x32_bf16 v[28:31], v[48:51], v[182:185], v[28:31]
	v_mfma_f32_16x16x32_bf16 v[24:27], v[76:79], v[182:185], v[24:27]
	v_mfma_f32_16x16x32_bf16 v[12:15], v[48:51], v[196:199], v[12:15]
	v_mfma_f32_16x16x32_bf16 v[8:11], v[76:79], v[196:199], v[8:11]
	v_mfma_f32_16x16x32_bf16 v[92:95], v[52:55], v[60:63], v[92:95]
	v_mfma_f32_16x16x32_bf16 v[88:91], v[80:83], v[60:63], v[88:91]
	v_mfma_f32_16x16x32_bf16 v[68:71], v[52:55], v[84:87], v[68:71]
	v_mfma_f32_16x16x32_bf16 v[64:67], v[80:83], v[84:87], v[64:67]
	v_mfma_f32_16x16x32_bf16 v[28:31], v[52:55], v[186:189], v[28:31]
	v_mfma_f32_16x16x32_bf16 v[24:27], v[80:83], v[186:189], v[24:27]
	v_mfma_f32_16x16x32_bf16 v[12:15], v[52:55], v[200:203], v[12:15]
	v_mfma_f32_16x16x32_bf16 v[8:11], v[80:83], v[200:203], v[8:11]
	s_barrier
	s_mov_b32 m0, s47
	s_nop 0
	global_load_lds_dwordx4 v160, s[100:101]
	s_mov_b32 m0, s49
	s_nop 0
	global_load_lds_dwordx4 v162, s[100:101]
	s_add_i32 m0, s36, 0x1c000
	s_add_u32 s8, s8, 0xb0080
	s_addc_u32 s9, s9, 0
	global_load_lds_dwordx4 v168, s[8:9]
	s_add_i32 m0, s36, 0x1e000
	s_add_i32 s58, s58, 2
	global_load_lds_dwordx4 v164, s[8:9]
	s_waitcnt vmcnt(6)
	s_barrier
	v_mfma_f32_16x16x32_bf16 v[40:43], v[212:215], v[56:59], v[40:43]
	v_mfma_f32_16x16x32_bf16 v[80:83], v[216:219], v[60:63], v[40:43]
	v_mfma_f32_16x16x32_bf16 v[40:43], v[220:223], v[56:59], v[44:47]
	v_mfma_f32_16x16x32_bf16 v[36:39], v[212:215], v[72:75], v[36:39]
	v_mfma_f32_16x16x32_bf16 v[32:35], v[220:223], v[72:75], v[32:35]
	v_mfma_f32_16x16x32_bf16 v[20:23], v[212:215], v[182:185], v[20:23]
	v_mfma_f32_16x16x32_bf16 v[16:19], v[220:223], v[182:185], v[16:19]
	v_mfma_f32_16x16x32_bf16 v[4:7], v[212:215], v[196:199], v[4:7]
	v_mfma_f32_16x16x32_bf16 v[0:3], v[220:223], v[196:199], v[0:3]
	v_mfma_f32_16x16x32_bf16 v[76:79], v[236:239], v[60:63], v[40:43]
	v_mfma_f32_16x16x32_bf16 v[36:39], v[216:219], v[84:87], v[36:39]
	v_mfma_f32_16x16x32_bf16 v[32:35], v[236:239], v[84:87], v[32:35]
	v_mfma_f32_16x16x32_bf16 v[20:23], v[216:219], v[186:189], v[20:23]
	v_mfma_f32_16x16x32_bf16 v[16:19], v[236:239], v[186:189], v[16:19]
	v_mfma_f32_16x16x32_bf16 v[4:7], v[216:219], v[200:203], v[4:7]
	v_mfma_f32_16x16x32_bf16 v[0:3], v[236:239], v[200:203], v[0:3]
	s_add_u32 s56, s56, 0x100
	s_addc_u32 s57, s57, 0
	s_cmp_gt_u32 s58, 41
	s_mov_b64 s[24:25], s[2:3]
	s_barrier
.LBB0_1049:
	s_add_u32 s2, s24, 0x100
	s_addc_u32 s3, s25, 0
	ds_read_b128 v[40:43], v194
	ds_read_b128 v[44:47], v194 offset:1024
	ds_read_b128 v[48:51], v194 offset:2048
	ds_read_b128 v[52:55], v194 offset:3072
	s_cmp_eq_u32 s58, 40
	s_cselect_b32 s27, s1, s3
	s_cselect_b32 s26, s0, s2
	s_cselect_b32 s9, s23, s57
	s_cselect_b32 s8, s22, s56
	ds_read_b128 v[56:59], v195
	ds_read_b128 v[60:63], v195 offset:1024
	ds_read_b128 v[72:75], v195 offset:2048
	ds_read_b128 v[84:87], v195 offset:3072
	ds_read_b128 v[182:185], v195 offset:4096
	ds_read_b128 v[186:189], v195 offset:5120
	ds_read_b128 v[196:199], v195 offset:6144
	ds_read_b128 v[200:203], v195 offset:7168
	s_waitcnt lgkmcnt(8)
	s_barrier
	s_waitcnt lgkmcnt(0)
	v_mfma_f32_16x16x32_bf16 v[156:159], v[40:43], v[56:59], v[156:159]
	v_mfma_f32_16x16x32_bf16 v[152:155], v[48:51], v[56:59], v[152:155]
	v_mfma_f32_16x16x32_bf16 v[140:143], v[40:43], v[72:75], v[140:143]
	v_mfma_f32_16x16x32_bf16 v[136:139], v[48:51], v[72:75], v[136:139]
	v_mfma_f32_16x16x32_bf16 v[124:127], v[40:43], v[182:185], v[124:127]
	v_mfma_f32_16x16x32_bf16 v[120:123], v[48:51], v[182:185], v[120:123]
	v_mfma_f32_16x16x32_bf16 v[108:111], v[40:43], v[196:199], v[108:111]
	v_mfma_f32_16x16x32_bf16 v[104:107], v[48:51], v[196:199], v[104:107]
	v_mfma_f32_16x16x32_bf16 v[156:159], v[44:47], v[60:63], v[156:159]
	v_mfma_f32_16x16x32_bf16 v[152:155], v[52:55], v[60:63], v[152:155]
	v_mfma_f32_16x16x32_bf16 v[140:143], v[44:47], v[84:87], v[140:143]
	v_mfma_f32_16x16x32_bf16 v[136:139], v[52:55], v[84:87], v[136:139]
	v_mfma_f32_16x16x32_bf16 v[124:127], v[44:47], v[186:189], v[124:127]
	v_mfma_f32_16x16x32_bf16 v[120:123], v[52:55], v[186:189], v[120:123]
	v_mfma_f32_16x16x32_bf16 v[108:111], v[44:47], v[200:203], v[108:111]
	v_mfma_f32_16x16x32_bf16 v[104:107], v[52:55], v[200:203], v[104:107]
	s_barrier
	s_add_i32 m0, s37, 0xc000
	ds_read_b128 v[204:207], v194 offset:16384
	ds_read_b128 v[208:211], v194 offset:17408
	ds_read_b128 v[212:215], v194 offset:18432
	global_load_lds_dwordx4 v166, s[24:25]
	s_add_i32 m0, s37, 0xe000
	ds_read_b128 v[216:219], v194 offset:19456
	global_load_lds_dwordx4 v180, s[24:25]
	s_add_u32 s98, s8, 0x80
	s_addc_u32 s99, s9, 0
	s_add_i32 m0, s36, 0x10000
	s_nop 0
	global_load_lds_dwordx4 v168, s[8:9]
	s_add_i32 m0, s36, 0x12000
	s_nop 0
	global_load_lds_dwordx4 v164, s[8:9]
	s_barrier
	s_waitcnt lgkmcnt(0)
	v_mfma_f32_16x16x32_bf16 v[148:151], v[204:207], v[56:59], v[148:151]
	v_mfma_f32_16x16x32_bf16 v[56:59], v[212:215], v[56:59], v[144:147]
	v_mfma_f32_16x16x32_bf16 v[148:151], v[208:211], v[60:63], v[148:151]
	v_mfma_f32_16x16x32_bf16 v[56:59], v[216:219], v[60:63], v[56:59]
	v_mfma_f32_16x16x32_bf16 v[60:63], v[204:207], v[72:75], v[132:135]
	v_mfma_f32_16x16x32_bf16 v[72:75], v[212:215], v[72:75], v[128:131]
	v_mfma_f32_16x16x32_bf16 v[112:115], v[212:215], v[182:185], v[112:115]
	v_mfma_f32_16x16x32_bf16 v[100:103], v[204:207], v[196:199], v[100:103]
	v_mfma_f32_16x16x32_bf16 v[96:99], v[212:215], v[196:199], v[96:99]
	v_mfma_f32_16x16x32_bf16 v[60:63], v[208:211], v[84:87], v[60:63]
	v_mfma_f32_16x16x32_bf16 v[72:75], v[216:219], v[84:87], v[72:75]
	v_mfma_f32_16x16x32_bf16 v[84:87], v[204:207], v[182:185], v[116:119]
	v_mfma_f32_16x16x32_bf16 v[112:115], v[216:219], v[186:189], v[112:115]
	v_mfma_f32_16x16x32_bf16 v[100:103], v[208:211], v[200:203], v[100:103]
	v_mfma_f32_16x16x32_bf16 v[96:99], v[216:219], v[200:203], v[96:99]
	v_mfma_f32_16x16x32_bf16 v[84:87], v[208:211], v[186:189], v[84:87]
	s_add_u32 s100, s26, 0x80
	s_addc_u32 s101, s27, 0
	s_barrier
	ds_read_b128 v[116:119], v195 offset:16384
	ds_read_b128 v[128:131], v195 offset:17408
	ds_read_b128 v[132:135], v195 offset:18432
	ds_read_b128 v[144:147], v195 offset:19456
	ds_read_b128 v[182:185], v195 offset:20480
	ds_read_b128 v[186:189], v195 offset:21504
	ds_read_b128 v[196:199], v195 offset:22528
	ds_read_b128 v[200:203], v195 offset:23552
	s_barrier
	s_waitcnt lgkmcnt(0)
	v_mfma_f32_16x16x32_bf16 v[92:95], v[40:43], v[116:119], v[92:95]
	v_mfma_f32_16x16x32_bf16 v[88:91], v[48:51], v[116:119], v[88:91]
	v_mfma_f32_16x16x32_bf16 v[68:71], v[40:43], v[132:135], v[68:71]
	v_mfma_f32_16x16x32_bf16 v[64:67], v[48:51], v[132:135], v[64:67]
	v_mfma_f32_16x16x32_bf16 v[28:31], v[40:43], v[182:185], v[28:31]
	v_mfma_f32_16x16x32_bf16 v[24:27], v[48:51], v[182:185], v[24:27]
	v_mfma_f32_16x16x32_bf16 v[12:15], v[40:43], v[196:199], v[12:15]
	v_mfma_f32_16x16x32_bf16 v[8:11], v[48:51], v[196:199], v[8:11]
	v_mfma_f32_16x16x32_bf16 v[92:95], v[44:47], v[128:131], v[92:95]
	v_mfma_f32_16x16x32_bf16 v[88:91], v[52:55], v[128:131], v[88:91]
	v_mfma_f32_16x16x32_bf16 v[68:71], v[44:47], v[144:147], v[68:71]
	v_mfma_f32_16x16x32_bf16 v[64:67], v[52:55], v[144:147], v[64:67]
	v_mfma_f32_16x16x32_bf16 v[28:31], v[44:47], v[186:189], v[28:31]
	v_mfma_f32_16x16x32_bf16 v[24:27], v[52:55], v[186:189], v[24:27]
	v_mfma_f32_16x16x32_bf16 v[12:15], v[44:47], v[200:203], v[12:15]
	v_mfma_f32_16x16x32_bf16 v[8:11], v[52:55], v[200:203], v[8:11]
	s_barrier
	s_mov_b32 m0, s37
	s_nop 0
	global_load_lds_dwordx4 v160, s[26:27]
	s_mov_b32 m0, s38
	s_nop 0
	global_load_lds_dwordx4 v162, s[26:27]
	s_add_i32 m0, s36, 0x14000
	s_add_u32 s24, s8, 0xb0000
	s_addc_u32 s25, s9, 0
	global_load_lds_dwordx4 v168, s[24:25]
	s_add_i32 m0, s36, 0x16000
	s_nop 0
	global_load_lds_dwordx4 v164, s[24:25]
	s_waitcnt vmcnt(6)
	s_barrier
	v_mfma_f32_16x16x32_bf16 v[36:39], v[204:207], v[132:135], v[36:39]
	v_mfma_f32_16x16x32_bf16 v[32:35], v[212:215], v[132:135], v[32:35]
	v_mfma_f32_16x16x32_bf16 v[20:23], v[204:207], v[182:185], v[20:23]
	v_mfma_f32_16x16x32_bf16 v[16:19], v[212:215], v[182:185], v[16:19]
	v_mfma_f32_16x16x32_bf16 v[4:7], v[204:207], v[196:199], v[4:7]
	v_mfma_f32_16x16x32_bf16 v[0:3], v[212:215], v[196:199], v[0:3]
	v_mfma_f32_16x16x32_bf16 v[40:43], v[204:207], v[116:119], v[80:83]
	v_mfma_f32_16x16x32_bf16 v[44:47], v[212:215], v[116:119], v[76:79]
	v_mfma_f32_16x16x32_bf16 v[36:39], v[208:211], v[144:147], v[36:39]
	v_mfma_f32_16x16x32_bf16 v[32:35], v[216:219], v[144:147], v[32:35]
	v_mfma_f32_16x16x32_bf16 v[20:23], v[208:211], v[186:189], v[20:23]
	v_mfma_f32_16x16x32_bf16 v[16:19], v[216:219], v[186:189], v[16:19]
	v_mfma_f32_16x16x32_bf16 v[4:7], v[208:211], v[200:203], v[4:7]
	v_mfma_f32_16x16x32_bf16 v[0:3], v[216:219], v[200:203], v[0:3]
	v_mfma_f32_16x16x32_bf16 v[40:43], v[208:211], v[128:131], v[40:43]
	v_mfma_f32_16x16x32_bf16 v[44:47], v[216:219], v[128:131], v[44:47]
	s_barrier
	ds_read_b128 v[48:51], v194 offset:32768
	ds_read_b128 v[52:55], v194 offset:33792
	ds_read_b128 v[76:79], v194 offset:34816
	ds_read_b128 v[80:83], v194 offset:35840
	s_add_u32 s24, s26, 0xb0000
	s_addc_u32 s25, s27, 0
	ds_read_b128 v[116:119], v195 offset:32768
	ds_read_b128 v[128:131], v195 offset:33792
	ds_read_b128 v[182:185], v195 offset:34816
	ds_read_b128 v[186:189], v195 offset:35840
	ds_read_b128 v[196:199], v195 offset:36864
	ds_read_b128 v[200:203], v195 offset:37888
	ds_read_b128 v[204:207], v195 offset:38912
	ds_read_b128 v[208:211], v195 offset:39936
	s_waitcnt lgkmcnt(8)
	s_barrier
	s_waitcnt lgkmcnt(0)
	v_mfma_f32_16x16x32_bf16 v[132:135], v[48:51], v[116:119], v[156:159]
	v_mfma_f32_16x16x32_bf16 v[156:159], v[52:55], v[128:131], v[132:135]
	v_mfma_f32_16x16x32_bf16 v[132:135], v[76:79], v[116:119], v[152:155]
	v_mfma_f32_16x16x32_bf16 v[152:155], v[80:83], v[128:131], v[132:135]
	v_mfma_f32_16x16x32_bf16 v[132:135], v[48:51], v[182:185], v[140:143]
	v_mfma_f32_16x16x32_bf16 v[140:143], v[52:55], v[186:189], v[132:135]
	v_mfma_f32_16x16x32_bf16 v[132:135], v[76:79], v[182:185], v[136:139]
	v_mfma_f32_16x16x32_bf16 v[124:127], v[48:51], v[196:199], v[124:127]
	v_mfma_f32_16x16x32_bf16 v[120:123], v[76:79], v[196:199], v[120:123]
	v_mfma_f32_16x16x32_bf16 v[108:111], v[48:51], v[204:207], v[108:111]
	v_mfma_f32_16x16x32_bf16 v[104:107], v[76:79], v[204:207], v[104:107]
	v_mfma_f32_16x16x32_bf16 v[136:139], v[80:83], v[186:189], v[132:135]
	v_mfma_f32_16x16x32_bf16 v[124:127], v[52:55], v[200:203], v[124:127]
	v_mfma_f32_16x16x32_bf16 v[120:123], v[80:83], v[200:203], v[120:123]
	v_mfma_f32_16x16x32_bf16 v[108:111], v[52:55], v[208:211], v[108:111]
	v_mfma_f32_16x16x32_bf16 v[104:107], v[80:83], v[208:211], v[104:107]
	s_barrier
	s_mov_b32 m0, s39
	ds_read_b128 v[212:215], v194 offset:49152
	ds_read_b128 v[216:219], v194 offset:50176
	ds_read_b128 v[220:223], v194 offset:51200
	global_load_lds_dwordx4 v160, s[24:25]
	s_mov_b32 m0, s40
	ds_read_b128 v[236:239], v194 offset:52224
	global_load_lds_dwordx4 v162, s[24:25]
	s_add_i32 m0, s36, 0x18000
	s_nop 0
	global_load_lds_dwordx4 v168, s[98:99]
	s_add_i32 m0, s36, 0x1a000
	s_nop 0
	global_load_lds_dwordx4 v164, s[98:99]
	s_barrier
	s_waitcnt lgkmcnt(0)
	v_mfma_f32_16x16x32_bf16 v[56:59], v[220:223], v[116:119], v[56:59]
	v_mfma_f32_16x16x32_bf16 v[132:135], v[212:215], v[116:119], v[148:151]
	v_mfma_f32_16x16x32_bf16 v[144:147], v[236:239], v[128:131], v[56:59]
	v_mfma_f32_16x16x32_bf16 v[56:59], v[212:215], v[182:185], v[60:63]
	v_mfma_f32_16x16x32_bf16 v[148:151], v[216:219], v[128:131], v[132:135]
	v_mfma_f32_16x16x32_bf16 v[132:135], v[216:219], v[186:189], v[56:59]
	v_mfma_f32_16x16x32_bf16 v[56:59], v[220:223], v[182:185], v[72:75]
	v_mfma_f32_16x16x32_bf16 v[128:131], v[236:239], v[186:189], v[56:59]
	v_mfma_f32_16x16x32_bf16 v[56:59], v[212:215], v[196:199], v[84:87]
	v_mfma_f32_16x16x32_bf16 v[116:119], v[216:219], v[200:203], v[56:59]
	v_mfma_f32_16x16x32_bf16 v[56:59], v[220:223], v[196:199], v[112:115]
	v_mfma_f32_16x16x32_bf16 v[112:115], v[236:239], v[200:203], v[56:59]
	v_mfma_f32_16x16x32_bf16 v[56:59], v[212:215], v[204:207], v[100:103]
	v_mfma_f32_16x16x32_bf16 v[100:103], v[216:219], v[208:211], v[56:59]
	v_mfma_f32_16x16x32_bf16 v[56:59], v[220:223], v[204:207], v[96:99]
	v_mfma_f32_16x16x32_bf16 v[96:99], v[236:239], v[208:211], v[56:59]
	s_barrier
	s_nop 2
	ds_read_b128 v[56:59], v195 offset:49152
	ds_read_b128 v[60:63], v195 offset:50176
	ds_read_b128 v[72:75], v195 offset:51200
	ds_read_b128 v[84:87], v195 offset:52224
	ds_read_b128 v[182:185], v195 offset:53248
	ds_read_b128 v[186:189], v195 offset:54272
	ds_read_b128 v[196:199], v195 offset:55296
	ds_read_b128 v[200:203], v195 offset:56320
	s_barrier
	s_waitcnt lgkmcnt(0)
	v_mfma_f32_16x16x32_bf16 v[92:95], v[48:51], v[56:59], v[92:95]
	v_mfma_f32_16x16x32_bf16 v[88:91], v[76:79], v[56:59], v[88:91]
	v_mfma_f32_16x16x32_bf16 v[68:71], v[48:51], v[72:75], v[68:71]
	v_mfma_f32_16x16x32_bf16 v[64:67], v[76:79], v[72:75], v[64:67]
	v_mfma_f32_16x16x32_bf16 v[28:31], v[48:51], v[182:185], v[28:31]
	v_mfma_f32_16x16x32_bf16 v[24:27], v[76:79], v[182:185], v[24:27]
	v_mfma_f32_16x16x32_bf16 v[12:15], v[48:51], v[196:199], v[12:15]
	v_mfma_f32_16x16x32_bf16 v[8:11], v[76:79], v[196:199], v[8:11]
	v_mfma_f32_16x16x32_bf16 v[92:95], v[52:55], v[60:63], v[92:95]
	v_mfma_f32_16x16x32_bf16 v[88:91], v[80:83], v[60:63], v[88:91]
	v_mfma_f32_16x16x32_bf16 v[68:71], v[52:55], v[84:87], v[68:71]
	v_mfma_f32_16x16x32_bf16 v[64:67], v[80:83], v[84:87], v[64:67]
	v_mfma_f32_16x16x32_bf16 v[28:31], v[52:55], v[186:189], v[28:31]
	v_mfma_f32_16x16x32_bf16 v[24:27], v[80:83], v[186:189], v[24:27]
	v_mfma_f32_16x16x32_bf16 v[12:15], v[52:55], v[200:203], v[12:15]
	v_mfma_f32_16x16x32_bf16 v[8:11], v[80:83], v[200:203], v[8:11]
	s_barrier
	s_mov_b32 m0, s47
	s_nop 0
	global_load_lds_dwordx4 v160, s[100:101]
	s_mov_b32 m0, s49
	s_nop 0
	global_load_lds_dwordx4 v162, s[100:101]
	s_add_i32 m0, s36, 0x1c000
	s_add_u32 s8, s8, 0xb0080
	s_addc_u32 s9, s9, 0
	global_load_lds_dwordx4 v168, s[8:9]
	s_add_i32 m0, s36, 0x1e000
	s_add_i32 s58, s58, 2
	global_load_lds_dwordx4 v164, s[8:9]
	s_waitcnt vmcnt(6)
	s_barrier
	v_mfma_f32_16x16x32_bf16 v[40:43], v[212:215], v[56:59], v[40:43]
	v_mfma_f32_16x16x32_bf16 v[80:83], v[216:219], v[60:63], v[40:43]
	v_mfma_f32_16x16x32_bf16 v[40:43], v[220:223], v[56:59], v[44:47]
	v_mfma_f32_16x16x32_bf16 v[36:39], v[212:215], v[72:75], v[36:39]
	v_mfma_f32_16x16x32_bf16 v[32:35], v[220:223], v[72:75], v[32:35]
	v_mfma_f32_16x16x32_bf16 v[20:23], v[212:215], v[182:185], v[20:23]
	v_mfma_f32_16x16x32_bf16 v[16:19], v[220:223], v[182:185], v[16:19]
	v_mfma_f32_16x16x32_bf16 v[4:7], v[212:215], v[196:199], v[4:7]
	v_mfma_f32_16x16x32_bf16 v[0:3], v[220:223], v[196:199], v[0:3]
	v_mfma_f32_16x16x32_bf16 v[76:79], v[236:239], v[60:63], v[40:43]
	v_mfma_f32_16x16x32_bf16 v[36:39], v[216:219], v[84:87], v[36:39]
	v_mfma_f32_16x16x32_bf16 v[32:35], v[236:239], v[84:87], v[32:35]
	v_mfma_f32_16x16x32_bf16 v[20:23], v[216:219], v[186:189], v[20:23]
	v_mfma_f32_16x16x32_bf16 v[16:19], v[236:239], v[186:189], v[16:19]
	v_mfma_f32_16x16x32_bf16 v[4:7], v[216:219], v[200:203], v[4:7]
	v_mfma_f32_16x16x32_bf16 v[0:3], v[236:239], v[200:203], v[0:3]
	s_add_u32 s56, s56, 0x100
	s_addc_u32 s57, s57, 0
	s_cmp_gt_u32 s58, 41
	s_mov_b64 s[24:25], s[2:3]
	s_barrier
	s_cbranch_scc0 .LBB0_1049
	s_lshl_b32 s2, s55, 8
	v_mov_b32_e32 v186, v193
	v_mov_b32_e32 v196, v192
	s_or_b32 s2, s2, s46
	v_mov_b32_e32 v52, 0
	v_lshl_add_u32 v182, v196, 3, s2
	s_add_i32 s2, s54, -16
	s_lshr_b32 s2, s2, 3
	s_add_i32 s2, s2, 1
	s_cmp_gt_i32 s54, 15
	s_cselect_b32 s8, s2, 0
	s_mul_i32 s96, s8, 0x1800
	s_lshl_b64 s[2:3], s[96:97], 2
	s_add_u32 s2, s41, s2
	v_ashrrev_i32_e32 v183, 31, v182
	s_addc_u32 s3, s42, s3
	v_lshlrev_b64 v[40:41], 2, v[182:183]
	v_lshl_add_u64 v[42:43], s[2:3], 0, v[40:41]
	global_load_dwordx4 v[72:75], v[42:43], off
	s_lshl_b32 s96, s8, 10
	s_lshl_b64 s[2:3], s[96:97], 2
	s_add_u32 s2, s43, s2
	s_addc_u32 s3, s44, s3
	v_lshl_add_u64 v[184:185], s[2:3], 0, v[40:41]
	s_and_b64 vcc, exec, s[4:5]
	v_mov_b32_e32 v60, 0
	v_mov_b32_e32 v61, v52
	v_mov_b32_e32 v62, 0
	v_mov_b32_e32 v63, 0
	s_cbranch_vccnz .LBB0_1052
	global_load_dwordx4 v[60:63], v[184:185], off
